# v022 plus back-edge rotation in the six GEMM K-loops: the loop-closing barrier becomes the loop head so the taken branch is issued before the wave parks at it
# speedup vs baseline: 1.0021x; 1.0021x over previous
.LBB0_126:
	s_ashr_i32 s29, s28, 31
	s_lshl_b64 s[6:7], s[28:29], 21
	v_cmp_lt_i64_e32 vcc, s[34:35], v[142:143]
	s_add_u32 s34, s70, s6
	s_addc_u32 s35, s71, s7
	s_and_b64 s[6:7], vcc, exec
	s_cselect_b32 s6, s35, s39
	s_cselect_b32 s7, s34, s38
	s_ashr_i32 s27, s26, 31
	s_lshl_b64 s[36:37], s[26:27], 21
	s_add_u32 s36, s58, s36
	s_addc_u32 s37, s59, s37
	s_and_b64 s[42:43], vcc, exec
	s_cselect_b32 s9, s37, s41
	s_cselect_b32 s11, s36, s40
	s_add_u32 s38, s38, 0x100080
	s_addc_u32 s39, s39, 0
	s_add_u32 s27, s40, 0x100
	v_mov_b32_e32 v0, 0
	s_addc_u32 s29, s41, 0
	s_mov_b32 s54, -2
	v_mov_b32_e32 v1, v0
	v_mov_b32_e32 v2, v0
	v_mov_b32_e32 v3, v0
	v_mov_b32_e32 v4, v0
	v_mov_b32_e32 v5, v0
	v_mov_b32_e32 v6, v0
	v_mov_b32_e32 v7, v0
	v_mov_b32_e32 v16, v0
	v_mov_b32_e32 v17, v0
	v_mov_b32_e32 v18, v0
	v_mov_b32_e32 v19, v0
	v_mov_b32_e32 v20, v0
	v_mov_b32_e32 v21, v0
	v_mov_b32_e32 v22, v0
	v_mov_b32_e32 v23, v0
	v_mov_b32_e32 v32, v0
	v_mov_b32_e32 v33, v0
	v_mov_b32_e32 v34, v0
	v_mov_b32_e32 v35, v0
	v_mov_b32_e32 v36, v0
	v_mov_b32_e32 v37, v0
	v_mov_b32_e32 v38, v0
	v_mov_b32_e32 v39, v0
	v_mov_b32_e32 v48, v0
	v_mov_b32_e32 v49, v0
	v_mov_b32_e32 v50, v0
	v_mov_b32_e32 v51, v0
	v_mov_b32_e32 v52, v0
	v_mov_b32_e32 v53, v0
	v_mov_b32_e32 v54, v0
	v_mov_b32_e32 v55, v0
	v_mov_b32_e32 v8, v0
	v_mov_b32_e32 v9, v0
	v_mov_b32_e32 v10, v0
	v_mov_b32_e32 v11, v0
	v_mov_b32_e32 v12, v0
	v_mov_b32_e32 v13, v0
	v_mov_b32_e32 v14, v0
	v_mov_b32_e32 v15, v0
	v_mov_b32_e32 v24, v0
	v_mov_b32_e32 v25, v0
	v_mov_b32_e32 v26, v0
	v_mov_b32_e32 v27, v0
	v_mov_b32_e32 v28, v0
	v_mov_b32_e32 v29, v0
	v_mov_b32_e32 v30, v0
	v_mov_b32_e32 v31, v0
	v_mov_b32_e32 v40, v0
	v_mov_b32_e32 v41, v0
	v_mov_b32_e32 v42, v0
	v_mov_b32_e32 v43, v0
	v_mov_b32_e32 v44, v0
	v_mov_b32_e32 v45, v0
	v_mov_b32_e32 v46, v0
	v_mov_b32_e32 v47, v0
	v_mov_b32_e32 v56, v0
	v_mov_b32_e32 v57, v0
	v_mov_b32_e32 v58, v0
	v_mov_b32_e32 v59, v0
	v_mov_b32_e32 v60, v0
	v_mov_b32_e32 v61, v0
	v_mov_b32_e32 v62, v0
	v_mov_b32_e32 v63, v0
	v_mov_b32_e32 v64, v0
	v_mov_b32_e32 v65, v0
	v_mov_b32_e32 v66, v0
	v_mov_b32_e32 v67, v0
	v_mov_b32_e32 v68, v0
	v_mov_b32_e32 v69, v0
	v_mov_b32_e32 v70, v0
	v_mov_b32_e32 v71, v0
	v_mov_b32_e32 v80, v0
	v_mov_b32_e32 v81, v0
	v_mov_b32_e32 v82, v0
	v_mov_b32_e32 v83, v0
	v_mov_b32_e32 v84, v0
	v_mov_b32_e32 v85, v0
	v_mov_b32_e32 v86, v0
	v_mov_b32_e32 v87, v0
	v_mov_b32_e32 v96, v0
	v_mov_b32_e32 v97, v0
	v_mov_b32_e32 v98, v0
	v_mov_b32_e32 v99, v0
	v_mov_b32_e32 v100, v0
	v_mov_b32_e32 v101, v0
	v_mov_b32_e32 v102, v0
	v_mov_b32_e32 v103, v0
	v_mov_b32_e32 v112, v0
	v_mov_b32_e32 v113, v0
	v_mov_b32_e32 v114, v0
	v_mov_b32_e32 v115, v0
	v_mov_b32_e32 v116, v0
	v_mov_b32_e32 v117, v0
	v_mov_b32_e32 v118, v0
	v_mov_b32_e32 v119, v0
	v_mov_b32_e32 v72, v0
	v_mov_b32_e32 v73, v0
	v_mov_b32_e32 v74, v0
	v_mov_b32_e32 v75, v0
	v_mov_b32_e32 v76, v0
	v_mov_b32_e32 v77, v0
	v_mov_b32_e32 v78, v0
	v_mov_b32_e32 v79, v0
	v_mov_b32_e32 v88, v0
	v_mov_b32_e32 v89, v0
	v_mov_b32_e32 v90, v0
	v_mov_b32_e32 v91, v0
	v_mov_b32_e32 v92, v0
	v_mov_b32_e32 v93, v0
	v_mov_b32_e32 v94, v0
	v_mov_b32_e32 v95, v0
	v_mov_b32_e32 v104, v0
	v_mov_b32_e32 v105, v0
	v_mov_b32_e32 v106, v0
	v_mov_b32_e32 v107, v0
	v_mov_b32_e32 v108, v0
	v_mov_b32_e32 v109, v0
	v_mov_b32_e32 v110, v0
	v_mov_b32_e32 v111, v0
	v_mov_b32_e32 v120, v0
	v_mov_b32_e32 v121, v0
	v_mov_b32_e32 v122, v0
	v_mov_b32_e32 v123, v0
	v_mov_b32_e32 v124, v0
	v_mov_b32_e32 v125, v0
	v_mov_b32_e32 v126, v0
	v_mov_b32_e32 v127, v0
	s_branch .LBB0_127

.LBB0_127:
	ds_read_b128 v[176:179], v167
	ds_read_b128 v[180:183], v167 offset:1024
	ds_read_b128 v[186:189], v167 offset:2048
	ds_read_b128 v[190:193], v167 offset:3072
	s_add_u32 s40, s38, 0xfff00080
	s_addc_u32 s41, s39, -1
	s_cmp_eq_u32 s54, 60
	s_cselect_b32 s43, s6, s41
	s_cselect_b32 s42, s7, s40
	s_cselect_b32 s41, s9, s29
	s_cselect_b32 s40, s11, s27
	v_lshl_add_u64 v[156:157], s[38:39], 0, v[138:139]
	s_add_i32 m0, s44, 0xc000
	ds_read_b128 v[194:197], v168
	ds_read_b128 v[198:201], v168 offset:1024
	ds_read_b128 v[202:205], v168 offset:2048
	ds_read_b128 v[206:209], v168 offset:3072
	ds_read_b128 v[210:213], v168 offset:4096
	ds_read_b128 v[214:217], v168 offset:5120
	ds_read_b128 v[218:221], v168 offset:6144
	ds_read_b128 v[222:225], v168 offset:7168
	global_load_lds_dwordx4 v[156:157], off
	v_lshl_add_u64 v[156:157], s[38:39], 0, v[140:141]
	s_add_i32 m0, s44, 0xe000
	s_nop 0
	global_load_lds_dwordx4 v[156:157], off
	s_waitcnt lgkmcnt(8)
	s_barrier
	s_waitcnt lgkmcnt(0)
	s_waitcnt lgkmcnt(0)
	v_mfma_f32_16x16x32_bf16 v[124:127], v[176:179], v[194:197], v[124:127]
	v_mfma_f32_16x16x32_bf16 v[124:127], v[180:183], v[198:201], v[124:127]
	v_mfma_f32_16x16x32_bf16 v[120:123], v[186:189], v[194:197], v[120:123]
	v_mfma_f32_16x16x32_bf16 v[120:123], v[190:193], v[198:201], v[120:123]
	v_mfma_f32_16x16x32_bf16 v[108:111], v[176:179], v[202:205], v[108:111]
	v_mfma_f32_16x16x32_bf16 v[108:111], v[180:183], v[206:209], v[108:111]
	v_mfma_f32_16x16x32_bf16 v[104:107], v[186:189], v[202:205], v[104:107]
	v_mfma_f32_16x16x32_bf16 v[104:107], v[190:193], v[206:209], v[104:107]
	v_mfma_f32_16x16x32_bf16 v[92:95], v[176:179], v[210:213], v[92:95]
	v_mfma_f32_16x16x32_bf16 v[92:95], v[180:183], v[214:217], v[92:95]
	v_mfma_f32_16x16x32_bf16 v[88:91], v[186:189], v[210:213], v[88:91]
	v_mfma_f32_16x16x32_bf16 v[88:91], v[190:193], v[214:217], v[88:91]
	v_mfma_f32_16x16x32_bf16 v[76:79], v[176:179], v[218:221], v[76:79]
	v_mfma_f32_16x16x32_bf16 v[76:79], v[180:183], v[222:225], v[76:79]
	v_mfma_f32_16x16x32_bf16 v[72:75], v[186:189], v[218:221], v[72:75]
	v_mfma_f32_16x16x32_bf16 v[72:75], v[190:193], v[222:225], v[72:75]
	s_barrier
	s_add_i32 s55, s72, s5
	v_lshl_add_u64 v[156:157], s[40:41], 0, v[130:131]
	s_mov_b32 m0, s55
	ds_read_b128 v[226:229], v169
	ds_read_b128 v[230:233], v169 offset:1024
	ds_read_b128 v[234:237], v169 offset:2048
	ds_read_b128 v[238:241], v169 offset:3072
	global_load_lds_dwordx4 v[156:157], off
	v_lshl_add_u64 v[162:163], s[40:41], 0, v[134:135]
	s_add_i32 m0, s55, 0x2000
	s_nop 0
	global_load_lds_dwordx4 v[162:163], off
	s_barrier
	s_waitcnt lgkmcnt(0)
	s_waitcnt lgkmcnt(0)
	v_mfma_f32_16x16x32_bf16 v[116:119], v[226:229], v[194:197], v[116:119]
	v_mfma_f32_16x16x32_bf16 v[116:119], v[230:233], v[198:201], v[116:119]
	v_mfma_f32_16x16x32_bf16 v[112:115], v[234:237], v[194:197], v[112:115]
	v_mfma_f32_16x16x32_bf16 v[112:115], v[238:241], v[198:201], v[112:115]
	v_mfma_f32_16x16x32_bf16 v[100:103], v[226:229], v[202:205], v[100:103]
	v_mfma_f32_16x16x32_bf16 v[100:103], v[230:233], v[206:209], v[100:103]
	v_mfma_f32_16x16x32_bf16 v[96:99], v[234:237], v[202:205], v[96:99]
	v_mfma_f32_16x16x32_bf16 v[96:99], v[238:241], v[206:209], v[96:99]
	v_mfma_f32_16x16x32_bf16 v[84:87], v[226:229], v[210:213], v[84:87]
	v_mfma_f32_16x16x32_bf16 v[84:87], v[230:233], v[214:217], v[84:87]
	v_mfma_f32_16x16x32_bf16 v[80:83], v[234:237], v[210:213], v[80:83]
	v_mfma_f32_16x16x32_bf16 v[80:83], v[238:241], v[214:217], v[80:83]
	v_mfma_f32_16x16x32_bf16 v[68:71], v[226:229], v[218:221], v[68:71]
	v_mfma_f32_16x16x32_bf16 v[68:71], v[230:233], v[222:225], v[68:71]
	v_mfma_f32_16x16x32_bf16 v[64:67], v[234:237], v[218:221], v[64:67]
	v_mfma_f32_16x16x32_bf16 v[64:67], v[238:241], v[222:225], v[64:67]
	s_mov_b32 m0, s44
	v_lshl_add_u64 v[170:171], s[42:43], 0, v[128:129]
	s_barrier
	ds_read_b128 v[194:197], v168 offset:16384
	ds_read_b128 v[198:201], v168 offset:17408
	ds_read_b128 v[202:205], v168 offset:18432
	ds_read_b128 v[206:209], v168 offset:19456
	ds_read_b128 v[210:213], v168 offset:20480
	ds_read_b128 v[214:217], v168 offset:21504
	ds_read_b128 v[218:221], v168 offset:22528
	ds_read_b128 v[222:225], v168 offset:23552
	global_load_lds_dwordx4 v[170:171], off
	v_lshl_add_u64 v[242:243], s[42:43], 0, v[132:133]
	s_mov_b32 m0, s45
	s_nop 0
	global_load_lds_dwordx4 v[242:243], off
	s_barrier
	s_waitcnt lgkmcnt(0)
	s_waitcnt lgkmcnt(0)
	v_mfma_f32_16x16x32_bf16 v[60:63], v[176:179], v[194:197], v[60:63]
	v_mfma_f32_16x16x32_bf16 v[60:63], v[180:183], v[198:201], v[60:63]
	v_mfma_f32_16x16x32_bf16 v[56:59], v[186:189], v[194:197], v[56:59]
	v_mfma_f32_16x16x32_bf16 v[56:59], v[190:193], v[198:201], v[56:59]
	v_mfma_f32_16x16x32_bf16 v[44:47], v[176:179], v[202:205], v[44:47]
	v_mfma_f32_16x16x32_bf16 v[44:47], v[180:183], v[206:209], v[44:47]
	v_mfma_f32_16x16x32_bf16 v[40:43], v[186:189], v[202:205], v[40:43]
	v_mfma_f32_16x16x32_bf16 v[40:43], v[190:193], v[206:209], v[40:43]
	v_mfma_f32_16x16x32_bf16 v[28:31], v[176:179], v[210:213], v[28:31]
	v_mfma_f32_16x16x32_bf16 v[28:31], v[180:183], v[214:217], v[28:31]
	v_mfma_f32_16x16x32_bf16 v[24:27], v[186:189], v[210:213], v[24:27]
	v_mfma_f32_16x16x32_bf16 v[24:27], v[190:193], v[214:217], v[24:27]
	v_mfma_f32_16x16x32_bf16 v[12:15], v[176:179], v[218:221], v[12:15]
	v_mfma_f32_16x16x32_bf16 v[12:15], v[180:183], v[222:225], v[12:15]
	v_mfma_f32_16x16x32_bf16 v[8:11], v[186:189], v[218:221], v[8:11]
	v_mfma_f32_16x16x32_bf16 v[8:11], v[190:193], v[222:225], v[8:11]
	s_barrier
	s_add_u32 s62, s40, 0x100000
	s_addc_u32 s63, s41, 0
	s_add_i32 s55, s73, s5
	v_lshl_add_u64 v[176:177], s[62:63], 0, v[130:131]
	s_mov_b32 m0, s55
	s_nop 0
	global_load_lds_dwordx4 v[176:177], off
	v_lshl_add_u64 v[176:177], s[62:63], 0, v[134:135]
	s_add_i32 m0, s55, 0x2000
	s_nop 0
	global_load_lds_dwordx4 v[176:177], off
	s_waitcnt vmcnt(6)
	s_barrier
	v_mfma_f32_16x16x32_bf16 v[52:55], v[226:229], v[194:197], v[52:55]
	v_mfma_f32_16x16x32_bf16 v[52:55], v[230:233], v[198:201], v[52:55]
	v_mfma_f32_16x16x32_bf16 v[48:51], v[234:237], v[194:197], v[48:51]
	v_mfma_f32_16x16x32_bf16 v[48:51], v[238:241], v[198:201], v[48:51]
	v_mfma_f32_16x16x32_bf16 v[36:39], v[226:229], v[202:205], v[36:39]
	v_mfma_f32_16x16x32_bf16 v[36:39], v[230:233], v[206:209], v[36:39]
	v_mfma_f32_16x16x32_bf16 v[32:35], v[234:237], v[202:205], v[32:35]
	v_mfma_f32_16x16x32_bf16 v[32:35], v[238:241], v[206:209], v[32:35]
	v_mfma_f32_16x16x32_bf16 v[20:23], v[226:229], v[210:213], v[20:23]
	v_mfma_f32_16x16x32_bf16 v[20:23], v[230:233], v[214:217], v[20:23]
	v_mfma_f32_16x16x32_bf16 v[16:19], v[234:237], v[210:213], v[16:19]
	v_mfma_f32_16x16x32_bf16 v[16:19], v[238:241], v[214:217], v[16:19]
	v_mfma_f32_16x16x32_bf16 v[4:7], v[226:229], v[218:221], v[4:7]
	v_mfma_f32_16x16x32_bf16 v[4:7], v[230:233], v[222:225], v[4:7]
	v_mfma_f32_16x16x32_bf16 v[0:3], v[234:237], v[218:221], v[0:3]
	v_mfma_f32_16x16x32_bf16 v[0:3], v[238:241], v[222:225], v[0:3]
	s_add_i32 s55, 0, 0x18000
	v_add_u32_e32 v137, s55, v165
	s_barrier
	ds_read_b128 v[176:179], v137
	ds_read_b128 v[180:183], v137 offset:1024
	ds_read_b128 v[186:189], v137 offset:2048
	ds_read_b128 v[190:193], v137 offset:3072
	s_add_u32 s42, s42, 0x100000
	s_addc_u32 s43, s43, 0
	s_mov_b32 m0, s46
	v_lshl_add_u64 v[226:227], s[42:43], 0, v[128:129]
	ds_read_b128 v[194:197], v168 offset:32768
	ds_read_b128 v[198:201], v168 offset:33792
	ds_read_b128 v[202:205], v168 offset:34816
	ds_read_b128 v[206:209], v168 offset:35840
	ds_read_b128 v[210:213], v168 offset:36864
	ds_read_b128 v[214:217], v168 offset:37888
	ds_read_b128 v[218:221], v168 offset:38912
	ds_read_b128 v[222:225], v168 offset:39936
	global_load_lds_dwordx4 v[226:227], off
	v_lshl_add_u64 v[226:227], s[42:43], 0, v[132:133]
	s_mov_b32 m0, s47
	s_nop 0
	global_load_lds_dwordx4 v[226:227], off
	s_waitcnt lgkmcnt(8)
	s_barrier
	s_waitcnt lgkmcnt(0)
	s_waitcnt lgkmcnt(0)
	v_mfma_f32_16x16x32_bf16 v[124:127], v[176:179], v[194:197], v[124:127]
	v_mfma_f32_16x16x32_bf16 v[124:127], v[180:183], v[198:201], v[124:127]
	v_mfma_f32_16x16x32_bf16 v[120:123], v[186:189], v[194:197], v[120:123]
	v_mfma_f32_16x16x32_bf16 v[120:123], v[190:193], v[198:201], v[120:123]
	v_mfma_f32_16x16x32_bf16 v[108:111], v[176:179], v[202:205], v[108:111]
	v_mfma_f32_16x16x32_bf16 v[108:111], v[180:183], v[206:209], v[108:111]
	v_mfma_f32_16x16x32_bf16 v[104:107], v[186:189], v[202:205], v[104:107]
	v_mfma_f32_16x16x32_bf16 v[104:107], v[190:193], v[206:209], v[104:107]
	v_mfma_f32_16x16x32_bf16 v[92:95], v[176:179], v[210:213], v[92:95]
	v_mfma_f32_16x16x32_bf16 v[92:95], v[180:183], v[214:217], v[92:95]
	v_mfma_f32_16x16x32_bf16 v[88:91], v[186:189], v[210:213], v[88:91]
	v_mfma_f32_16x16x32_bf16 v[88:91], v[190:193], v[214:217], v[88:91]
	v_mfma_f32_16x16x32_bf16 v[76:79], v[176:179], v[218:221], v[76:79]
	v_mfma_f32_16x16x32_bf16 v[76:79], v[180:183], v[222:225], v[76:79]
	v_mfma_f32_16x16x32_bf16 v[72:75], v[186:189], v[218:221], v[72:75]
	v_mfma_f32_16x16x32_bf16 v[72:75], v[190:193], v[222:225], v[72:75]
	s_barrier
	s_add_i32 s42, 0, 0x1c000
	s_add_i32 s43, s55, s5
	v_add_u32_e32 v137, s42, v165
	v_lshl_add_u64 v[156:157], v[156:157], 0, s[24:25]
	s_mov_b32 m0, s43
	ds_read_b128 v[226:229], v137
	ds_read_b128 v[230:233], v137 offset:1024
	ds_read_b128 v[234:237], v137 offset:2048
	ds_read_b128 v[238:241], v137 offset:3072
	global_load_lds_dwordx4 v[156:157], off
	v_lshl_add_u64 v[156:157], v[162:163], 0, s[24:25]
	s_add_i32 m0, s43, 0x2000
	s_nop 0
	global_load_lds_dwordx4 v[156:157], off
	s_barrier
	s_waitcnt lgkmcnt(0)
	s_waitcnt lgkmcnt(0)
	v_mfma_f32_16x16x32_bf16 v[116:119], v[226:229], v[194:197], v[116:119]
	v_mfma_f32_16x16x32_bf16 v[116:119], v[230:233], v[198:201], v[116:119]
	v_mfma_f32_16x16x32_bf16 v[112:115], v[234:237], v[194:197], v[112:115]
	v_mfma_f32_16x16x32_bf16 v[112:115], v[238:241], v[198:201], v[112:115]
	v_mfma_f32_16x16x32_bf16 v[100:103], v[226:229], v[202:205], v[100:103]
	v_mfma_f32_16x16x32_bf16 v[100:103], v[230:233], v[206:209], v[100:103]
	v_mfma_f32_16x16x32_bf16 v[96:99], v[234:237], v[202:205], v[96:99]
	v_mfma_f32_16x16x32_bf16 v[96:99], v[238:241], v[206:209], v[96:99]
	v_mfma_f32_16x16x32_bf16 v[84:87], v[226:229], v[210:213], v[84:87]
	v_mfma_f32_16x16x32_bf16 v[84:87], v[230:233], v[214:217], v[84:87]
	v_mfma_f32_16x16x32_bf16 v[80:83], v[234:237], v[210:213], v[80:83]
	v_mfma_f32_16x16x32_bf16 v[80:83], v[238:241], v[214:217], v[80:83]
	v_mfma_f32_16x16x32_bf16 v[68:71], v[226:229], v[218:221], v[68:71]
	v_mfma_f32_16x16x32_bf16 v[68:71], v[230:233], v[222:225], v[68:71]
	v_mfma_f32_16x16x32_bf16 v[64:67], v[234:237], v[218:221], v[64:67]
	v_mfma_f32_16x16x32_bf16 v[64:67], v[238:241], v[222:225], v[64:67]
	s_mov_b32 m0, s49
	v_lshl_add_u64 v[156:157], v[170:171], 0, s[24:25]
	s_barrier
	ds_read_b128 v[194:197], v168 offset:49152
	ds_read_b128 v[198:201], v168 offset:50176
	ds_read_b128 v[202:205], v168 offset:51200
	ds_read_b128 v[206:209], v168 offset:52224
	ds_read_b128 v[210:213], v168 offset:53248
	ds_read_b128 v[214:217], v168 offset:54272
	ds_read_b128 v[218:221], v168 offset:55296
	ds_read_b128 v[222:225], v168 offset:56320
	global_load_lds_dwordx4 v[156:157], off
	v_lshl_add_u64 v[156:157], v[242:243], 0, s[24:25]
	s_mov_b32 m0, s50
	s_nop 0
	global_load_lds_dwordx4 v[156:157], off
	s_barrier
	s_waitcnt lgkmcnt(0)
	s_waitcnt lgkmcnt(0)
	v_mfma_f32_16x16x32_bf16 v[60:63], v[176:179], v[194:197], v[60:63]
	v_mfma_f32_16x16x32_bf16 v[60:63], v[180:183], v[198:201], v[60:63]
	v_mfma_f32_16x16x32_bf16 v[56:59], v[186:189], v[194:197], v[56:59]
	v_mfma_f32_16x16x32_bf16 v[56:59], v[190:193], v[198:201], v[56:59]
	v_mfma_f32_16x16x32_bf16 v[44:47], v[176:179], v[202:205], v[44:47]
	v_mfma_f32_16x16x32_bf16 v[44:47], v[180:183], v[206:209], v[44:47]
	v_mfma_f32_16x16x32_bf16 v[40:43], v[186:189], v[202:205], v[40:43]
	v_mfma_f32_16x16x32_bf16 v[40:43], v[190:193], v[206:209], v[40:43]
	v_mfma_f32_16x16x32_bf16 v[28:31], v[176:179], v[210:213], v[28:31]
	v_mfma_f32_16x16x32_bf16 v[28:31], v[180:183], v[214:217], v[28:31]
	v_mfma_f32_16x16x32_bf16 v[24:27], v[186:189], v[210:213], v[24:27]
	v_mfma_f32_16x16x32_bf16 v[24:27], v[190:193], v[214:217], v[24:27]
	v_mfma_f32_16x16x32_bf16 v[12:15], v[176:179], v[218:221], v[12:15]
	v_mfma_f32_16x16x32_bf16 v[12:15], v[180:183], v[222:225], v[12:15]
	v_mfma_f32_16x16x32_bf16 v[8:11], v[186:189], v[218:221], v[8:11]
	v_mfma_f32_16x16x32_bf16 v[8:11], v[190:193], v[222:225], v[8:11]
	s_barrier
	s_add_u32 s40, s40, 0x100080
	s_addc_u32 s41, s41, 0
	s_add_i32 s42, s42, s5
	v_lshl_add_u64 v[156:157], s[40:41], 0, v[130:131]
	s_mov_b32 m0, s42
	s_nop 0
	global_load_lds_dwordx4 v[156:157], off
	v_lshl_add_u64 v[156:157], s[40:41], 0, v[134:135]
	s_add_i32 m0, s42, 0x2000
	s_nop 0
	global_load_lds_dwordx4 v[156:157], off
	s_waitcnt vmcnt(6)
	s_barrier
	v_mfma_f32_16x16x32_bf16 v[52:55], v[226:229], v[194:197], v[52:55]
	v_mfma_f32_16x16x32_bf16 v[52:55], v[230:233], v[198:201], v[52:55]
	v_mfma_f32_16x16x32_bf16 v[48:51], v[234:237], v[194:197], v[48:51]
	v_mfma_f32_16x16x32_bf16 v[48:51], v[238:241], v[198:201], v[48:51]
	v_mfma_f32_16x16x32_bf16 v[36:39], v[226:229], v[202:205], v[36:39]
	v_mfma_f32_16x16x32_bf16 v[36:39], v[230:233], v[206:209], v[36:39]
	v_mfma_f32_16x16x32_bf16 v[32:35], v[234:237], v[202:205], v[32:35]
	v_mfma_f32_16x16x32_bf16 v[32:35], v[238:241], v[206:209], v[32:35]
	v_mfma_f32_16x16x32_bf16 v[20:23], v[226:229], v[210:213], v[20:23]
	v_mfma_f32_16x16x32_bf16 v[20:23], v[230:233], v[214:217], v[20:23]
	v_mfma_f32_16x16x32_bf16 v[16:19], v[234:237], v[210:213], v[16:19]
	v_mfma_f32_16x16x32_bf16 v[16:19], v[238:241], v[214:217], v[16:19]
	v_mfma_f32_16x16x32_bf16 v[4:7], v[226:229], v[218:221], v[4:7]
	v_mfma_f32_16x16x32_bf16 v[4:7], v[230:233], v[222:225], v[4:7]
	v_mfma_f32_16x16x32_bf16 v[0:3], v[234:237], v[218:221], v[0:3]
	v_mfma_f32_16x16x32_bf16 v[0:3], v[238:241], v[222:225], v[0:3]
	s_add_i32 s54, s54, 2
	s_add_u32 s38, s38, 0x100
	s_addc_u32 s39, s39, 0
	s_add_u32 s27, s27, 0x100
	s_addc_u32 s29, s29, 0
	s_cmp_gt_u32 s54, 61
	s_cbranch_scc0 .Lrot_127
	s_barrier
	v_lshl_or_b32 v156, s8, 8, v166
	s_waitcnt vmcnt(0)
	v_pk_mul_f32 v[126:127], v[160:161], v[126:127] op_sel_hi:[0,1]
	v_pk_mul_f32 v[124:125], v[160:161], v[124:125] op_sel_hi:[0,1]
	v_pk_mul_f32 v[122:123], v[160:161], v[122:123] op_sel_hi:[0,1]
	v_pk_mul_f32 v[162:163], v[160:161], v[120:121] op_sel_hi:[0,1]
	v_cmp_lt_i32_e64 s[8:9], s74, v156
	s_and_saveexec_b64 s[38:39], s[8:9]
	s_cbranch_execz .LBB0_130
	v_mul_f32_e32 v147, 0xbfb8aa3b, v126
	v_mul_f32_e32 v121, 0xbfb8aa3b, v162
	v_exp_f32_e32 v147, v147
	v_mul_f32_e32 v149, 0xbfb8aa3b, v122
	v_mul_f32_e32 v137, 0xbfb8aa3b, v125
	v_exp_f32_e32 v121, v121
	v_exp_f32_e32 v149, v149
	v_exp_f32_e32 v137, v137
	v_add_f32_e32 v147, 1.0, v147
	v_add_f32_e32 v121, 1.0, v121
	v_rcp_f32_e32 v176, v147
	v_add_f32_e32 v147, 1.0, v149
	v_mul_f32_e32 v149, 0xbfb8aa3b, v127
	v_mul_f32_e32 v120, 0xbfb8aa3b, v124
	v_rcp_f32_e32 v170, v121
	v_add_f32_e32 v121, 1.0, v137
	v_mul_f32_e32 v137, 0xbfb8aa3b, v163
	v_exp_f32_e32 v149, v149
	v_mul_f32_e32 v151, 0xbfb8aa3b, v123
	v_exp_f32_e32 v120, v120
	v_exp_f32_e32 v137, v137
	v_exp_f32_e32 v151, v151
	v_rcp_f32_e32 v178, v147
	v_add_f32_e32 v147, 1.0, v149
	v_add_f32_e32 v120, 1.0, v120
	v_add_f32_e32 v137, 1.0, v137
	v_rcp_f32_e32 v177, v147
	v_add_f32_e32 v147, 1.0, v151
	v_rcp_f32_e32 v120, v120
	v_rcp_f32_e32 v121, v121
	v_rcp_f32_e32 v179, v147
	v_rcp_f32_e32 v171, v137
	v_pk_mul_f32 v[126:127], v[126:127], v[176:177]
	v_pk_mul_f32 v[124:125], v[124:125], v[120:121]
	v_pk_mul_f32 v[122:123], v[122:123], v[178:179]
	v_pk_mul_f32 v[162:163], v[162:163], v[170:171]

.LBB0_300:
	s_ashr_i32 s37, s36, 31
	s_lshl_b64 s[40:41], s[36:37], 19
	s_add_u32 s40, s30, s40
	s_addc_u32 s41, s31, s41
	s_and_b64 s[46:47], s[8:9], exec
	s_cselect_b32 s37, s41, s45
	s_cselect_b32 s62, s40, s44
	s_add_u32 s63, s44, 0x100
	v_mov_b32_e32 v0, 0
	s_addc_u32 s82, s45, 0
	s_mov_b32 s83, -2
	v_mov_b32_e32 v1, v0
	v_mov_b32_e32 v2, v0
	v_mov_b32_e32 v3, v0
	v_mov_b32_e32 v4, v0
	v_mov_b32_e32 v5, v0
	v_mov_b32_e32 v6, v0
	v_mov_b32_e32 v7, v0
	v_mov_b32_e32 v12, v0
	v_mov_b32_e32 v13, v0
	v_mov_b32_e32 v14, v0
	v_mov_b32_e32 v15, v0
	v_mov_b32_e32 v20, v0
	v_mov_b32_e32 v21, v0
	v_mov_b32_e32 v22, v0
	v_mov_b32_e32 v23, v0
	v_mov_b32_e32 v28, v0
	v_mov_b32_e32 v29, v0
	v_mov_b32_e32 v30, v0
	v_mov_b32_e32 v31, v0
	v_mov_b32_e32 v36, v0
	v_mov_b32_e32 v37, v0
	v_mov_b32_e32 v38, v0
	v_mov_b32_e32 v39, v0
	v_mov_b32_e32 v44, v0
	v_mov_b32_e32 v45, v0
	v_mov_b32_e32 v46, v0
	v_mov_b32_e32 v47, v0
	v_mov_b32_e32 v52, v0
	v_mov_b32_e32 v53, v0
	v_mov_b32_e32 v54, v0
	v_mov_b32_e32 v55, v0
	v_mov_b32_e32 v8, v0
	v_mov_b32_e32 v9, v0
	v_mov_b32_e32 v10, v0
	v_mov_b32_e32 v11, v0
	v_mov_b32_e32 v16, v0
	v_mov_b32_e32 v17, v0
	v_mov_b32_e32 v18, v0
	v_mov_b32_e32 v19, v0
	v_mov_b32_e32 v24, v0
	v_mov_b32_e32 v25, v0
	v_mov_b32_e32 v26, v0
	v_mov_b32_e32 v27, v0
	v_mov_b32_e32 v32, v0
	v_mov_b32_e32 v33, v0
	v_mov_b32_e32 v34, v0
	v_mov_b32_e32 v35, v0
	v_mov_b32_e32 v40, v0
	v_mov_b32_e32 v41, v0
	v_mov_b32_e32 v42, v0
	v_mov_b32_e32 v43, v0
	v_mov_b32_e32 v48, v0
	v_mov_b32_e32 v49, v0
	v_mov_b32_e32 v50, v0
	v_mov_b32_e32 v51, v0
	v_mov_b32_e32 v56, v0
	v_mov_b32_e32 v57, v0
	v_mov_b32_e32 v58, v0
	v_mov_b32_e32 v59, v0
	v_mov_b32_e32 v60, v0
	v_mov_b32_e32 v61, v0
	v_mov_b32_e32 v62, v0
	v_mov_b32_e32 v63, v0
	v_mov_b32_e32 v64, v0
	v_mov_b32_e32 v65, v0
	v_mov_b32_e32 v66, v0
	v_mov_b32_e32 v67, v0
	v_mov_b32_e32 v68, v0
	v_mov_b32_e32 v69, v0
	v_mov_b32_e32 v70, v0
	v_mov_b32_e32 v71, v0
	v_mov_b32_e32 v76, v0
	v_mov_b32_e32 v77, v0
	v_mov_b32_e32 v78, v0
	v_mov_b32_e32 v79, v0
	v_mov_b32_e32 v84, v0
	v_mov_b32_e32 v85, v0
	v_mov_b32_e32 v86, v0
	v_mov_b32_e32 v87, v0
	v_mov_b32_e32 v92, v0
	v_mov_b32_e32 v93, v0
	v_mov_b32_e32 v94, v0
	v_mov_b32_e32 v95, v0
	v_mov_b32_e32 v100, v0
	v_mov_b32_e32 v101, v0
	v_mov_b32_e32 v102, v0
	v_mov_b32_e32 v103, v0
	v_mov_b32_e32 v108, v0
	v_mov_b32_e32 v109, v0
	v_mov_b32_e32 v110, v0
	v_mov_b32_e32 v111, v0
	v_mov_b32_e32 v116, v0
	v_mov_b32_e32 v117, v0
	v_mov_b32_e32 v118, v0
	v_mov_b32_e32 v119, v0
	v_mov_b32_e32 v72, v0
	v_mov_b32_e32 v73, v0
	v_mov_b32_e32 v74, v0
	v_mov_b32_e32 v75, v0
	v_mov_b32_e32 v80, v0
	v_mov_b32_e32 v81, v0
	v_mov_b32_e32 v82, v0
	v_mov_b32_e32 v83, v0
	v_mov_b32_e32 v88, v0
	v_mov_b32_e32 v89, v0
	v_mov_b32_e32 v90, v0
	v_mov_b32_e32 v91, v0
	v_mov_b32_e32 v96, v0
	v_mov_b32_e32 v97, v0
	v_mov_b32_e32 v98, v0
	v_mov_b32_e32 v99, v0
	v_mov_b32_e32 v104, v0
	v_mov_b32_e32 v105, v0
	v_mov_b32_e32 v106, v0
	v_mov_b32_e32 v107, v0
	v_mov_b32_e32 v112, v0
	v_mov_b32_e32 v113, v0
	v_mov_b32_e32 v114, v0
	v_mov_b32_e32 v115, v0
	v_mov_b32_e32 v120, v0
	v_mov_b32_e32 v121, v0
	v_mov_b32_e32 v122, v0
	v_mov_b32_e32 v123, v0
	v_mov_b32_e32 v124, v0
	v_mov_b32_e32 v125, v0
	v_mov_b32_e32 v126, v0
	v_mov_b32_e32 v127, v0
	s_branch .LBB0_301

.LBB0_301:
	ds_read_b128 v[160:163], v151
	ds_read_b128 v[164:167], v151 offset:1024
	ds_read_b128 v[168:171], v151 offset:2048
	ds_read_b128 v[176:179], v151 offset:3072
	s_add_u32 s44, s42, 0x100
	s_addc_u32 s45, s43, 0
	s_cmp_eq_u32 s83, 12
	s_cselect_b32 s49, s39, s45
	s_cselect_b32 s48, s38, s44
	s_cselect_b32 s47, s37, s82
	s_cselect_b32 s46, s62, s63
	v_lshl_add_u64 v[214:215], s[42:43], 0, v[142:143]
	s_add_i32 m0, s50, 0xc000
	ds_read_b128 v[180:183], v153
	ds_read_b128 v[186:189], v153 offset:1024
	ds_read_b128 v[190:193], v153 offset:2048
	ds_read_b128 v[194:197], v153 offset:3072
	ds_read_b128 v[198:201], v153 offset:4096
	ds_read_b128 v[202:205], v153 offset:5120
	ds_read_b128 v[206:209], v153 offset:6144
	ds_read_b128 v[210:213], v153 offset:7168
	global_load_lds_dwordx4 v[214:215], off
	v_lshl_add_u64 v[214:215], s[42:43], 0, v[144:145]
	s_add_i32 m0, s50, 0xe000
	s_nop 0
	global_load_lds_dwordx4 v[214:215], off
	s_waitcnt lgkmcnt(8)
	s_barrier
	s_waitcnt lgkmcnt(0)
	s_waitcnt lgkmcnt(0)
	v_mfma_f32_16x16x32_bf16 v[124:127], v[160:163], v[180:183], v[124:127]
	v_mfma_f32_16x16x32_bf16 v[124:127], v[164:167], v[186:189], v[124:127]
	v_mfma_f32_16x16x32_bf16 v[120:123], v[168:171], v[180:183], v[120:123]
	v_mfma_f32_16x16x32_bf16 v[120:123], v[176:179], v[186:189], v[120:123]
	v_mfma_f32_16x16x32_bf16 v[112:115], v[160:163], v[190:193], v[112:115]
	v_mfma_f32_16x16x32_bf16 v[112:115], v[164:167], v[194:197], v[112:115]
	v_mfma_f32_16x16x32_bf16 v[104:107], v[168:171], v[190:193], v[104:107]
	v_mfma_f32_16x16x32_bf16 v[104:107], v[176:179], v[194:197], v[104:107]
	v_mfma_f32_16x16x32_bf16 v[96:99], v[160:163], v[198:201], v[96:99]
	v_mfma_f32_16x16x32_bf16 v[96:99], v[164:167], v[202:205], v[96:99]
	v_mfma_f32_16x16x32_bf16 v[88:91], v[168:171], v[198:201], v[88:91]
	v_mfma_f32_16x16x32_bf16 v[88:91], v[176:179], v[202:205], v[88:91]
	v_mfma_f32_16x16x32_bf16 v[80:83], v[160:163], v[206:209], v[80:83]
	v_mfma_f32_16x16x32_bf16 v[80:83], v[164:167], v[210:213], v[80:83]
	v_mfma_f32_16x16x32_bf16 v[72:75], v[168:171], v[206:209], v[72:75]
	v_mfma_f32_16x16x32_bf16 v[72:75], v[176:179], v[210:213], v[72:75]
	s_barrier
	s_add_i32 s42, s76, s5
	v_lshl_add_u64 v[230:231], s[46:47], 0, v[132:133]
	s_mov_b32 m0, s42
	ds_read_b128 v[214:217], v155
	ds_read_b128 v[218:221], v155 offset:1024
	ds_read_b128 v[222:225], v155 offset:2048
	ds_read_b128 v[226:229], v155 offset:3072
	global_load_lds_dwordx4 v[230:231], off
	v_lshl_add_u64 v[232:233], s[46:47], 0, v[128:129]
	s_add_i32 m0, s42, 0x2000
	s_nop 0
	global_load_lds_dwordx4 v[232:233], off
	s_barrier
	s_waitcnt lgkmcnt(0)
	s_waitcnt lgkmcnt(0)
	v_mfma_f32_16x16x32_bf16 v[116:119], v[214:217], v[180:183], v[116:119]
	v_mfma_f32_16x16x32_bf16 v[116:119], v[218:221], v[186:189], v[116:119]
	v_mfma_f32_16x16x32_bf16 v[108:111], v[222:225], v[180:183], v[108:111]
	v_mfma_f32_16x16x32_bf16 v[108:111], v[226:229], v[186:189], v[108:111]
	v_mfma_f32_16x16x32_bf16 v[100:103], v[214:217], v[190:193], v[100:103]
	v_mfma_f32_16x16x32_bf16 v[100:103], v[218:221], v[194:197], v[100:103]
	v_mfma_f32_16x16x32_bf16 v[92:95], v[222:225], v[190:193], v[92:95]
	v_mfma_f32_16x16x32_bf16 v[92:95], v[226:229], v[194:197], v[92:95]
	v_mfma_f32_16x16x32_bf16 v[84:87], v[214:217], v[198:201], v[84:87]
	v_mfma_f32_16x16x32_bf16 v[84:87], v[218:221], v[202:205], v[84:87]
	v_mfma_f32_16x16x32_bf16 v[76:79], v[222:225], v[198:201], v[76:79]
	v_mfma_f32_16x16x32_bf16 v[76:79], v[226:229], v[202:205], v[76:79]
	v_mfma_f32_16x16x32_bf16 v[68:71], v[214:217], v[206:209], v[68:71]
	v_mfma_f32_16x16x32_bf16 v[68:71], v[218:221], v[210:213], v[68:71]
	v_mfma_f32_16x16x32_bf16 v[64:67], v[222:225], v[206:209], v[64:67]
	v_mfma_f32_16x16x32_bf16 v[64:67], v[226:229], v[210:213], v[64:67]
	s_mov_b32 m0, s50
	v_lshl_add_u64 v[234:235], s[48:49], 0, v[134:135]
	s_barrier
	ds_read_b128 v[180:183], v153 offset:16384
	ds_read_b128 v[186:189], v153 offset:17408
	ds_read_b128 v[190:193], v153 offset:18432
	ds_read_b128 v[194:197], v153 offset:19456
	ds_read_b128 v[198:201], v153 offset:20480
	ds_read_b128 v[202:205], v153 offset:21504
	ds_read_b128 v[206:209], v153 offset:22528
	ds_read_b128 v[210:213], v153 offset:23552
	global_load_lds_dwordx4 v[234:235], off
	v_lshl_add_u64 v[236:237], s[48:49], 0, v[130:131]
	s_mov_b32 m0, s51
	s_nop 0
	global_load_lds_dwordx4 v[236:237], off
	s_barrier
	s_waitcnt lgkmcnt(0)
	s_waitcnt lgkmcnt(0)
	v_mfma_f32_16x16x32_bf16 v[60:63], v[160:163], v[180:183], v[60:63]
	v_mfma_f32_16x16x32_bf16 v[60:63], v[164:167], v[186:189], v[60:63]
	v_mfma_f32_16x16x32_bf16 v[56:59], v[168:171], v[180:183], v[56:59]
	v_mfma_f32_16x16x32_bf16 v[56:59], v[176:179], v[186:189], v[56:59]
	v_mfma_f32_16x16x32_bf16 v[48:51], v[160:163], v[190:193], v[48:51]
	v_mfma_f32_16x16x32_bf16 v[48:51], v[164:167], v[194:197], v[48:51]
	v_mfma_f32_16x16x32_bf16 v[40:43], v[168:171], v[190:193], v[40:43]
	v_mfma_f32_16x16x32_bf16 v[40:43], v[176:179], v[194:197], v[40:43]
	v_mfma_f32_16x16x32_bf16 v[32:35], v[160:163], v[198:201], v[32:35]
	v_mfma_f32_16x16x32_bf16 v[32:35], v[164:167], v[202:205], v[32:35]
	v_mfma_f32_16x16x32_bf16 v[24:27], v[168:171], v[198:201], v[24:27]
	v_mfma_f32_16x16x32_bf16 v[24:27], v[176:179], v[202:205], v[24:27]
	v_mfma_f32_16x16x32_bf16 v[16:19], v[160:163], v[206:209], v[16:19]
	v_mfma_f32_16x16x32_bf16 v[16:19], v[164:167], v[210:213], v[16:19]
	v_mfma_f32_16x16x32_bf16 v[8:11], v[168:171], v[206:209], v[8:11]
	v_mfma_f32_16x16x32_bf16 v[8:11], v[176:179], v[210:213], v[8:11]
	s_barrier
	s_add_u32 s42, s46, 0x40000
	s_addc_u32 s43, s47, 0
	s_add_i32 s84, s77, s5
	v_lshl_add_u64 v[160:161], s[42:43], 0, v[132:133]
	s_mov_b32 m0, s84
	s_nop 0
	global_load_lds_dwordx4 v[160:161], off
	v_lshl_add_u64 v[160:161], s[42:43], 0, v[128:129]
	s_add_i32 m0, s84, 0x2000
	s_nop 0
	global_load_lds_dwordx4 v[160:161], off
	s_waitcnt vmcnt(6)
	s_barrier
	v_mfma_f32_16x16x32_bf16 v[52:55], v[214:217], v[180:183], v[52:55]
	v_mfma_f32_16x16x32_bf16 v[52:55], v[218:221], v[186:189], v[52:55]
	v_mfma_f32_16x16x32_bf16 v[44:47], v[222:225], v[180:183], v[44:47]
	v_mfma_f32_16x16x32_bf16 v[44:47], v[226:229], v[186:189], v[44:47]
	v_mfma_f32_16x16x32_bf16 v[36:39], v[214:217], v[190:193], v[36:39]
	v_mfma_f32_16x16x32_bf16 v[36:39], v[218:221], v[194:197], v[36:39]
	v_mfma_f32_16x16x32_bf16 v[28:31], v[222:225], v[190:193], v[28:31]
	v_mfma_f32_16x16x32_bf16 v[28:31], v[226:229], v[194:197], v[28:31]
	v_mfma_f32_16x16x32_bf16 v[20:23], v[214:217], v[198:201], v[20:23]
	v_mfma_f32_16x16x32_bf16 v[20:23], v[218:221], v[202:205], v[20:23]
	v_mfma_f32_16x16x32_bf16 v[12:15], v[222:225], v[198:201], v[12:15]
	v_mfma_f32_16x16x32_bf16 v[12:15], v[226:229], v[202:205], v[12:15]
	v_mfma_f32_16x16x32_bf16 v[4:7], v[214:217], v[206:209], v[4:7]
	v_mfma_f32_16x16x32_bf16 v[4:7], v[218:221], v[210:213], v[4:7]
	v_mfma_f32_16x16x32_bf16 v[0:3], v[222:225], v[206:209], v[0:3]
	v_mfma_f32_16x16x32_bf16 v[0:3], v[226:229], v[210:213], v[0:3]
	s_add_i32 s84, 0, 0x18000
	v_add_u32_e32 v157, s84, v139
	s_barrier
	ds_read_b128 v[160:163], v157
	ds_read_b128 v[164:167], v157 offset:1024
	ds_read_b128 v[168:171], v157 offset:2048
	ds_read_b128 v[176:179], v157 offset:3072
	s_add_u32 s42, s48, 0x170000
	s_addc_u32 s43, s49, 0
	s_mov_b32 m0, s52
	v_lshl_add_u64 v[214:215], s[42:43], 0, v[134:135]
	ds_read_b128 v[180:183], v153 offset:32768
	ds_read_b128 v[186:189], v153 offset:33792
	ds_read_b128 v[190:193], v153 offset:34816
	ds_read_b128 v[194:197], v153 offset:35840
	ds_read_b128 v[198:201], v153 offset:36864
	ds_read_b128 v[202:205], v153 offset:37888
	ds_read_b128 v[206:209], v153 offset:38912
	ds_read_b128 v[210:213], v153 offset:39936
	global_load_lds_dwordx4 v[214:215], off
	v_lshl_add_u64 v[214:215], s[42:43], 0, v[130:131]
	s_mov_b32 m0, s53
	s_nop 0
	global_load_lds_dwordx4 v[214:215], off
	s_waitcnt lgkmcnt(8)
	s_barrier
	s_waitcnt lgkmcnt(0)
	s_waitcnt lgkmcnt(0)
	v_mfma_f32_16x16x32_bf16 v[124:127], v[160:163], v[180:183], v[124:127]
	v_mfma_f32_16x16x32_bf16 v[124:127], v[164:167], v[186:189], v[124:127]
	v_mfma_f32_16x16x32_bf16 v[120:123], v[168:171], v[180:183], v[120:123]
	v_mfma_f32_16x16x32_bf16 v[120:123], v[176:179], v[186:189], v[120:123]
	v_mfma_f32_16x16x32_bf16 v[112:115], v[160:163], v[190:193], v[112:115]
	v_mfma_f32_16x16x32_bf16 v[112:115], v[164:167], v[194:197], v[112:115]
	v_mfma_f32_16x16x32_bf16 v[104:107], v[168:171], v[190:193], v[104:107]
	v_mfma_f32_16x16x32_bf16 v[104:107], v[176:179], v[194:197], v[104:107]
	v_mfma_f32_16x16x32_bf16 v[96:99], v[160:163], v[198:201], v[96:99]
	v_mfma_f32_16x16x32_bf16 v[96:99], v[164:167], v[202:205], v[96:99]
	v_mfma_f32_16x16x32_bf16 v[88:91], v[168:171], v[198:201], v[88:91]
	v_mfma_f32_16x16x32_bf16 v[88:91], v[176:179], v[202:205], v[88:91]
	v_mfma_f32_16x16x32_bf16 v[80:83], v[160:163], v[206:209], v[80:83]
	v_mfma_f32_16x16x32_bf16 v[80:83], v[164:167], v[210:213], v[80:83]
	v_mfma_f32_16x16x32_bf16 v[72:75], v[168:171], v[206:209], v[72:75]
	v_mfma_f32_16x16x32_bf16 v[72:75], v[176:179], v[210:213], v[72:75]
	s_barrier
	s_add_i32 s48, 0, 0x1c000
	s_add_i32 s42, s84, s5
	v_add_u32_e32 v157, s48, v139
	v_lshl_add_u64 v[230:231], v[230:231], 0, s[10:11]
	s_mov_b32 m0, s42
	ds_read_b128 v[214:217], v157
	ds_read_b128 v[218:221], v157 offset:1024
	ds_read_b128 v[222:225], v157 offset:2048
	ds_read_b128 v[226:229], v157 offset:3072
	global_load_lds_dwordx4 v[230:231], off
	v_lshl_add_u64 v[230:231], v[232:233], 0, s[10:11]
	s_add_i32 m0, s42, 0x2000
	s_nop 0
	global_load_lds_dwordx4 v[230:231], off
	s_barrier
	s_waitcnt lgkmcnt(0)
	s_waitcnt lgkmcnt(0)
	v_mfma_f32_16x16x32_bf16 v[116:119], v[214:217], v[180:183], v[116:119]
	v_mfma_f32_16x16x32_bf16 v[116:119], v[218:221], v[186:189], v[116:119]
	v_mfma_f32_16x16x32_bf16 v[108:111], v[222:225], v[180:183], v[108:111]
	v_mfma_f32_16x16x32_bf16 v[108:111], v[226:229], v[186:189], v[108:111]
	v_mfma_f32_16x16x32_bf16 v[100:103], v[214:217], v[190:193], v[100:103]
	v_mfma_f32_16x16x32_bf16 v[100:103], v[218:221], v[194:197], v[100:103]
	v_mfma_f32_16x16x32_bf16 v[92:95], v[222:225], v[190:193], v[92:95]
	v_mfma_f32_16x16x32_bf16 v[92:95], v[226:229], v[194:197], v[92:95]
	v_mfma_f32_16x16x32_bf16 v[84:87], v[214:217], v[198:201], v[84:87]
	v_mfma_f32_16x16x32_bf16 v[84:87], v[218:221], v[202:205], v[84:87]
	v_mfma_f32_16x16x32_bf16 v[76:79], v[222:225], v[198:201], v[76:79]
	v_mfma_f32_16x16x32_bf16 v[76:79], v[226:229], v[202:205], v[76:79]
	v_mfma_f32_16x16x32_bf16 v[68:71], v[214:217], v[206:209], v[68:71]
	v_mfma_f32_16x16x32_bf16 v[68:71], v[218:221], v[210:213], v[68:71]
	v_mfma_f32_16x16x32_bf16 v[64:67], v[222:225], v[206:209], v[64:67]
	v_mfma_f32_16x16x32_bf16 v[64:67], v[226:229], v[210:213], v[64:67]
	s_mov_b32 m0, s55
	v_lshl_add_u64 v[230:231], v[234:235], 0, s[10:11]
	s_barrier
	ds_read_b128 v[180:183], v153 offset:49152
	ds_read_b128 v[186:189], v153 offset:50176
	ds_read_b128 v[190:193], v153 offset:51200
	ds_read_b128 v[194:197], v153 offset:52224
	ds_read_b128 v[198:201], v153 offset:53248
	ds_read_b128 v[202:205], v153 offset:54272
	ds_read_b128 v[206:209], v153 offset:55296
	ds_read_b128 v[210:213], v153 offset:56320
	global_load_lds_dwordx4 v[230:231], off
	v_lshl_add_u64 v[230:231], v[236:237], 0, s[10:11]
	s_mov_b32 m0, s61
	s_nop 0
	global_load_lds_dwordx4 v[230:231], off
	s_barrier
	s_waitcnt lgkmcnt(0)
	s_waitcnt lgkmcnt(0)
	v_mfma_f32_16x16x32_bf16 v[60:63], v[160:163], v[180:183], v[60:63]
	v_mfma_f32_16x16x32_bf16 v[60:63], v[164:167], v[186:189], v[60:63]
	v_mfma_f32_16x16x32_bf16 v[56:59], v[168:171], v[180:183], v[56:59]
	v_mfma_f32_16x16x32_bf16 v[56:59], v[176:179], v[186:189], v[56:59]
	v_mfma_f32_16x16x32_bf16 v[48:51], v[160:163], v[190:193], v[48:51]
	v_mfma_f32_16x16x32_bf16 v[48:51], v[164:167], v[194:197], v[48:51]
	v_mfma_f32_16x16x32_bf16 v[40:43], v[168:171], v[190:193], v[40:43]
	v_mfma_f32_16x16x32_bf16 v[40:43], v[176:179], v[194:197], v[40:43]
	v_mfma_f32_16x16x32_bf16 v[32:35], v[160:163], v[198:201], v[32:35]
	v_mfma_f32_16x16x32_bf16 v[32:35], v[164:167], v[202:205], v[32:35]
	v_mfma_f32_16x16x32_bf16 v[24:27], v[168:171], v[198:201], v[24:27]
	v_mfma_f32_16x16x32_bf16 v[24:27], v[176:179], v[202:205], v[24:27]
	v_mfma_f32_16x16x32_bf16 v[16:19], v[160:163], v[206:209], v[16:19]
	v_mfma_f32_16x16x32_bf16 v[16:19], v[164:167], v[210:213], v[16:19]
	v_mfma_f32_16x16x32_bf16 v[8:11], v[168:171], v[206:209], v[8:11]
	v_mfma_f32_16x16x32_bf16 v[8:11], v[176:179], v[210:213], v[8:11]
	s_barrier
	s_add_u32 s42, s46, 0x40080
	s_addc_u32 s43, s47, 0
	s_add_i32 s46, s48, s5
	v_lshl_add_u64 v[160:161], s[42:43], 0, v[132:133]
	s_mov_b32 m0, s46
	s_nop 0
	global_load_lds_dwordx4 v[160:161], off
	v_lshl_add_u64 v[160:161], s[42:43], 0, v[128:129]
	s_add_i32 m0, s46, 0x2000
	s_nop 0
	global_load_lds_dwordx4 v[160:161], off
	s_waitcnt vmcnt(6)
	s_barrier
	v_mfma_f32_16x16x32_bf16 v[52:55], v[214:217], v[180:183], v[52:55]
	v_mfma_f32_16x16x32_bf16 v[52:55], v[218:221], v[186:189], v[52:55]
	v_mfma_f32_16x16x32_bf16 v[44:47], v[222:225], v[180:183], v[44:47]
	v_mfma_f32_16x16x32_bf16 v[44:47], v[226:229], v[186:189], v[44:47]
	v_mfma_f32_16x16x32_bf16 v[36:39], v[214:217], v[190:193], v[36:39]
	v_mfma_f32_16x16x32_bf16 v[36:39], v[218:221], v[194:197], v[36:39]
	v_mfma_f32_16x16x32_bf16 v[28:31], v[222:225], v[190:193], v[28:31]
	v_mfma_f32_16x16x32_bf16 v[28:31], v[226:229], v[194:197], v[28:31]
	v_mfma_f32_16x16x32_bf16 v[20:23], v[214:217], v[198:201], v[20:23]
	v_mfma_f32_16x16x32_bf16 v[20:23], v[218:221], v[202:205], v[20:23]
	v_mfma_f32_16x16x32_bf16 v[12:15], v[222:225], v[198:201], v[12:15]
	v_mfma_f32_16x16x32_bf16 v[12:15], v[226:229], v[202:205], v[12:15]
	v_mfma_f32_16x16x32_bf16 v[4:7], v[214:217], v[206:209], v[4:7]
	v_mfma_f32_16x16x32_bf16 v[4:7], v[218:221], v[210:213], v[4:7]
	v_mfma_f32_16x16x32_bf16 v[0:3], v[222:225], v[206:209], v[0:3]
	v_mfma_f32_16x16x32_bf16 v[0:3], v[226:229], v[210:213], v[0:3]
	s_add_i32 s83, s83, 2
	s_add_u32 s63, s63, 0x100
	s_addc_u32 s82, s82, 0
	s_cmp_gt_u32 s83, 13
	s_mov_b64 s[42:43], s[44:45]
	s_cbranch_scc0 .Lrot_301
	s_barrier
	v_lshl_or_b32 v162, s81, 8, v141
	v_lshl_add_u32 v157, s80, 8, v137
	v_ashrrev_i32_e32 v163, 31, v162
	v_mov_b64_e32 v[160:161], s[12:13]
	v_mad_i64_i32 v[164:165], s[42:43], v157, s78, v[160:161]
	v_lshlrev_b64 v[162:163], 1, v[162:163]
	v_lshl_add_u64 v[164:165], v[164:165], 0, v[162:163]
	s_waitcnt vmcnt(0)
	v_pk_mul_f32 v[126:127], v[158:159], v[126:127] op_sel_hi:[0,1]
	v_pk_mul_f32 v[124:125], v[158:159], v[124:125] op_sel_hi:[0,1]
	v_pk_mul_f32 v[166:167], v[158:159], v[122:123] op_sel_hi:[0,1]
	v_pk_mul_f32 v[122:123], v[158:159], v[120:121] op_sel_hi:[0,1]
	v_cvt_pk_bf16_f32 v120, v124, v125
	v_cvt_pk_bf16_f32 v121, v126, v127
	v_cvt_pk_bf16_f32 v122, v122, v123
	v_cvt_pk_bf16_f32 v123, v166, v167
	global_store_dwordx4 v[164:165], v[120:123], off
	v_pk_mul_f32 v[116:117], v[158:159], v[116:117] op_sel_hi:[0,1]
	v_pk_mul_f32 v[118:119], v[158:159], v[118:119] op_sel_hi:[0,1]
	v_pk_mul_f32 v[120:121], v[158:159], v[110:111] op_sel_hi:[0,1]
	v_pk_mul_f32 v[110:111], v[158:159], v[108:109] op_sel_hi:[0,1]
	v_cvt_pk_bf16_f32 v108, v116, v117
	v_cvt_pk_bf16_f32 v109, v118, v119
	v_cvt_pk_bf16_f32 v110, v110, v111
	v_cvt_pk_bf16_f32 v111, v120, v121
	global_store_dwordx4 v[164:165], v[108:111], off offset:256
	v_pk_mul_f32 v[112:113], v[156:157], v[112:113] op_sel_hi:[0,1]
	v_pk_mul_f32 v[100:101], v[156:157], v[100:101] op_sel_hi:[0,1]
	v_or_b32_e32 v108, 16, v157
	v_mad_i64_i32 v[108:109], s[42:43], v108, s78, v[160:161]
	v_lshl_add_u64 v[108:109], v[108:109], 0, v[162:163]
	v_pk_mul_f32 v[110:111], v[156:157], v[114:115] op_sel_hi:[0,1]
	v_pk_mul_f32 v[114:115], v[156:157], v[106:107] op_sel_hi:[0,1]
	v_pk_mul_f32 v[106:107], v[156:157], v[104:105] op_sel_hi:[0,1]
	v_cvt_pk_bf16_f32 v104, v112, v113
	v_cvt_pk_bf16_f32 v105, v110, v111
	v_cvt_pk_bf16_f32 v106, v106, v107
	v_cvt_pk_bf16_f32 v107, v114, v115
	global_store_dwordx4 v[108:109], v[104:107], off
	v_pk_mul_f32 v[102:103], v[156:157], v[102:103] op_sel_hi:[0,1]
	v_pk_mul_f32 v[96:97], v[154:155], v[96:97] op_sel_hi:[0,1]
	v_pk_mul_f32 v[104:105], v[156:157], v[94:95] op_sel_hi:[0,1]
	v_pk_mul_f32 v[94:95], v[156:157], v[92:93] op_sel_hi:[0,1]
	v_cvt_pk_bf16_f32 v92, v100, v101
	v_cvt_pk_bf16_f32 v93, v102, v103
	v_cvt_pk_bf16_f32 v94, v94, v95
	v_cvt_pk_bf16_f32 v95, v104, v105
	global_store_dwordx4 v[108:109], v[92:95], off offset:256
	v_pk_mul_f32 v[84:85], v[154:155], v[84:85] op_sel_hi:[0,1]
	v_pk_mul_f32 v[86:87], v[154:155], v[86:87] op_sel_hi:[0,1]
	v_or_b32_e32 v92, 32, v157
	v_mad_i64_i32 v[92:93], s[42:43], v92, s78, v[160:161]
	v_lshl_add_u64 v[92:93], v[92:93], 0, v[162:163]
	v_pk_mul_f32 v[94:95], v[154:155], v[98:99] op_sel_hi:[0,1]
	v_pk_mul_f32 v[98:99], v[154:155], v[90:91] op_sel_hi:[0,1]
	v_pk_mul_f32 v[90:91], v[154:155], v[88:89] op_sel_hi:[0,1]
	v_cvt_pk_bf16_f32 v88, v96, v97
	v_cvt_pk_bf16_f32 v89, v94, v95
	v_cvt_pk_bf16_f32 v90, v90, v91
	v_cvt_pk_bf16_f32 v91, v98, v99
	global_store_dwordx4 v[92:93], v[88:91], off
	v_pk_mul_f32 v[80:81], v[152:153], v[80:81] op_sel_hi:[0,1]
	v_pk_mul_f32 v[68:69], v[152:153], v[68:69] op_sel_hi:[0,1]
	v_pk_mul_f32 v[88:89], v[154:155], v[78:79] op_sel_hi:[0,1]
	v_pk_mul_f32 v[78:79], v[154:155], v[76:77] op_sel_hi:[0,1]
	v_cvt_pk_bf16_f32 v76, v84, v85
	v_cvt_pk_bf16_f32 v77, v86, v87
	v_cvt_pk_bf16_f32 v78, v78, v79
	v_cvt_pk_bf16_f32 v79, v88, v89
	global_store_dwordx4 v[92:93], v[76:79], off offset:256
	v_pk_mul_f32 v[70:71], v[152:153], v[70:71] op_sel_hi:[0,1]
	v_pk_mul_f32 v[62:63], v[150:151], v[62:63] op_sel_hi:[0,1]
	v_or_b32_e32 v76, 48, v157
	v_mad_i64_i32 v[76:77], s[42:43], v76, s78, v[160:161]
	v_lshl_add_u64 v[76:77], v[76:77], 0, v[162:163]
	v_pk_mul_f32 v[78:79], v[152:153], v[82:83] op_sel_hi:[0,1]
	v_pk_mul_f32 v[82:83], v[152:153], v[74:75] op_sel_hi:[0,1]
	v_pk_mul_f32 v[74:75], v[152:153], v[72:73] op_sel_hi:[0,1]
	v_cvt_pk_bf16_f32 v72, v80, v81
	v_cvt_pk_bf16_f32 v73, v78, v79
	v_cvt_pk_bf16_f32 v74, v74, v75
	v_cvt_pk_bf16_f32 v75, v82, v83
	global_store_dwordx4 v[76:77], v[72:75], off
	v_pk_mul_f32 v[60:61], v[150:151], v[60:61] op_sel_hi:[0,1]
	v_pk_mul_f32 v[52:53], v[150:151], v[52:53] op_sel_hi:[0,1]
	v_pk_mul_f32 v[72:73], v[152:153], v[66:67] op_sel_hi:[0,1]
	v_pk_mul_f32 v[66:67], v[152:153], v[64:65] op_sel_hi:[0,1]
	v_cvt_pk_bf16_f32 v64, v68, v69
	v_cvt_pk_bf16_f32 v65, v70, v71
	v_cvt_pk_bf16_f32 v66, v66, v67
	v_cvt_pk_bf16_f32 v67, v72, v73
	global_store_dwordx4 v[76:77], v[64:67], off offset:256
	v_pk_mul_f32 v[54:55], v[150:151], v[54:55] op_sel_hi:[0,1]
	v_pk_mul_f32 v[48:49], v[140:141], v[48:49] op_sel_hi:[0,1]
	v_add_u32_e32 v64, 0x80, v157
	v_mad_i64_i32 v[64:65], s[42:43], v64, s78, v[160:161]
	v_lshl_add_u64 v[64:65], v[64:65], 0, v[162:163]
	v_pk_mul_f32 v[66:67], v[150:151], v[58:59] op_sel_hi:[0,1]
	v_pk_mul_f32 v[58:59], v[150:151], v[56:57] op_sel_hi:[0,1]
	v_cvt_pk_bf16_f32 v56, v60, v61
	v_cvt_pk_bf16_f32 v57, v62, v63
	v_cvt_pk_bf16_f32 v58, v58, v59
	v_cvt_pk_bf16_f32 v59, v66, v67
	global_store_dwordx4 v[64:65], v[56:59], off
	v_pk_mul_f32 v[36:37], v[140:141], v[36:37] op_sel_hi:[0,1]
	v_pk_mul_f32 v[38:39], v[140:141], v[38:39] op_sel_hi:[0,1]
	v_pk_mul_f32 v[56:57], v[150:151], v[46:47] op_sel_hi:[0,1]
	v_pk_mul_f32 v[46:47], v[150:151], v[44:45] op_sel_hi:[0,1]
	v_cvt_pk_bf16_f32 v44, v52, v53
	v_cvt_pk_bf16_f32 v45, v54, v55
	v_cvt_pk_bf16_f32 v46, v46, v47
	v_cvt_pk_bf16_f32 v47, v56, v57
	global_store_dwordx4 v[64:65], v[44:47], off offset:256
	v_pk_mul_f32 v[32:33], v[138:139], v[32:33] op_sel_hi:[0,1]
	v_pk_mul_f32 v[20:21], v[138:139], v[20:21] op_sel_hi:[0,1]
	v_add_u32_e32 v44, 0x90, v157
	v_mad_i64_i32 v[44:45], s[42:43], v44, s78, v[160:161]
	v_lshl_add_u64 v[44:45], v[44:45], 0, v[162:163]
	v_pk_mul_f32 v[46:47], v[140:141], v[50:51] op_sel_hi:[0,1]
	v_pk_mul_f32 v[50:51], v[140:141], v[42:43] op_sel_hi:[0,1]
	v_pk_mul_f32 v[42:43], v[140:141], v[40:41] op_sel_hi:[0,1]
	v_cvt_pk_bf16_f32 v40, v48, v49
	v_cvt_pk_bf16_f32 v41, v46, v47
	v_cvt_pk_bf16_f32 v42, v42, v43
	v_cvt_pk_bf16_f32 v43, v50, v51
	global_store_dwordx4 v[44:45], v[40:43], off
	v_pk_mul_f32 v[22:23], v[138:139], v[22:23] op_sel_hi:[0,1]
	v_pk_mul_f32 v[16:17], v[136:137], v[16:17] op_sel_hi:[0,1]
	v_pk_mul_f32 v[40:41], v[140:141], v[30:31] op_sel_hi:[0,1]
	v_pk_mul_f32 v[30:31], v[140:141], v[28:29] op_sel_hi:[0,1]
	v_cvt_pk_bf16_f32 v28, v36, v37
	v_cvt_pk_bf16_f32 v29, v38, v39
	v_cvt_pk_bf16_f32 v30, v30, v31
	v_cvt_pk_bf16_f32 v31, v40, v41
	global_store_dwordx4 v[44:45], v[28:31], off offset:256
	s_and_b64 vcc, s[8:9], exec
	v_pk_mul_f32 v[6:7], v[136:137], v[6:7] op_sel_hi:[0,1]
	v_add_u32_e32 v28, 0xa0, v157
	v_mad_i64_i32 v[28:29], s[42:43], v28, s78, v[160:161]
	v_lshl_add_u64 v[28:29], v[28:29], 0, v[162:163]
	v_pk_mul_f32 v[30:31], v[138:139], v[34:35] op_sel_hi:[0,1]
	v_pk_mul_f32 v[34:35], v[138:139], v[26:27] op_sel_hi:[0,1]
	v_pk_mul_f32 v[26:27], v[138:139], v[24:25] op_sel_hi:[0,1]
	v_cvt_pk_bf16_f32 v24, v32, v33
	v_cvt_pk_bf16_f32 v25, v30, v31
	v_cvt_pk_bf16_f32 v26, v26, v27
	v_cvt_pk_bf16_f32 v27, v34, v35
	global_store_dwordx4 v[28:29], v[24:27], off
	v_pk_mul_f32 v[4:5], v[136:137], v[4:5] op_sel_hi:[0,1]
	s_nop 0
	v_pk_mul_f32 v[24:25], v[138:139], v[14:15] op_sel_hi:[0,1]
	v_pk_mul_f32 v[14:15], v[138:139], v[12:13] op_sel_hi:[0,1]
	v_cvt_pk_bf16_f32 v12, v20, v21
	v_cvt_pk_bf16_f32 v13, v22, v23
	v_cvt_pk_bf16_f32 v14, v14, v15
	v_cvt_pk_bf16_f32 v15, v24, v25
	global_store_dwordx4 v[28:29], v[12:15], off offset:256
	s_nop 1
	v_add_u32_e32 v12, 0xb0, v157
	v_mad_i64_i32 v[12:13], s[42:43], v12, s78, v[160:161]
	v_lshl_add_u64 v[12:13], v[12:13], 0, v[162:163]
	v_pk_mul_f32 v[14:15], v[136:137], v[18:19] op_sel_hi:[0,1]
	v_pk_mul_f32 v[18:19], v[136:137], v[10:11] op_sel_hi:[0,1]
	v_pk_mul_f32 v[10:11], v[136:137], v[8:9] op_sel_hi:[0,1]
	v_cvt_pk_bf16_f32 v8, v16, v17
	v_cvt_pk_bf16_f32 v9, v14, v15
	v_cvt_pk_bf16_f32 v10, v10, v11
	v_cvt_pk_bf16_f32 v11, v18, v19
	global_store_dwordx4 v[12:13], v[8:11], off
	s_mov_b64 s[42:43], -1
	s_nop 0
	v_pk_mul_f32 v[8:9], v[136:137], v[2:3] op_sel_hi:[0,1]
	v_pk_mul_f32 v[2:3], v[136:137], v[0:1] op_sel_hi:[0,1]
	v_cvt_pk_bf16_f32 v0, v4, v5
	v_cvt_pk_bf16_f32 v1, v6, v7
	v_cvt_pk_bf16_f32 v2, v2, v3
	v_cvt_pk_bf16_f32 v3, v8, v9
	global_store_dwordx4 v[12:13], v[0:3], off offset:256
	s_cbranch_vccz .LBB0_295
	s_nop 0
	v_lshl_add_u32 v0, s79, 8, v137
	v_ashrrev_i32_e32 v1, 31, v0
	v_lshl_add_u64 v[0:1], v[0:1], 2, s[72:73]
	global_load_dword v158, v[0:1], off
	global_load_dword v156, v[0:1], off offset:64
	global_load_dword v154, v[0:1], off offset:128
	global_load_dword v152, v[0:1], off offset:192
	global_load_dword v150, v[0:1], off offset:512
	global_load_dword v140, v[0:1], off offset:576
	global_load_dword v138, v[0:1], off offset:640
	global_load_dword v136, v[0:1], off offset:704
	s_mov_b64 s[42:43], 0
	s_branch .LBB0_295

.LBB0_324:
	s_ashr_i32 s41, s40, 31
	s_lshl_b64 s[44:45], s[40:41], 18
	s_add_u32 s44, s22, s44
	s_addc_u32 s45, s23, s45
	s_and_b64 s[50:51], s[8:9], exec
	s_cselect_b32 s41, s45, s49
	s_cselect_b32 s62, s44, s48
	s_add_u32 s63, s48, 0x100
	v_mov_b32_e32 v0, 0
	s_addc_u32 s90, s49, 0
	s_mov_b32 s91, -2
	v_mov_b32_e32 v1, v0
	v_mov_b32_e32 v2, v0
	v_mov_b32_e32 v3, v0
	v_mov_b32_e32 v4, v0
	v_mov_b32_e32 v5, v0
	v_mov_b32_e32 v6, v0
	v_mov_b32_e32 v7, v0
	v_mov_b32_e32 v12, v0
	v_mov_b32_e32 v13, v0
	v_mov_b32_e32 v14, v0
	v_mov_b32_e32 v15, v0
	v_mov_b32_e32 v20, v0
	v_mov_b32_e32 v21, v0
	v_mov_b32_e32 v22, v0
	v_mov_b32_e32 v23, v0
	v_mov_b32_e32 v28, v0
	v_mov_b32_e32 v29, v0
	v_mov_b32_e32 v30, v0
	v_mov_b32_e32 v31, v0
	v_mov_b32_e32 v36, v0
	v_mov_b32_e32 v37, v0
	v_mov_b32_e32 v38, v0
	v_mov_b32_e32 v39, v0
	v_mov_b32_e32 v44, v0
	v_mov_b32_e32 v45, v0
	v_mov_b32_e32 v46, v0
	v_mov_b32_e32 v47, v0
	v_mov_b32_e32 v52, v0
	v_mov_b32_e32 v53, v0
	v_mov_b32_e32 v54, v0
	v_mov_b32_e32 v55, v0
	v_mov_b32_e32 v8, v0
	v_mov_b32_e32 v9, v0
	v_mov_b32_e32 v10, v0
	v_mov_b32_e32 v11, v0
	v_mov_b32_e32 v16, v0
	v_mov_b32_e32 v17, v0
	v_mov_b32_e32 v18, v0
	v_mov_b32_e32 v19, v0
	v_mov_b32_e32 v24, v0
	v_mov_b32_e32 v25, v0
	v_mov_b32_e32 v26, v0
	v_mov_b32_e32 v27, v0
	v_mov_b32_e32 v32, v0
	v_mov_b32_e32 v33, v0
	v_mov_b32_e32 v34, v0
	v_mov_b32_e32 v35, v0
	v_mov_b32_e32 v40, v0
	v_mov_b32_e32 v41, v0
	v_mov_b32_e32 v42, v0
	v_mov_b32_e32 v43, v0
	v_mov_b32_e32 v48, v0
	v_mov_b32_e32 v49, v0
	v_mov_b32_e32 v50, v0
	v_mov_b32_e32 v51, v0
	v_mov_b32_e32 v56, v0
	v_mov_b32_e32 v57, v0
	v_mov_b32_e32 v58, v0
	v_mov_b32_e32 v59, v0
	v_mov_b32_e32 v60, v0
	v_mov_b32_e32 v61, v0
	v_mov_b32_e32 v62, v0
	v_mov_b32_e32 v63, v0
	v_mov_b32_e32 v64, v0
	v_mov_b32_e32 v65, v0
	v_mov_b32_e32 v66, v0
	v_mov_b32_e32 v67, v0
	v_mov_b32_e32 v68, v0
	v_mov_b32_e32 v69, v0
	v_mov_b32_e32 v70, v0
	v_mov_b32_e32 v71, v0
	v_mov_b32_e32 v80, v0
	v_mov_b32_e32 v81, v0
	v_mov_b32_e32 v82, v0
	v_mov_b32_e32 v83, v0
	v_mov_b32_e32 v84, v0
	v_mov_b32_e32 v85, v0
	v_mov_b32_e32 v86, v0
	v_mov_b32_e32 v87, v0
	v_mov_b32_e32 v96, v0
	v_mov_b32_e32 v97, v0
	v_mov_b32_e32 v98, v0
	v_mov_b32_e32 v99, v0
	v_mov_b32_e32 v100, v0
	v_mov_b32_e32 v101, v0
	v_mov_b32_e32 v102, v0
	v_mov_b32_e32 v103, v0
	v_mov_b32_e32 v112, v0
	v_mov_b32_e32 v113, v0
	v_mov_b32_e32 v114, v0
	v_mov_b32_e32 v115, v0
	v_mov_b32_e32 v116, v0
	v_mov_b32_e32 v117, v0
	v_mov_b32_e32 v118, v0
	v_mov_b32_e32 v119, v0
	v_mov_b32_e32 v72, v0
	v_mov_b32_e32 v73, v0
	v_mov_b32_e32 v74, v0
	v_mov_b32_e32 v75, v0
	v_mov_b32_e32 v76, v0
	v_mov_b32_e32 v77, v0
	v_mov_b32_e32 v78, v0
	v_mov_b32_e32 v79, v0
	v_mov_b32_e32 v88, v0
	v_mov_b32_e32 v89, v0
	v_mov_b32_e32 v90, v0
	v_mov_b32_e32 v91, v0
	v_mov_b32_e32 v92, v0
	v_mov_b32_e32 v93, v0
	v_mov_b32_e32 v94, v0
	v_mov_b32_e32 v95, v0
	v_mov_b32_e32 v104, v0
	v_mov_b32_e32 v105, v0
	v_mov_b32_e32 v106, v0
	v_mov_b32_e32 v107, v0
	v_mov_b32_e32 v108, v0
	v_mov_b32_e32 v109, v0
	v_mov_b32_e32 v110, v0
	v_mov_b32_e32 v111, v0
	v_mov_b32_e32 v120, v0
	v_mov_b32_e32 v121, v0
	v_mov_b32_e32 v122, v0
	v_mov_b32_e32 v123, v0
	v_mov_b32_e32 v124, v0
	v_mov_b32_e32 v125, v0
	v_mov_b32_e32 v126, v0
	v_mov_b32_e32 v127, v0
	s_branch .LBB0_325

.LBB0_325:
	ds_read_b128 v[160:163], v151
	ds_read_b128 v[164:167], v151 offset:1024
	ds_read_b128 v[168:171], v151 offset:2048
	ds_read_b128 v[176:179], v151 offset:3072
	s_add_u32 s48, s46, 0x100
	s_addc_u32 s49, s47, 0
	s_cmp_eq_u32 s91, 4
	s_cselect_b32 s53, s43, s49
	s_cselect_b32 s52, s42, s48
	s_cselect_b32 s51, s41, s90
	s_cselect_b32 s50, s62, s63
	v_lshl_add_u64 v[214:215], s[46:47], 0, v[142:143]
	s_add_i32 m0, s55, 0xc000
	ds_read_b128 v[180:183], v153
	ds_read_b128 v[186:189], v153 offset:1024
	ds_read_b128 v[190:193], v153 offset:2048
	ds_read_b128 v[194:197], v153 offset:3072
	ds_read_b128 v[198:201], v153 offset:4096
	ds_read_b128 v[202:205], v153 offset:5120
	ds_read_b128 v[206:209], v153 offset:6144
	ds_read_b128 v[210:213], v153 offset:7168
	global_load_lds_dwordx4 v[214:215], off
	v_lshl_add_u64 v[214:215], s[46:47], 0, v[144:145]
	s_add_i32 m0, s55, 0xe000
	s_nop 0
	global_load_lds_dwordx4 v[214:215], off
	s_waitcnt lgkmcnt(8)
	s_barrier
	s_waitcnt lgkmcnt(0)
	s_waitcnt lgkmcnt(0)
	v_mfma_f32_16x16x32_bf16 v[124:127], v[160:163], v[180:183], v[124:127]
	v_mfma_f32_16x16x32_bf16 v[124:127], v[164:167], v[186:189], v[124:127]
	v_mfma_f32_16x16x32_bf16 v[120:123], v[168:171], v[180:183], v[120:123]
	v_mfma_f32_16x16x32_bf16 v[120:123], v[176:179], v[186:189], v[120:123]
	v_mfma_f32_16x16x32_bf16 v[108:111], v[160:163], v[190:193], v[108:111]
	v_mfma_f32_16x16x32_bf16 v[108:111], v[164:167], v[194:197], v[108:111]
	v_mfma_f32_16x16x32_bf16 v[104:107], v[168:171], v[190:193], v[104:107]
	v_mfma_f32_16x16x32_bf16 v[104:107], v[176:179], v[194:197], v[104:107]
	v_mfma_f32_16x16x32_bf16 v[92:95], v[160:163], v[198:201], v[92:95]
	v_mfma_f32_16x16x32_bf16 v[92:95], v[164:167], v[202:205], v[92:95]
	v_mfma_f32_16x16x32_bf16 v[88:91], v[168:171], v[198:201], v[88:91]
	v_mfma_f32_16x16x32_bf16 v[88:91], v[176:179], v[202:205], v[88:91]
	v_mfma_f32_16x16x32_bf16 v[76:79], v[160:163], v[206:209], v[76:79]
	v_mfma_f32_16x16x32_bf16 v[76:79], v[164:167], v[210:213], v[76:79]
	v_mfma_f32_16x16x32_bf16 v[72:75], v[168:171], v[206:209], v[72:75]
	v_mfma_f32_16x16x32_bf16 v[72:75], v[176:179], v[210:213], v[72:75]
	s_barrier
	s_add_i32 s46, s81, s54
	v_lshl_add_u64 v[230:231], s[50:51], 0, v[130:131]
	s_mov_b32 m0, s46
	ds_read_b128 v[214:217], v155
	ds_read_b128 v[218:221], v155 offset:1024
	ds_read_b128 v[222:225], v155 offset:2048
	ds_read_b128 v[226:229], v155 offset:3072
	global_load_lds_dwordx4 v[230:231], off
	v_lshl_add_u64 v[232:233], s[50:51], 0, v[134:135]
	s_add_i32 m0, s46, 0x2000
	s_nop 0
	global_load_lds_dwordx4 v[232:233], off
	s_barrier
	s_waitcnt lgkmcnt(0)
	s_waitcnt lgkmcnt(0)
	v_mfma_f32_16x16x32_bf16 v[116:119], v[214:217], v[180:183], v[116:119]
	v_mfma_f32_16x16x32_bf16 v[116:119], v[218:221], v[186:189], v[116:119]
	v_mfma_f32_16x16x32_bf16 v[112:115], v[222:225], v[180:183], v[112:115]
	v_mfma_f32_16x16x32_bf16 v[112:115], v[226:229], v[186:189], v[112:115]
	v_mfma_f32_16x16x32_bf16 v[100:103], v[214:217], v[190:193], v[100:103]
	v_mfma_f32_16x16x32_bf16 v[100:103], v[218:221], v[194:197], v[100:103]
	v_mfma_f32_16x16x32_bf16 v[96:99], v[222:225], v[190:193], v[96:99]
	v_mfma_f32_16x16x32_bf16 v[96:99], v[226:229], v[194:197], v[96:99]
	v_mfma_f32_16x16x32_bf16 v[84:87], v[214:217], v[198:201], v[84:87]
	v_mfma_f32_16x16x32_bf16 v[84:87], v[218:221], v[202:205], v[84:87]
	v_mfma_f32_16x16x32_bf16 v[80:83], v[222:225], v[198:201], v[80:83]
	v_mfma_f32_16x16x32_bf16 v[80:83], v[226:229], v[202:205], v[80:83]
	v_mfma_f32_16x16x32_bf16 v[68:71], v[214:217], v[206:209], v[68:71]
	v_mfma_f32_16x16x32_bf16 v[68:71], v[218:221], v[210:213], v[68:71]
	v_mfma_f32_16x16x32_bf16 v[64:67], v[222:225], v[206:209], v[64:67]
	v_mfma_f32_16x16x32_bf16 v[64:67], v[226:229], v[210:213], v[64:67]
	s_mov_b32 m0, s55
	v_lshl_add_u64 v[234:235], s[52:53], 0, v[128:129]
	s_barrier
	ds_read_b128 v[180:183], v153 offset:16384
	ds_read_b128 v[186:189], v153 offset:17408
	ds_read_b128 v[190:193], v153 offset:18432
	ds_read_b128 v[194:197], v153 offset:19456
	ds_read_b128 v[198:201], v153 offset:20480
	ds_read_b128 v[202:205], v153 offset:21504
	ds_read_b128 v[206:209], v153 offset:22528
	ds_read_b128 v[210:213], v153 offset:23552
	global_load_lds_dwordx4 v[234:235], off
	v_lshl_add_u64 v[236:237], s[52:53], 0, v[132:133]
	s_mov_b32 m0, s61
	s_nop 0
	global_load_lds_dwordx4 v[236:237], off
	s_barrier
	s_waitcnt lgkmcnt(0)
	s_waitcnt lgkmcnt(0)
	v_mfma_f32_16x16x32_bf16 v[60:63], v[160:163], v[180:183], v[60:63]
	v_mfma_f32_16x16x32_bf16 v[60:63], v[164:167], v[186:189], v[60:63]
	v_mfma_f32_16x16x32_bf16 v[56:59], v[168:171], v[180:183], v[56:59]
	v_mfma_f32_16x16x32_bf16 v[56:59], v[176:179], v[186:189], v[56:59]
	v_mfma_f32_16x16x32_bf16 v[48:51], v[160:163], v[190:193], v[48:51]
	v_mfma_f32_16x16x32_bf16 v[48:51], v[164:167], v[194:197], v[48:51]
	v_mfma_f32_16x16x32_bf16 v[40:43], v[168:171], v[190:193], v[40:43]
	v_mfma_f32_16x16x32_bf16 v[40:43], v[176:179], v[194:197], v[40:43]
	v_mfma_f32_16x16x32_bf16 v[32:35], v[160:163], v[198:201], v[32:35]
	v_mfma_f32_16x16x32_bf16 v[32:35], v[164:167], v[202:205], v[32:35]
	v_mfma_f32_16x16x32_bf16 v[24:27], v[168:171], v[198:201], v[24:27]
	v_mfma_f32_16x16x32_bf16 v[24:27], v[176:179], v[202:205], v[24:27]
	v_mfma_f32_16x16x32_bf16 v[16:19], v[160:163], v[206:209], v[16:19]
	v_mfma_f32_16x16x32_bf16 v[16:19], v[164:167], v[210:213], v[16:19]
	v_mfma_f32_16x16x32_bf16 v[8:11], v[168:171], v[206:209], v[8:11]
	v_mfma_f32_16x16x32_bf16 v[8:11], v[176:179], v[210:213], v[8:11]
	s_barrier
	s_add_u32 s46, s50, 0x20000
	s_addc_u32 s47, s51, 0
	s_add_i32 s92, s82, s54
	v_lshl_add_u64 v[160:161], s[46:47], 0, v[130:131]
	s_mov_b32 m0, s92
	s_nop 0
	global_load_lds_dwordx4 v[160:161], off
	v_lshl_add_u64 v[160:161], s[46:47], 0, v[134:135]
	s_add_i32 m0, s92, 0x2000
	s_nop 0
	global_load_lds_dwordx4 v[160:161], off
	s_waitcnt vmcnt(6)
	s_barrier
	v_mfma_f32_16x16x32_bf16 v[52:55], v[214:217], v[180:183], v[52:55]
	v_mfma_f32_16x16x32_bf16 v[52:55], v[218:221], v[186:189], v[52:55]
	v_mfma_f32_16x16x32_bf16 v[44:47], v[222:225], v[180:183], v[44:47]
	v_mfma_f32_16x16x32_bf16 v[44:47], v[226:229], v[186:189], v[44:47]
	v_mfma_f32_16x16x32_bf16 v[36:39], v[214:217], v[190:193], v[36:39]
	v_mfma_f32_16x16x32_bf16 v[36:39], v[218:221], v[194:197], v[36:39]
	v_mfma_f32_16x16x32_bf16 v[28:31], v[222:225], v[190:193], v[28:31]
	v_mfma_f32_16x16x32_bf16 v[28:31], v[226:229], v[194:197], v[28:31]
	v_mfma_f32_16x16x32_bf16 v[20:23], v[214:217], v[198:201], v[20:23]
	v_mfma_f32_16x16x32_bf16 v[20:23], v[218:221], v[202:205], v[20:23]
	v_mfma_f32_16x16x32_bf16 v[12:15], v[222:225], v[198:201], v[12:15]
	v_mfma_f32_16x16x32_bf16 v[12:15], v[226:229], v[202:205], v[12:15]
	v_mfma_f32_16x16x32_bf16 v[4:7], v[214:217], v[206:209], v[4:7]
	v_mfma_f32_16x16x32_bf16 v[4:7], v[218:221], v[210:213], v[4:7]
	v_mfma_f32_16x16x32_bf16 v[0:3], v[222:225], v[206:209], v[0:3]
	v_mfma_f32_16x16x32_bf16 v[0:3], v[226:229], v[210:213], v[0:3]
	s_add_i32 s92, 0, 0x18000
	v_add_u32_e32 v157, s92, v139
	s_barrier
	ds_read_b128 v[160:163], v157
	ds_read_b128 v[164:167], v157 offset:1024
	ds_read_b128 v[168:171], v157 offset:2048
	ds_read_b128 v[176:179], v157 offset:3072
	s_add_u32 s46, s52, 0x170000
	s_addc_u32 s47, s53, 0
	s_mov_b32 m0, s74
	v_lshl_add_u64 v[214:215], s[46:47], 0, v[128:129]
	ds_read_b128 v[180:183], v153 offset:32768
	ds_read_b128 v[186:189], v153 offset:33792
	ds_read_b128 v[190:193], v153 offset:34816
	ds_read_b128 v[194:197], v153 offset:35840
	ds_read_b128 v[198:201], v153 offset:36864
	ds_read_b128 v[202:205], v153 offset:37888
	ds_read_b128 v[206:209], v153 offset:38912
	ds_read_b128 v[210:213], v153 offset:39936
	global_load_lds_dwordx4 v[214:215], off
	v_lshl_add_u64 v[214:215], s[46:47], 0, v[132:133]
	s_mov_b32 m0, s75
	s_nop 0
	global_load_lds_dwordx4 v[214:215], off
	s_waitcnt lgkmcnt(8)
	s_barrier
	s_waitcnt lgkmcnt(0)
	s_waitcnt lgkmcnt(0)
	v_mfma_f32_16x16x32_bf16 v[124:127], v[160:163], v[180:183], v[124:127]
	v_mfma_f32_16x16x32_bf16 v[124:127], v[164:167], v[186:189], v[124:127]
	v_mfma_f32_16x16x32_bf16 v[120:123], v[168:171], v[180:183], v[120:123]
	v_mfma_f32_16x16x32_bf16 v[120:123], v[176:179], v[186:189], v[120:123]
	v_mfma_f32_16x16x32_bf16 v[108:111], v[160:163], v[190:193], v[108:111]
	v_mfma_f32_16x16x32_bf16 v[108:111], v[164:167], v[194:197], v[108:111]
	v_mfma_f32_16x16x32_bf16 v[104:107], v[168:171], v[190:193], v[104:107]
	v_mfma_f32_16x16x32_bf16 v[104:107], v[176:179], v[194:197], v[104:107]
	v_mfma_f32_16x16x32_bf16 v[92:95], v[160:163], v[198:201], v[92:95]
	v_mfma_f32_16x16x32_bf16 v[92:95], v[164:167], v[202:205], v[92:95]
	v_mfma_f32_16x16x32_bf16 v[88:91], v[168:171], v[198:201], v[88:91]
	v_mfma_f32_16x16x32_bf16 v[88:91], v[176:179], v[202:205], v[88:91]
	v_mfma_f32_16x16x32_bf16 v[76:79], v[160:163], v[206:209], v[76:79]
	v_mfma_f32_16x16x32_bf16 v[76:79], v[164:167], v[210:213], v[76:79]
	v_mfma_f32_16x16x32_bf16 v[72:75], v[168:171], v[206:209], v[72:75]
	v_mfma_f32_16x16x32_bf16 v[72:75], v[176:179], v[210:213], v[72:75]
	s_barrier
	s_add_i32 s52, 0, 0x1c000
	s_add_i32 s46, s92, s54
	v_add_u32_e32 v157, s52, v139
	v_lshl_add_u64 v[230:231], v[230:231], 0, s[10:11]
	s_mov_b32 m0, s46
	ds_read_b128 v[214:217], v157
	ds_read_b128 v[218:221], v157 offset:1024
	ds_read_b128 v[222:225], v157 offset:2048
	ds_read_b128 v[226:229], v157 offset:3072
	global_load_lds_dwordx4 v[230:231], off
	v_lshl_add_u64 v[230:231], v[232:233], 0, s[10:11]
	s_add_i32 m0, s46, 0x2000
	s_nop 0
	global_load_lds_dwordx4 v[230:231], off
	s_barrier
	s_waitcnt lgkmcnt(0)
	s_waitcnt lgkmcnt(0)
	v_mfma_f32_16x16x32_bf16 v[116:119], v[214:217], v[180:183], v[116:119]
	v_mfma_f32_16x16x32_bf16 v[116:119], v[218:221], v[186:189], v[116:119]
	v_mfma_f32_16x16x32_bf16 v[112:115], v[222:225], v[180:183], v[112:115]
	v_mfma_f32_16x16x32_bf16 v[112:115], v[226:229], v[186:189], v[112:115]
	v_mfma_f32_16x16x32_bf16 v[100:103], v[214:217], v[190:193], v[100:103]
	v_mfma_f32_16x16x32_bf16 v[100:103], v[218:221], v[194:197], v[100:103]
	v_mfma_f32_16x16x32_bf16 v[96:99], v[222:225], v[190:193], v[96:99]
	v_mfma_f32_16x16x32_bf16 v[96:99], v[226:229], v[194:197], v[96:99]
	v_mfma_f32_16x16x32_bf16 v[84:87], v[214:217], v[198:201], v[84:87]
	v_mfma_f32_16x16x32_bf16 v[84:87], v[218:221], v[202:205], v[84:87]
	v_mfma_f32_16x16x32_bf16 v[80:83], v[222:225], v[198:201], v[80:83]
	v_mfma_f32_16x16x32_bf16 v[80:83], v[226:229], v[202:205], v[80:83]
	v_mfma_f32_16x16x32_bf16 v[68:71], v[214:217], v[206:209], v[68:71]
	v_mfma_f32_16x16x32_bf16 v[68:71], v[218:221], v[210:213], v[68:71]
	v_mfma_f32_16x16x32_bf16 v[64:67], v[222:225], v[206:209], v[64:67]
	v_mfma_f32_16x16x32_bf16 v[64:67], v[226:229], v[210:213], v[64:67]
	s_mov_b32 m0, s77
	v_lshl_add_u64 v[230:231], v[234:235], 0, s[10:11]
	s_barrier
	ds_read_b128 v[180:183], v153 offset:49152
	ds_read_b128 v[186:189], v153 offset:50176
	ds_read_b128 v[190:193], v153 offset:51200
	ds_read_b128 v[194:197], v153 offset:52224
	ds_read_b128 v[198:201], v153 offset:53248
	ds_read_b128 v[202:205], v153 offset:54272
	ds_read_b128 v[206:209], v153 offset:55296
	ds_read_b128 v[210:213], v153 offset:56320
	global_load_lds_dwordx4 v[230:231], off
	v_lshl_add_u64 v[230:231], v[236:237], 0, s[10:11]
	s_mov_b32 m0, s78
	s_nop 0
	global_load_lds_dwordx4 v[230:231], off
	s_barrier
	s_waitcnt lgkmcnt(0)
	s_waitcnt lgkmcnt(0)
	v_mfma_f32_16x16x32_bf16 v[60:63], v[160:163], v[180:183], v[60:63]
	v_mfma_f32_16x16x32_bf16 v[60:63], v[164:167], v[186:189], v[60:63]
	v_mfma_f32_16x16x32_bf16 v[56:59], v[168:171], v[180:183], v[56:59]
	v_mfma_f32_16x16x32_bf16 v[56:59], v[176:179], v[186:189], v[56:59]
	v_mfma_f32_16x16x32_bf16 v[48:51], v[160:163], v[190:193], v[48:51]
	v_mfma_f32_16x16x32_bf16 v[48:51], v[164:167], v[194:197], v[48:51]
	v_mfma_f32_16x16x32_bf16 v[40:43], v[168:171], v[190:193], v[40:43]
	v_mfma_f32_16x16x32_bf16 v[40:43], v[176:179], v[194:197], v[40:43]
	v_mfma_f32_16x16x32_bf16 v[32:35], v[160:163], v[198:201], v[32:35]
	v_mfma_f32_16x16x32_bf16 v[32:35], v[164:167], v[202:205], v[32:35]
	v_mfma_f32_16x16x32_bf16 v[24:27], v[168:171], v[198:201], v[24:27]
	v_mfma_f32_16x16x32_bf16 v[24:27], v[176:179], v[202:205], v[24:27]
	v_mfma_f32_16x16x32_bf16 v[16:19], v[160:163], v[206:209], v[16:19]
	v_mfma_f32_16x16x32_bf16 v[16:19], v[164:167], v[210:213], v[16:19]
	v_mfma_f32_16x16x32_bf16 v[8:11], v[168:171], v[206:209], v[8:11]
	v_mfma_f32_16x16x32_bf16 v[8:11], v[176:179], v[210:213], v[8:11]
	s_barrier
	s_add_u32 s46, s50, 0x20080
	s_addc_u32 s47, s51, 0
	s_add_i32 s50, s52, s54
	v_lshl_add_u64 v[160:161], s[46:47], 0, v[130:131]
	s_mov_b32 m0, s50
	s_nop 0
	global_load_lds_dwordx4 v[160:161], off
	v_lshl_add_u64 v[160:161], s[46:47], 0, v[134:135]
	s_add_i32 m0, s50, 0x2000
	s_nop 0
	global_load_lds_dwordx4 v[160:161], off
	s_waitcnt vmcnt(6)
	s_barrier
	v_mfma_f32_16x16x32_bf16 v[52:55], v[214:217], v[180:183], v[52:55]
	v_mfma_f32_16x16x32_bf16 v[52:55], v[218:221], v[186:189], v[52:55]
	v_mfma_f32_16x16x32_bf16 v[44:47], v[222:225], v[180:183], v[44:47]
	v_mfma_f32_16x16x32_bf16 v[44:47], v[226:229], v[186:189], v[44:47]
	v_mfma_f32_16x16x32_bf16 v[36:39], v[214:217], v[190:193], v[36:39]
	v_mfma_f32_16x16x32_bf16 v[36:39], v[218:221], v[194:197], v[36:39]
	v_mfma_f32_16x16x32_bf16 v[28:31], v[222:225], v[190:193], v[28:31]
	v_mfma_f32_16x16x32_bf16 v[28:31], v[226:229], v[194:197], v[28:31]
	v_mfma_f32_16x16x32_bf16 v[20:23], v[214:217], v[198:201], v[20:23]
	v_mfma_f32_16x16x32_bf16 v[20:23], v[218:221], v[202:205], v[20:23]
	v_mfma_f32_16x16x32_bf16 v[12:15], v[222:225], v[198:201], v[12:15]
	v_mfma_f32_16x16x32_bf16 v[12:15], v[226:229], v[202:205], v[12:15]
	v_mfma_f32_16x16x32_bf16 v[4:7], v[214:217], v[206:209], v[4:7]
	v_mfma_f32_16x16x32_bf16 v[4:7], v[218:221], v[210:213], v[4:7]
	v_mfma_f32_16x16x32_bf16 v[0:3], v[222:225], v[206:209], v[0:3]
	v_mfma_f32_16x16x32_bf16 v[0:3], v[226:229], v[210:213], v[0:3]
	s_add_i32 s91, s91, 2
	s_add_u32 s63, s63, 0x100
	s_addc_u32 s90, s90, 0
	s_cmp_gt_u32 s91, 5
	s_mov_b64 s[46:47], s[48:49]
	s_cbranch_scc0 .Lrot_325
	s_barrier
	v_lshl_add_u32 v162, s88, 8, v137
	v_lshl_or_b32 v160, s89, 8, v141
	v_ashrrev_i32_e32 v163, 31, v162
	v_ashrrev_i32_e32 v161, 31, v160
	v_lshlrev_b64 v[164:165], 14, v[162:163]
	v_lshl_add_u64 v[164:165], s[56:57], 0, v[164:165]
	v_lshlrev_b64 v[166:167], 1, v[160:161]
	v_lshl_add_u64 v[160:161], v[164:165], 0, v[166:167]
	s_waitcnt vmcnt(0)
	v_pk_mul_f32 v[126:127], v[158:159], v[126:127] op_sel_hi:[0,1]
	v_pk_mul_f32 v[124:125], v[158:159], v[124:125] op_sel_hi:[0,1]
	v_pk_mul_f32 v[164:165], v[158:159], v[122:123] op_sel_hi:[0,1]
	v_pk_mul_f32 v[122:123], v[158:159], v[120:121] op_sel_hi:[0,1]
	v_cvt_pk_bf16_f32 v120, v124, v125
	v_cvt_pk_bf16_f32 v121, v126, v127
	v_cvt_pk_bf16_f32 v122, v122, v123
	v_cvt_pk_bf16_f32 v123, v164, v165
	global_store_dwordx4 v[160:161], v[120:123], off
	v_pk_mul_f32 v[116:117], v[158:159], v[116:117] op_sel_hi:[0,1]
	v_pk_mul_f32 v[118:119], v[158:159], v[118:119] op_sel_hi:[0,1]
	v_pk_mul_f32 v[120:121], v[158:159], v[114:115] op_sel_hi:[0,1]
	v_pk_mul_f32 v[114:115], v[158:159], v[112:113] op_sel_hi:[0,1]
	v_cvt_pk_bf16_f32 v112, v116, v117
	v_cvt_pk_bf16_f32 v113, v118, v119
	v_cvt_pk_bf16_f32 v114, v114, v115
	v_cvt_pk_bf16_f32 v115, v120, v121
	global_store_dwordx4 v[160:161], v[112:115], off offset:256
	v_pk_mul_f32 v[110:111], v[156:157], v[110:111] op_sel_hi:[0,1]
	v_pk_mul_f32 v[108:109], v[156:157], v[108:109] op_sel_hi:[0,1]
	v_or_b32_e32 v112, 16, v162
	v_ashrrev_i32_e32 v113, 31, v112
	v_lshlrev_b64 v[112:113], 14, v[112:113]
	v_lshl_add_u64 v[112:113], s[56:57], 0, v[112:113]
	v_lshl_add_u64 v[112:113], v[112:113], 0, v[166:167]
	v_pk_mul_f32 v[114:115], v[156:157], v[106:107] op_sel_hi:[0,1]
	v_pk_mul_f32 v[106:107], v[156:157], v[104:105] op_sel_hi:[0,1]
	v_cvt_pk_bf16_f32 v104, v108, v109
	v_cvt_pk_bf16_f32 v105, v110, v111
	v_cvt_pk_bf16_f32 v106, v106, v107
	v_cvt_pk_bf16_f32 v107, v114, v115
	global_store_dwordx4 v[112:113], v[104:107], off
	v_pk_mul_f32 v[100:101], v[156:157], v[100:101] op_sel_hi:[0,1]
	v_pk_mul_f32 v[102:103], v[156:157], v[102:103] op_sel_hi:[0,1]
	v_pk_mul_f32 v[104:105], v[156:157], v[98:99] op_sel_hi:[0,1]
	v_pk_mul_f32 v[98:99], v[156:157], v[96:97] op_sel_hi:[0,1]
	v_cvt_pk_bf16_f32 v96, v100, v101
	v_cvt_pk_bf16_f32 v97, v102, v103
	v_cvt_pk_bf16_f32 v98, v98, v99
	v_cvt_pk_bf16_f32 v99, v104, v105
	global_store_dwordx4 v[112:113], v[96:99], off offset:256
	v_pk_mul_f32 v[94:95], v[154:155], v[94:95] op_sel_hi:[0,1]
	v_pk_mul_f32 v[92:93], v[154:155], v[92:93] op_sel_hi:[0,1]
	v_or_b32_e32 v96, 32, v162
	v_ashrrev_i32_e32 v97, 31, v96
	v_lshlrev_b64 v[96:97], 14, v[96:97]
	v_lshl_add_u64 v[96:97], s[56:57], 0, v[96:97]
	v_lshl_add_u64 v[96:97], v[96:97], 0, v[166:167]
	v_pk_mul_f32 v[98:99], v[154:155], v[90:91] op_sel_hi:[0,1]
	v_pk_mul_f32 v[90:91], v[154:155], v[88:89] op_sel_hi:[0,1]
	v_cvt_pk_bf16_f32 v88, v92, v93
	v_cvt_pk_bf16_f32 v89, v94, v95
	v_cvt_pk_bf16_f32 v90, v90, v91
	v_cvt_pk_bf16_f32 v91, v98, v99
	global_store_dwordx4 v[96:97], v[88:91], off
	v_pk_mul_f32 v[84:85], v[154:155], v[84:85] op_sel_hi:[0,1]
	v_pk_mul_f32 v[86:87], v[154:155], v[86:87] op_sel_hi:[0,1]
	v_pk_mul_f32 v[88:89], v[154:155], v[82:83] op_sel_hi:[0,1]
	v_pk_mul_f32 v[82:83], v[154:155], v[80:81] op_sel_hi:[0,1]
	v_cvt_pk_bf16_f32 v80, v84, v85
	v_cvt_pk_bf16_f32 v81, v86, v87
	v_cvt_pk_bf16_f32 v82, v82, v83
	v_cvt_pk_bf16_f32 v83, v88, v89
	global_store_dwordx4 v[96:97], v[80:83], off offset:256
	v_pk_mul_f32 v[78:79], v[152:153], v[78:79] op_sel_hi:[0,1]
	v_pk_mul_f32 v[76:77], v[152:153], v[76:77] op_sel_hi:[0,1]
	v_or_b32_e32 v80, 48, v162
	v_ashrrev_i32_e32 v81, 31, v80
	v_lshlrev_b64 v[80:81], 14, v[80:81]
	v_lshl_add_u64 v[80:81], s[56:57], 0, v[80:81]
	v_lshl_add_u64 v[80:81], v[80:81], 0, v[166:167]
	v_pk_mul_f32 v[82:83], v[152:153], v[74:75] op_sel_hi:[0,1]
	v_pk_mul_f32 v[74:75], v[152:153], v[72:73] op_sel_hi:[0,1]
	v_cvt_pk_bf16_f32 v72, v76, v77
	v_cvt_pk_bf16_f32 v73, v78, v79
	v_cvt_pk_bf16_f32 v74, v74, v75
	v_cvt_pk_bf16_f32 v75, v82, v83
	global_store_dwordx4 v[80:81], v[72:75], off
	v_pk_mul_f32 v[70:71], v[152:153], v[70:71] op_sel_hi:[0,1]
	v_pk_mul_f32 v[68:69], v[152:153], v[68:69] op_sel_hi:[0,1]
	v_pk_mul_f32 v[72:73], v[152:153], v[66:67] op_sel_hi:[0,1]
	v_pk_mul_f32 v[66:67], v[152:153], v[64:65] op_sel_hi:[0,1]
	v_cvt_pk_bf16_f32 v64, v68, v69
	v_cvt_pk_bf16_f32 v65, v70, v71
	v_cvt_pk_bf16_f32 v66, v66, v67
	v_cvt_pk_bf16_f32 v67, v72, v73
	v_pk_mul_f32 v[60:61], v[150:151], v[60:61] op_sel_hi:[0,1]
	global_store_dwordx4 v[80:81], v[64:67], off offset:256
	v_pk_mul_f32 v[62:63], v[150:151], v[62:63] op_sel_hi:[0,1]
	s_mov_b64 s[46:47], 0x200000
	v_pk_mul_f32 v[66:67], v[150:151], v[58:59] op_sel_hi:[0,1]
	v_pk_mul_f32 v[58:59], v[150:151], v[56:57] op_sel_hi:[0,1]
	v_cvt_pk_bf16_f32 v56, v60, v61
	v_add_co_u32_e32 v60, vcc, s83, v160
	v_cvt_pk_bf16_f32 v57, v62, v63
	v_cvt_pk_bf16_f32 v58, v58, v59
	v_cvt_pk_bf16_f32 v59, v66, v67
	v_lshl_add_u64 v[64:65], v[160:161], 0, s[46:47]
	s_nop 0
	v_addc_co_u32_e32 v61, vcc, 0, v161, vcc
	global_store_dwordx4 v[60:61], v[56:59], off
	v_pk_mul_f32 v[54:55], v[150:151], v[54:55] op_sel_hi:[0,1]
	v_pk_mul_f32 v[52:53], v[150:151], v[52:53] op_sel_hi:[0,1]
	v_pk_mul_f32 v[56:57], v[150:151], v[46:47] op_sel_hi:[0,1]
	v_pk_mul_f32 v[46:47], v[150:151], v[44:45] op_sel_hi:[0,1]
	v_cvt_pk_bf16_f32 v44, v52, v53
	v_cvt_pk_bf16_f32 v45, v54, v55
	v_cvt_pk_bf16_f32 v46, v46, v47
	v_cvt_pk_bf16_f32 v47, v56, v57
	global_store_dwordx4 v[64:65], v[44:47], off offset:256
	v_pk_mul_f32 v[48:49], v[140:141], v[48:49] op_sel_hi:[0,1]
	v_pk_mul_f32 v[38:39], v[140:141], v[38:39] op_sel_hi:[0,1]
	v_pk_mul_f32 v[46:47], v[140:141], v[50:51] op_sel_hi:[0,1]
	v_pk_mul_f32 v[50:51], v[140:141], v[42:43] op_sel_hi:[0,1]
	v_pk_mul_f32 v[42:43], v[140:141], v[40:41] op_sel_hi:[0,1]
	v_cvt_pk_bf16_f32 v40, v48, v49
	v_cvt_pk_bf16_f32 v41, v46, v47
	v_add_co_u32_e32 v46, vcc, s84, v160
	v_cvt_pk_bf16_f32 v42, v42, v43
	v_cvt_pk_bf16_f32 v43, v50, v51
	v_lshl_add_u64 v[44:45], v[160:161], 0, s[30:31]
	s_nop 0
	v_addc_co_u32_e32 v47, vcc, 0, v161, vcc
	global_store_dwordx4 v[46:47], v[40:43], off
	v_pk_mul_f32 v[36:37], v[140:141], v[36:37] op_sel_hi:[0,1]
	v_pk_mul_f32 v[32:33], v[138:139], v[32:33] op_sel_hi:[0,1]
	v_pk_mul_f32 v[40:41], v[140:141], v[30:31] op_sel_hi:[0,1]
	v_pk_mul_f32 v[30:31], v[140:141], v[28:29] op_sel_hi:[0,1]
	v_cvt_pk_bf16_f32 v28, v36, v37
	v_cvt_pk_bf16_f32 v29, v38, v39
	v_cvt_pk_bf16_f32 v30, v30, v31
	v_cvt_pk_bf16_f32 v31, v40, v41
	global_store_dwordx4 v[44:45], v[28:31], off offset:256
	v_pk_mul_f32 v[22:23], v[138:139], v[22:23] op_sel_hi:[0,1]
	v_pk_mul_f32 v[20:21], v[138:139], v[20:21] op_sel_hi:[0,1]
	v_pk_mul_f32 v[30:31], v[138:139], v[34:35] op_sel_hi:[0,1]
	v_pk_mul_f32 v[34:35], v[138:139], v[26:27] op_sel_hi:[0,1]
	v_pk_mul_f32 v[26:27], v[138:139], v[24:25] op_sel_hi:[0,1]
	v_cvt_pk_bf16_f32 v24, v32, v33
	v_cvt_pk_bf16_f32 v25, v30, v31
	v_add_co_u32_e32 v30, vcc, s85, v160
	v_cvt_pk_bf16_f32 v26, v26, v27
	v_cvt_pk_bf16_f32 v27, v34, v35
	v_lshl_add_u64 v[28:29], v[160:161], 0, s[36:37]
	s_nop 0
	v_addc_co_u32_e32 v31, vcc, 0, v161, vcc
	global_store_dwordx4 v[30:31], v[24:27], off
	v_pk_mul_f32 v[16:17], v[136:137], v[16:17] op_sel_hi:[0,1]
	s_mov_b64 s[46:47], -1
	v_pk_mul_f32 v[24:25], v[138:139], v[14:15] op_sel_hi:[0,1]
	v_pk_mul_f32 v[14:15], v[138:139], v[12:13] op_sel_hi:[0,1]
	v_cvt_pk_bf16_f32 v12, v20, v21
	v_cvt_pk_bf16_f32 v13, v22, v23
	v_cvt_pk_bf16_f32 v14, v14, v15
	v_cvt_pk_bf16_f32 v15, v24, v25
	global_store_dwordx4 v[28:29], v[12:15], off offset:256
	v_pk_mul_f32 v[6:7], v[136:137], v[6:7] op_sel_hi:[0,1]
	v_pk_mul_f32 v[4:5], v[136:137], v[4:5] op_sel_hi:[0,1]
	v_pk_mul_f32 v[14:15], v[136:137], v[18:19] op_sel_hi:[0,1]
	v_pk_mul_f32 v[18:19], v[136:137], v[10:11] op_sel_hi:[0,1]
	v_pk_mul_f32 v[10:11], v[136:137], v[8:9] op_sel_hi:[0,1]
	v_cvt_pk_bf16_f32 v8, v16, v17
	v_cvt_pk_bf16_f32 v9, v14, v15
	v_add_co_u32_e32 v14, vcc, s86, v160
	v_lshl_add_u64 v[12:13], v[160:161], 0, s[38:39]
	s_nop 0
	v_addc_co_u32_e32 v15, vcc, 0, v161, vcc
	v_cvt_pk_bf16_f32 v10, v10, v11
	v_cvt_pk_bf16_f32 v11, v18, v19
	global_store_dwordx4 v[14:15], v[8:11], off
	s_and_b64 vcc, s[8:9], exec
	s_nop 0
	v_pk_mul_f32 v[8:9], v[136:137], v[2:3] op_sel_hi:[0,1]
	v_pk_mul_f32 v[2:3], v[136:137], v[0:1] op_sel_hi:[0,1]
	v_cvt_pk_bf16_f32 v0, v4, v5
	v_cvt_pk_bf16_f32 v1, v6, v7
	v_cvt_pk_bf16_f32 v2, v2, v3
	v_cvt_pk_bf16_f32 v3, v8, v9
	global_store_dwordx4 v[12:13], v[0:3], off offset:256
	s_cbranch_vccz .LBB0_315
	s_nop 0
	v_lshl_add_u32 v0, s87, 8, v137
	v_ashrrev_i32_e32 v1, 31, v0
	v_lshl_add_u64 v[0:1], v[0:1], 2, s[34:35]
	global_load_dword v158, v[0:1], off
	global_load_dword v156, v[0:1], off offset:64
	global_load_dword v154, v[0:1], off offset:128
	global_load_dword v152, v[0:1], off offset:192
	global_load_dword v150, v[0:1], off offset:512
	global_load_dword v140, v[0:1], off offset:576
	global_load_dword v138, v[0:1], off offset:640
	global_load_dword v136, v[0:1], off offset:704
	s_mov_b64 s[46:47], 0
	s_branch .LBB0_315

.LBB0_513:
	s_ashr_i32 s27, s26, 31
	s_lshl_b64 s[6:7], s[26:27], 21
	v_cmp_lt_i64_e32 vcc, s[28:29], v[156:157]
	s_add_u32 s28, s70, s6
	s_addc_u32 s29, s71, s7
	s_and_b64 s[6:7], vcc, exec
	s_cselect_b32 s6, s29, s39
	s_cselect_b32 s7, s28, s38
	s_ashr_i32 s25, s24, 31
	s_lshl_b64 s[30:31], s[24:25], 21
	s_add_u32 s30, s14, s30
	s_addc_u32 s31, s15, s31
	s_and_b64 s[42:43], vcc, exec
	s_cselect_b32 s25, s31, s41
	s_cselect_b32 s27, s30, s40
	s_add_u32 s38, s38, 0x100080
	s_addc_u32 s39, s39, 0
	s_add_u32 s35, s40, 0x100
	v_mov_b32_e32 v0, 0
	s_addc_u32 s55, s41, 0
	s_mov_b32 s61, -2
	s_waitcnt lgkmcnt(0)
	v_mov_b32_e32 v1, v0
	v_mov_b32_e32 v2, v0
	v_mov_b32_e32 v3, v0
	v_mov_b32_e32 v4, v0
	v_mov_b32_e32 v5, v0
	v_mov_b32_e32 v6, v0
	v_mov_b32_e32 v7, v0
	v_mov_b32_e32 v16, v0
	v_mov_b32_e32 v17, v0
	v_mov_b32_e32 v18, v0
	v_mov_b32_e32 v19, v0
	v_mov_b32_e32 v20, v0
	v_mov_b32_e32 v21, v0
	v_mov_b32_e32 v22, v0
	v_mov_b32_e32 v23, v0
	v_mov_b32_e32 v32, v0
	v_mov_b32_e32 v33, v0
	v_mov_b32_e32 v34, v0
	v_mov_b32_e32 v35, v0
	v_mov_b32_e32 v36, v0
	v_mov_b32_e32 v37, v0
	v_mov_b32_e32 v38, v0
	v_mov_b32_e32 v39, v0
	v_mov_b32_e32 v48, v0
	v_mov_b32_e32 v49, v0
	v_mov_b32_e32 v50, v0
	v_mov_b32_e32 v51, v0
	v_mov_b32_e32 v52, v0
	v_mov_b32_e32 v53, v0
	v_mov_b32_e32 v54, v0
	v_mov_b32_e32 v55, v0
	v_mov_b32_e32 v8, v0
	v_mov_b32_e32 v9, v0
	v_mov_b32_e32 v10, v0
	v_mov_b32_e32 v11, v0
	v_mov_b32_e32 v12, v0
	v_mov_b32_e32 v13, v0
	v_mov_b32_e32 v14, v0
	v_mov_b32_e32 v15, v0
	v_mov_b32_e32 v24, v0
	v_mov_b32_e32 v25, v0
	v_mov_b32_e32 v26, v0
	v_mov_b32_e32 v27, v0
	v_mov_b32_e32 v28, v0
	v_mov_b32_e32 v29, v0
	v_mov_b32_e32 v30, v0
	v_mov_b32_e32 v31, v0
	v_mov_b32_e32 v40, v0
	v_mov_b32_e32 v41, v0
	v_mov_b32_e32 v42, v0
	v_mov_b32_e32 v43, v0
	v_mov_b32_e32 v44, v0
	v_mov_b32_e32 v45, v0
	v_mov_b32_e32 v46, v0
	v_mov_b32_e32 v47, v0
	v_mov_b32_e32 v56, v0
	v_mov_b32_e32 v57, v0
	v_mov_b32_e32 v58, v0
	v_mov_b32_e32 v59, v0
	v_mov_b32_e32 v60, v0
	v_mov_b32_e32 v61, v0
	v_mov_b32_e32 v62, v0
	v_mov_b32_e32 v63, v0
	v_mov_b32_e32 v64, v0
	v_mov_b32_e32 v65, v0
	v_mov_b32_e32 v66, v0
	v_mov_b32_e32 v67, v0
	v_mov_b32_e32 v68, v0
	v_mov_b32_e32 v69, v0
	v_mov_b32_e32 v70, v0
	v_mov_b32_e32 v71, v0
	v_mov_b32_e32 v80, v0
	v_mov_b32_e32 v81, v0
	v_mov_b32_e32 v82, v0
	v_mov_b32_e32 v83, v0
	v_mov_b32_e32 v84, v0
	v_mov_b32_e32 v85, v0
	v_mov_b32_e32 v86, v0
	v_mov_b32_e32 v87, v0
	v_mov_b32_e32 v96, v0
	v_mov_b32_e32 v97, v0
	v_mov_b32_e32 v98, v0
	v_mov_b32_e32 v99, v0
	v_mov_b32_e32 v100, v0
	v_mov_b32_e32 v101, v0
	v_mov_b32_e32 v102, v0
	v_mov_b32_e32 v103, v0
	v_mov_b32_e32 v112, v0
	v_mov_b32_e32 v113, v0
	v_mov_b32_e32 v114, v0
	v_mov_b32_e32 v115, v0
	v_mov_b32_e32 v116, v0
	v_mov_b32_e32 v117, v0
	v_mov_b32_e32 v118, v0
	v_mov_b32_e32 v119, v0
	v_mov_b32_e32 v72, v0
	v_mov_b32_e32 v73, v0
	v_mov_b32_e32 v74, v0
	v_mov_b32_e32 v75, v0
	v_mov_b32_e32 v76, v0
	v_mov_b32_e32 v77, v0
	v_mov_b32_e32 v78, v0
	v_mov_b32_e32 v79, v0
	v_mov_b32_e32 v88, v0
	v_mov_b32_e32 v89, v0
	v_mov_b32_e32 v90, v0
	v_mov_b32_e32 v91, v0
	v_mov_b32_e32 v92, v0
	v_mov_b32_e32 v93, v0
	v_mov_b32_e32 v94, v0
	v_mov_b32_e32 v95, v0
	v_mov_b32_e32 v104, v0
	v_mov_b32_e32 v105, v0
	v_mov_b32_e32 v106, v0
	v_mov_b32_e32 v107, v0
	v_mov_b32_e32 v108, v0
	v_mov_b32_e32 v109, v0
	v_mov_b32_e32 v110, v0
	v_mov_b32_e32 v111, v0
	v_mov_b32_e32 v120, v0
	v_mov_b32_e32 v121, v0
	v_mov_b32_e32 v122, v0
	v_mov_b32_e32 v123, v0
	v_mov_b32_e32 v124, v0
	v_mov_b32_e32 v125, v0
	v_mov_b32_e32 v126, v0
	v_mov_b32_e32 v127, v0
	s_branch .LBB0_514

.LBB0_514:
	ds_read_b128 v[128:131], v171
	ds_read_b128 v[132:135], v171 offset:1024
	ds_read_b128 v[136:139], v171 offset:2048
	ds_read_b128 v[140:143], v171 offset:3072
	s_add_u32 s40, s38, 0xfff00080
	s_addc_u32 s41, s39, -1
	s_cmp_eq_u32 s61, 60
	s_cselect_b32 s43, s6, s41
	s_cselect_b32 s42, s7, s40
	s_cselect_b32 s41, s25, s55
	s_cselect_b32 s40, s27, s35
	v_lshl_add_u64 v[202:203], s[38:39], 0, v[152:153]
	s_add_i32 m0, s37, 0xc000
	ds_read_b128 v[160:163], v173
	ds_read_b128 v[164:167], v173 offset:1024
	ds_read_b128 v[176:179], v173 offset:2048
	ds_read_b128 v[180:183], v173 offset:3072
	ds_read_b128 v[186:189], v173 offset:4096
	ds_read_b128 v[190:193], v173 offset:5120
	ds_read_b128 v[194:197], v173 offset:6144
	ds_read_b128 v[198:201], v173 offset:7168
	global_load_lds_dwordx4 v[202:203], off
	v_lshl_add_u64 v[202:203], s[38:39], 0, v[154:155]
	s_add_i32 m0, s37, 0xe000
	s_nop 0
	global_load_lds_dwordx4 v[202:203], off
	s_waitcnt lgkmcnt(8)
	s_barrier
	s_waitcnt lgkmcnt(0)
	s_waitcnt lgkmcnt(0)
	v_mfma_f32_16x16x32_bf16 v[124:127], v[128:131], v[160:163], v[124:127]
	v_mfma_f32_16x16x32_bf16 v[124:127], v[132:135], v[164:167], v[124:127]
	v_mfma_f32_16x16x32_bf16 v[120:123], v[136:139], v[160:163], v[120:123]
	v_mfma_f32_16x16x32_bf16 v[120:123], v[140:143], v[164:167], v[120:123]
	v_mfma_f32_16x16x32_bf16 v[108:111], v[128:131], v[176:179], v[108:111]
	v_mfma_f32_16x16x32_bf16 v[108:111], v[132:135], v[180:183], v[108:111]
	v_mfma_f32_16x16x32_bf16 v[104:107], v[136:139], v[176:179], v[104:107]
	v_mfma_f32_16x16x32_bf16 v[104:107], v[140:143], v[180:183], v[104:107]
	v_mfma_f32_16x16x32_bf16 v[92:95], v[128:131], v[186:189], v[92:95]
	v_mfma_f32_16x16x32_bf16 v[92:95], v[132:135], v[190:193], v[92:95]
	v_mfma_f32_16x16x32_bf16 v[88:91], v[136:139], v[186:189], v[88:91]
	v_mfma_f32_16x16x32_bf16 v[88:91], v[140:143], v[190:193], v[88:91]
	v_mfma_f32_16x16x32_bf16 v[76:79], v[128:131], v[194:197], v[76:79]
	v_mfma_f32_16x16x32_bf16 v[76:79], v[132:135], v[198:201], v[76:79]
	v_mfma_f32_16x16x32_bf16 v[72:75], v[136:139], v[194:197], v[72:75]
	v_mfma_f32_16x16x32_bf16 v[72:75], v[140:143], v[198:201], v[72:75]
	s_barrier
	s_add_i32 s62, s53, s5
	v_lshl_add_u64 v[218:219], s[40:41], 0, v[146:147]
	s_mov_b32 m0, s62
	ds_read_b128 v[202:205], v174
	ds_read_b128 v[206:209], v174 offset:1024
	ds_read_b128 v[210:213], v174 offset:2048
	ds_read_b128 v[214:217], v174 offset:3072
	global_load_lds_dwordx4 v[218:219], off
	v_lshl_add_u64 v[220:221], s[40:41], 0, v[150:151]
	s_add_i32 m0, s62, 0x2000
	s_nop 0
	global_load_lds_dwordx4 v[220:221], off
	s_barrier
	s_waitcnt lgkmcnt(0)
	s_waitcnt lgkmcnt(0)
	v_mfma_f32_16x16x32_bf16 v[116:119], v[202:205], v[160:163], v[116:119]
	v_mfma_f32_16x16x32_bf16 v[116:119], v[206:209], v[164:167], v[116:119]
	v_mfma_f32_16x16x32_bf16 v[112:115], v[210:213], v[160:163], v[112:115]
	v_mfma_f32_16x16x32_bf16 v[112:115], v[214:217], v[164:167], v[112:115]
	v_mfma_f32_16x16x32_bf16 v[100:103], v[202:205], v[176:179], v[100:103]
	v_mfma_f32_16x16x32_bf16 v[100:103], v[206:209], v[180:183], v[100:103]
	v_mfma_f32_16x16x32_bf16 v[96:99], v[210:213], v[176:179], v[96:99]
	v_mfma_f32_16x16x32_bf16 v[96:99], v[214:217], v[180:183], v[96:99]
	v_mfma_f32_16x16x32_bf16 v[84:87], v[202:205], v[186:189], v[84:87]
	v_mfma_f32_16x16x32_bf16 v[84:87], v[206:209], v[190:193], v[84:87]
	v_mfma_f32_16x16x32_bf16 v[80:83], v[210:213], v[186:189], v[80:83]
	v_mfma_f32_16x16x32_bf16 v[80:83], v[214:217], v[190:193], v[80:83]
	v_mfma_f32_16x16x32_bf16 v[68:71], v[202:205], v[194:197], v[68:71]
	v_mfma_f32_16x16x32_bf16 v[68:71], v[206:209], v[198:201], v[68:71]
	v_mfma_f32_16x16x32_bf16 v[64:67], v[210:213], v[194:197], v[64:67]
	v_mfma_f32_16x16x32_bf16 v[64:67], v[214:217], v[198:201], v[64:67]
	s_mov_b32 m0, s37
	v_lshl_add_u64 v[222:223], s[42:43], 0, v[144:145]
	s_barrier
	ds_read_b128 v[160:163], v173 offset:16384
	ds_read_b128 v[164:167], v173 offset:17408
	ds_read_b128 v[176:179], v173 offset:18432
	ds_read_b128 v[180:183], v173 offset:19456
	ds_read_b128 v[186:189], v173 offset:20480
	ds_read_b128 v[190:193], v173 offset:21504
	ds_read_b128 v[194:197], v173 offset:22528
	ds_read_b128 v[198:201], v173 offset:23552
	global_load_lds_dwordx4 v[222:223], off
	v_lshl_add_u64 v[224:225], s[42:43], 0, v[148:149]
	s_mov_b32 m0, s44
	s_nop 0
	global_load_lds_dwordx4 v[224:225], off
	s_barrier
	s_waitcnt lgkmcnt(0)
	s_waitcnt lgkmcnt(0)
	v_mfma_f32_16x16x32_bf16 v[60:63], v[128:131], v[160:163], v[60:63]
	v_mfma_f32_16x16x32_bf16 v[60:63], v[132:135], v[164:167], v[60:63]
	v_mfma_f32_16x16x32_bf16 v[56:59], v[136:139], v[160:163], v[56:59]
	v_mfma_f32_16x16x32_bf16 v[56:59], v[140:143], v[164:167], v[56:59]
	v_mfma_f32_16x16x32_bf16 v[44:47], v[128:131], v[176:179], v[44:47]
	v_mfma_f32_16x16x32_bf16 v[44:47], v[132:135], v[180:183], v[44:47]
	v_mfma_f32_16x16x32_bf16 v[40:43], v[136:139], v[176:179], v[40:43]
	v_mfma_f32_16x16x32_bf16 v[40:43], v[140:143], v[180:183], v[40:43]
	v_mfma_f32_16x16x32_bf16 v[28:31], v[128:131], v[186:189], v[28:31]
	v_mfma_f32_16x16x32_bf16 v[28:31], v[132:135], v[190:193], v[28:31]
	v_mfma_f32_16x16x32_bf16 v[24:27], v[136:139], v[186:189], v[24:27]
	v_mfma_f32_16x16x32_bf16 v[24:27], v[140:143], v[190:193], v[24:27]
	v_mfma_f32_16x16x32_bf16 v[12:15], v[128:131], v[194:197], v[12:15]
	v_mfma_f32_16x16x32_bf16 v[12:15], v[132:135], v[198:201], v[12:15]
	v_mfma_f32_16x16x32_bf16 v[8:11], v[136:139], v[194:197], v[8:11]
	v_mfma_f32_16x16x32_bf16 v[8:11], v[140:143], v[198:201], v[8:11]
	s_barrier
	s_add_u32 s62, s40, 0x100000
	s_addc_u32 s63, s41, 0
	s_add_i32 s74, s54, s5
	v_lshl_add_u64 v[128:129], s[62:63], 0, v[146:147]
	s_mov_b32 m0, s74
	s_nop 0
	global_load_lds_dwordx4 v[128:129], off
	v_lshl_add_u64 v[128:129], s[62:63], 0, v[150:151]
	s_add_i32 m0, s74, 0x2000
	s_nop 0
	global_load_lds_dwordx4 v[128:129], off
	s_waitcnt vmcnt(6)
	s_barrier
	v_mfma_f32_16x16x32_bf16 v[52:55], v[202:205], v[160:163], v[52:55]
	v_mfma_f32_16x16x32_bf16 v[52:55], v[206:209], v[164:167], v[52:55]
	v_mfma_f32_16x16x32_bf16 v[48:51], v[210:213], v[160:163], v[48:51]
	v_mfma_f32_16x16x32_bf16 v[48:51], v[214:217], v[164:167], v[48:51]
	v_mfma_f32_16x16x32_bf16 v[36:39], v[202:205], v[176:179], v[36:39]
	v_mfma_f32_16x16x32_bf16 v[36:39], v[206:209], v[180:183], v[36:39]
	v_mfma_f32_16x16x32_bf16 v[32:35], v[210:213], v[176:179], v[32:35]
	v_mfma_f32_16x16x32_bf16 v[32:35], v[214:217], v[180:183], v[32:35]
	v_mfma_f32_16x16x32_bf16 v[20:23], v[202:205], v[186:189], v[20:23]
	v_mfma_f32_16x16x32_bf16 v[20:23], v[206:209], v[190:193], v[20:23]
	v_mfma_f32_16x16x32_bf16 v[16:19], v[210:213], v[186:189], v[16:19]
	v_mfma_f32_16x16x32_bf16 v[16:19], v[214:217], v[190:193], v[16:19]
	v_mfma_f32_16x16x32_bf16 v[4:7], v[202:205], v[194:197], v[4:7]
	v_mfma_f32_16x16x32_bf16 v[4:7], v[206:209], v[198:201], v[4:7]
	v_mfma_f32_16x16x32_bf16 v[0:3], v[210:213], v[194:197], v[0:3]
	v_mfma_f32_16x16x32_bf16 v[0:3], v[214:217], v[198:201], v[0:3]
	s_add_i32 s62, 0, 0x18000
	v_add_u32_e32 v140, s62, v169
	s_barrier
	ds_read_b128 v[128:131], v140
	ds_read_b128 v[132:135], v140 offset:1024
	ds_read_b128 v[136:139], v140 offset:2048
	ds_read_b128 v[140:143], v140 offset:3072
	s_add_u32 s42, s42, 0x100000
	s_addc_u32 s43, s43, 0
	s_mov_b32 m0, s45
	v_lshl_add_u64 v[202:203], s[42:43], 0, v[144:145]
	ds_read_b128 v[160:163], v173 offset:32768
	ds_read_b128 v[164:167], v173 offset:33792
	ds_read_b128 v[176:179], v173 offset:34816
	ds_read_b128 v[180:183], v173 offset:35840
	ds_read_b128 v[186:189], v173 offset:36864
	ds_read_b128 v[190:193], v173 offset:37888
	ds_read_b128 v[194:197], v173 offset:38912
	ds_read_b128 v[198:201], v173 offset:39936
	global_load_lds_dwordx4 v[202:203], off
	v_lshl_add_u64 v[202:203], s[42:43], 0, v[148:149]
	s_mov_b32 m0, s46
	s_nop 0
	global_load_lds_dwordx4 v[202:203], off
	s_waitcnt lgkmcnt(8)
	s_barrier
	s_waitcnt lgkmcnt(0)
	s_waitcnt lgkmcnt(0)
	v_mfma_f32_16x16x32_bf16 v[124:127], v[128:131], v[160:163], v[124:127]
	v_mfma_f32_16x16x32_bf16 v[124:127], v[132:135], v[164:167], v[124:127]
	v_mfma_f32_16x16x32_bf16 v[120:123], v[136:139], v[160:163], v[120:123]
	v_mfma_f32_16x16x32_bf16 v[120:123], v[140:143], v[164:167], v[120:123]
	v_mfma_f32_16x16x32_bf16 v[108:111], v[128:131], v[176:179], v[108:111]
	v_mfma_f32_16x16x32_bf16 v[108:111], v[132:135], v[180:183], v[108:111]
	v_mfma_f32_16x16x32_bf16 v[104:107], v[136:139], v[176:179], v[104:107]
	v_mfma_f32_16x16x32_bf16 v[104:107], v[140:143], v[180:183], v[104:107]
	v_mfma_f32_16x16x32_bf16 v[92:95], v[128:131], v[186:189], v[92:95]
	v_mfma_f32_16x16x32_bf16 v[92:95], v[132:135], v[190:193], v[92:95]
	v_mfma_f32_16x16x32_bf16 v[88:91], v[136:139], v[186:189], v[88:91]
	v_mfma_f32_16x16x32_bf16 v[88:91], v[140:143], v[190:193], v[88:91]
	v_mfma_f32_16x16x32_bf16 v[76:79], v[128:131], v[194:197], v[76:79]
	v_mfma_f32_16x16x32_bf16 v[76:79], v[132:135], v[198:201], v[76:79]
	v_mfma_f32_16x16x32_bf16 v[72:75], v[136:139], v[194:197], v[72:75]
	v_mfma_f32_16x16x32_bf16 v[72:75], v[140:143], v[198:201], v[72:75]
	s_barrier
	s_add_i32 s42, 0, 0x1c000
	s_add_i32 s43, s62, s5
	v_add_u32_e32 v185, s42, v169
	v_lshl_add_u64 v[218:219], v[218:219], 0, s[22:23]
	s_mov_b32 m0, s43
	ds_read_b128 v[202:205], v185
	ds_read_b128 v[206:209], v185 offset:1024
	ds_read_b128 v[210:213], v185 offset:2048
	ds_read_b128 v[214:217], v185 offset:3072
	global_load_lds_dwordx4 v[218:219], off
	v_lshl_add_u64 v[218:219], v[220:221], 0, s[22:23]
	s_add_i32 m0, s43, 0x2000
	s_nop 0
	global_load_lds_dwordx4 v[218:219], off
	s_barrier
	s_waitcnt lgkmcnt(0)
	s_waitcnt lgkmcnt(0)
	v_mfma_f32_16x16x32_bf16 v[116:119], v[202:205], v[160:163], v[116:119]
	v_mfma_f32_16x16x32_bf16 v[116:119], v[206:209], v[164:167], v[116:119]
	v_mfma_f32_16x16x32_bf16 v[112:115], v[210:213], v[160:163], v[112:115]
	v_mfma_f32_16x16x32_bf16 v[112:115], v[214:217], v[164:167], v[112:115]
	v_mfma_f32_16x16x32_bf16 v[100:103], v[202:205], v[176:179], v[100:103]
	v_mfma_f32_16x16x32_bf16 v[100:103], v[206:209], v[180:183], v[100:103]
	v_mfma_f32_16x16x32_bf16 v[96:99], v[210:213], v[176:179], v[96:99]
	v_mfma_f32_16x16x32_bf16 v[96:99], v[214:217], v[180:183], v[96:99]
	v_mfma_f32_16x16x32_bf16 v[84:87], v[202:205], v[186:189], v[84:87]
	v_mfma_f32_16x16x32_bf16 v[84:87], v[206:209], v[190:193], v[84:87]
	v_mfma_f32_16x16x32_bf16 v[80:83], v[210:213], v[186:189], v[80:83]
	v_mfma_f32_16x16x32_bf16 v[80:83], v[214:217], v[190:193], v[80:83]
	v_mfma_f32_16x16x32_bf16 v[68:71], v[202:205], v[194:197], v[68:71]
	v_mfma_f32_16x16x32_bf16 v[68:71], v[206:209], v[198:201], v[68:71]
	v_mfma_f32_16x16x32_bf16 v[64:67], v[210:213], v[194:197], v[64:67]
	v_mfma_f32_16x16x32_bf16 v[64:67], v[214:217], v[198:201], v[64:67]
	s_mov_b32 m0, s48
	v_lshl_add_u64 v[218:219], v[222:223], 0, s[22:23]
	s_barrier
	ds_read_b128 v[160:163], v173 offset:49152
	ds_read_b128 v[164:167], v173 offset:50176
	ds_read_b128 v[176:179], v173 offset:51200
	ds_read_b128 v[180:183], v173 offset:52224
	ds_read_b128 v[186:189], v173 offset:53248
	ds_read_b128 v[190:193], v173 offset:54272
	ds_read_b128 v[194:197], v173 offset:55296
	ds_read_b128 v[198:201], v173 offset:56320
	global_load_lds_dwordx4 v[218:219], off
	v_lshl_add_u64 v[218:219], v[224:225], 0, s[22:23]
	s_mov_b32 m0, s49
	s_nop 0
	global_load_lds_dwordx4 v[218:219], off
	s_barrier
	s_waitcnt lgkmcnt(0)
	s_waitcnt lgkmcnt(0)
	v_mfma_f32_16x16x32_bf16 v[60:63], v[128:131], v[160:163], v[60:63]
	v_mfma_f32_16x16x32_bf16 v[60:63], v[132:135], v[164:167], v[60:63]
	v_mfma_f32_16x16x32_bf16 v[56:59], v[136:139], v[160:163], v[56:59]
	v_mfma_f32_16x16x32_bf16 v[56:59], v[140:143], v[164:167], v[56:59]
	v_mfma_f32_16x16x32_bf16 v[44:47], v[128:131], v[176:179], v[44:47]
	v_mfma_f32_16x16x32_bf16 v[44:47], v[132:135], v[180:183], v[44:47]
	v_mfma_f32_16x16x32_bf16 v[40:43], v[136:139], v[176:179], v[40:43]
	v_mfma_f32_16x16x32_bf16 v[40:43], v[140:143], v[180:183], v[40:43]
	v_mfma_f32_16x16x32_bf16 v[28:31], v[128:131], v[186:189], v[28:31]
	v_mfma_f32_16x16x32_bf16 v[28:31], v[132:135], v[190:193], v[28:31]
	v_mfma_f32_16x16x32_bf16 v[24:27], v[136:139], v[186:189], v[24:27]
	v_mfma_f32_16x16x32_bf16 v[24:27], v[140:143], v[190:193], v[24:27]
	v_mfma_f32_16x16x32_bf16 v[12:15], v[128:131], v[194:197], v[12:15]
	v_mfma_f32_16x16x32_bf16 v[12:15], v[132:135], v[198:201], v[12:15]
	v_mfma_f32_16x16x32_bf16 v[8:11], v[136:139], v[194:197], v[8:11]
	v_mfma_f32_16x16x32_bf16 v[8:11], v[140:143], v[198:201], v[8:11]
	s_barrier
	s_add_u32 s40, s40, 0x100080
	s_addc_u32 s41, s41, 0
	s_add_i32 s42, s42, s5
	v_lshl_add_u64 v[128:129], s[40:41], 0, v[146:147]
	s_mov_b32 m0, s42
	s_nop 0
	global_load_lds_dwordx4 v[128:129], off
	v_lshl_add_u64 v[128:129], s[40:41], 0, v[150:151]
	s_add_i32 m0, s42, 0x2000
	s_nop 0
	global_load_lds_dwordx4 v[128:129], off
	s_waitcnt vmcnt(6)
	s_barrier
	v_mfma_f32_16x16x32_bf16 v[52:55], v[202:205], v[160:163], v[52:55]
	v_mfma_f32_16x16x32_bf16 v[52:55], v[206:209], v[164:167], v[52:55]
	v_mfma_f32_16x16x32_bf16 v[48:51], v[210:213], v[160:163], v[48:51]
	v_mfma_f32_16x16x32_bf16 v[48:51], v[214:217], v[164:167], v[48:51]
	v_mfma_f32_16x16x32_bf16 v[36:39], v[202:205], v[176:179], v[36:39]
	v_mfma_f32_16x16x32_bf16 v[36:39], v[206:209], v[180:183], v[36:39]
	v_mfma_f32_16x16x32_bf16 v[32:35], v[210:213], v[176:179], v[32:35]
	v_mfma_f32_16x16x32_bf16 v[32:35], v[214:217], v[180:183], v[32:35]
	v_mfma_f32_16x16x32_bf16 v[20:23], v[202:205], v[186:189], v[20:23]
	v_mfma_f32_16x16x32_bf16 v[20:23], v[206:209], v[190:193], v[20:23]
	v_mfma_f32_16x16x32_bf16 v[16:19], v[210:213], v[186:189], v[16:19]
	v_mfma_f32_16x16x32_bf16 v[16:19], v[214:217], v[190:193], v[16:19]
	v_mfma_f32_16x16x32_bf16 v[4:7], v[202:205], v[194:197], v[4:7]
	v_mfma_f32_16x16x32_bf16 v[4:7], v[206:209], v[198:201], v[4:7]
	v_mfma_f32_16x16x32_bf16 v[0:3], v[210:213], v[194:197], v[0:3]
	v_mfma_f32_16x16x32_bf16 v[0:3], v[214:217], v[198:201], v[0:3]
	s_add_i32 s61, s61, 2
	s_add_u32 s38, s38, 0x100
	s_addc_u32 s39, s39, 0
	s_add_u32 s35, s35, 0x100
	s_addc_u32 s55, s55, 0
	s_cmp_gt_u32 s61, 61
	s_cbranch_scc0 .Lrot_514
	s_barrier
	v_lshl_add_u32 v162, s34, 8, v168
	v_lshl_or_b32 v160, s36, 8, v170
	v_ashrrev_i32_e32 v163, 31, v162
	v_ashrrev_i32_e32 v161, 31, v160
	v_lshlrev_b64 v[128:129], 14, v[162:163]
	v_lshl_add_u64 v[128:129], s[12:13], 0, v[128:129]
	v_lshlrev_b64 v[130:131], 2, v[160:161]
	v_lshl_add_u64 v[128:129], v[128:129], 0, v[130:131]
	global_load_dwordx4 v[178:181], v[128:129], off
	global_load_dwordx4 v[186:189], v[128:129], off offset:16
	global_load_dwordx4 v[190:193], v[128:129], off offset:512
	global_load_dwordx4 v[194:197], v[128:129], off offset:528
	v_or_b32_e32 v164, 16, v162
	v_ashrrev_i32_e32 v165, 31, v164
	v_lshlrev_b64 v[128:129], 14, v[164:165]
	v_lshl_add_u64 v[128:129], s[12:13], 0, v[128:129]
	v_lshl_add_u64 v[132:133], v[128:129], 0, v[130:131]
	global_load_dwordx4 v[136:139], v[132:133], off offset:16
	global_load_dwordx4 v[140:143], v[132:133], off
	global_load_dwordx4 v[128:131], v[132:133], off offset:528
	s_nop 0
	global_load_dwordx4 v[132:135], v[132:133], off offset:512
	v_and_b32_e32 v166, 64, v175
	v_xor_b32_e32 v176, 16, v175
	v_add_u32_e32 v182, 64, v166
	v_xor_b32_e32 v177, 32, v175
	v_cmp_lt_i32_e32 vcc, v176, v182
	v_lshlrev_b64 v[166:167], 13, v[162:163]
	v_lshl_add_u64 v[166:167], s[56:57], 0, v[166:167]
	v_cndmask_b32_e32 v176, v175, v176, vcc
	v_cmp_lt_i32_e32 vcc, v177, v182
	v_lshlrev_b32_e32 v176, 2, v176
	v_lshl_add_u64 v[166:167], v[160:161], 1, v[166:167]
	v_cndmask_b32_e32 v177, v175, v177, vcc
	v_lshlrev_b32_e32 v177, 2, v177
	s_waitcnt vmcnt(0)
	v_pk_add_f32 v[126:127], v[126:127], v[180:181]
	v_pk_add_f32 v[124:125], v[124:125], v[178:179]
	v_pk_add_f32 v[118:119], v[118:119], v[192:193]
	v_pk_add_f32 v[116:117], v[116:117], v[190:191]
	v_pk_add_f32 v[120:121], v[120:121], v[186:187]
	v_pk_add_f32 v[178:179], v[114:115], v[196:197]
	v_pk_add_f32 v[180:181], v[112:113], v[194:195]
	v_mul_f32_e32 v114, v125, v125
	v_mul_f32_e32 v115, v127, v127
	v_cvt_pk_bf16_f32 v112, v124, v125
	v_cvt_pk_bf16_f32 v113, v126, v127
	v_mul_f32_e32 v125, v117, v117
	v_mul_f32_e32 v127, v119, v119
	v_pk_add_f32 v[122:123], v[122:123], v[188:189]
	v_mul_f32_e32 v182, v121, v121
	v_mul_f32_e32 v185, v181, v181
	v_fmac_f32_e32 v114, v124, v124
	v_fmac_f32_e32 v115, v126, v126
	v_fmac_f32_e32 v125, v116, v116
	v_fmac_f32_e32 v127, v118, v118
	v_mul_f32_e32 v183, v123, v123
	v_mul_f32_e32 v186, v179, v179
	v_fmac_f32_e32 v182, v120, v120
	v_fmac_f32_e32 v185, v180, v180
	v_add_f32_e32 v114, v114, v115
	v_add_f32_e32 v115, v125, v127
	v_fmac_f32_e32 v183, v122, v122
	v_fmac_f32_e32 v186, v178, v178
	v_add_f32_e32 v114, v114, v182
	v_add_f32_e32 v115, v115, v185
	v_add_f32_e32 v114, v183, v114
	v_add_f32_e32 v115, v186, v115
	v_add_f32_e32 v124, v114, v115
	ds_bpermute_b32 v125, v176, v124
	v_cvt_pk_bf16_f32 v114, v120, v121
	v_cvt_pk_bf16_f32 v115, v122, v123
	global_store_dwordx4 v[166:167], v[112:115], off
	s_waitcnt lgkmcnt(0)
	s_nop 0
	v_add_f32_e32 v112, v124, v125
	ds_bpermute_b32 v113, v177, v112
	v_cvt_pk_bf16_f32 v114, v116, v117
	v_cvt_pk_bf16_f32 v115, v118, v119
	v_cvt_pk_bf16_f32 v116, v180, v181
	v_cvt_pk_bf16_f32 v117, v178, v179
	global_store_dwordx4 v[166:167], v[114:117], off offset:256
	s_and_saveexec_b64 s[34:35], s[8:9]
	s_cbranch_execz .LBB0_517
	v_lshl_add_u64 v[114:115], v[162:163], 2, s[20:21]
	s_waitcnt lgkmcnt(0)
	v_add_f32_e32 v112, v112, v113
	global_atomic_add_f32 v[114:115], v112, off

.LBB0_603:
	s_ashr_i32 s41, s40, 31
	s_lshl_b64 s[4:5], s[40:41], 21
	s_add_u32 s42, s56, s4
	v_cmp_lt_i64_e64 s[8:9], s[8:9], v[156:157]
	s_addc_u32 s43, s57, s5
	s_and_b64 s[4:5], s[8:9], exec
	s_cselect_b32 s4, s43, s11
	s_cselect_b32 s5, s42, s10
	s_ashr_i32 s39, s38, 31
	s_lshl_b64 s[6:7], s[38:39], 21
	s_add_u32 s44, s16, s6
	s_addc_u32 s45, s17, s7
	s_and_b64 s[6:7], s[8:9], exec
	s_cselect_b32 s6, s45, s47
	s_cselect_b32 s7, s44, s46
	s_add_u32 s10, s10, 0x100080
	s_addc_u32 s11, s11, 0
	s_add_u32 s13, s46, 0x100
	v_mov_b32_e32 v0, 0
	s_addc_u32 s15, s47, 0
	s_mov_b32 s39, -2
	v_mov_b32_e32 v1, v0
	v_mov_b32_e32 v2, v0
	v_mov_b32_e32 v3, v0
	v_mov_b32_e32 v4, v0
	v_mov_b32_e32 v5, v0
	v_mov_b32_e32 v6, v0
	v_mov_b32_e32 v7, v0
	v_mov_b32_e32 v24, v0
	v_mov_b32_e32 v25, v0
	v_mov_b32_e32 v26, v0
	v_mov_b32_e32 v27, v0
	v_mov_b32_e32 v28, v0
	v_mov_b32_e32 v29, v0
	v_mov_b32_e32 v30, v0
	v_mov_b32_e32 v31, v0
	v_mov_b32_e32 v48, v0
	v_mov_b32_e32 v49, v0
	v_mov_b32_e32 v50, v0
	v_mov_b32_e32 v51, v0
	v_mov_b32_e32 v52, v0
	v_mov_b32_e32 v53, v0
	v_mov_b32_e32 v54, v0
	v_mov_b32_e32 v55, v0
	v_mov_b32_e32 v64, v0
	v_mov_b32_e32 v65, v0
	v_mov_b32_e32 v66, v0
	v_mov_b32_e32 v67, v0
	v_mov_b32_e32 v68, v0
	v_mov_b32_e32 v69, v0
	v_mov_b32_e32 v70, v0
	v_mov_b32_e32 v71, v0
	v_mov_b32_e32 v8, v0
	v_mov_b32_e32 v9, v0
	v_mov_b32_e32 v10, v0
	v_mov_b32_e32 v11, v0
	v_mov_b32_e32 v12, v0
	v_mov_b32_e32 v13, v0
	v_mov_b32_e32 v14, v0
	v_mov_b32_e32 v15, v0
	v_mov_b32_e32 v40, v0
	v_mov_b32_e32 v41, v0
	v_mov_b32_e32 v42, v0
	v_mov_b32_e32 v43, v0
	v_mov_b32_e32 v44, v0
	v_mov_b32_e32 v45, v0
	v_mov_b32_e32 v46, v0
	v_mov_b32_e32 v47, v0
	v_mov_b32_e32 v56, v0
	v_mov_b32_e32 v57, v0
	v_mov_b32_e32 v58, v0
	v_mov_b32_e32 v59, v0
	v_mov_b32_e32 v60, v0
	v_mov_b32_e32 v61, v0
	v_mov_b32_e32 v62, v0
	v_mov_b32_e32 v63, v0
	v_mov_b32_e32 v72, v0
	v_mov_b32_e32 v73, v0
	v_mov_b32_e32 v74, v0
	v_mov_b32_e32 v75, v0
	v_mov_b32_e32 v76, v0
	v_mov_b32_e32 v77, v0
	v_mov_b32_e32 v78, v0
	v_mov_b32_e32 v79, v0
	v_mov_b32_e32 v80, v0
	v_mov_b32_e32 v81, v0
	v_mov_b32_e32 v82, v0
	v_mov_b32_e32 v83, v0
	v_mov_b32_e32 v84, v0
	v_mov_b32_e32 v85, v0
	v_mov_b32_e32 v86, v0
	v_mov_b32_e32 v87, v0
	v_mov_b32_e32 v96, v0
	v_mov_b32_e32 v97, v0
	v_mov_b32_e32 v98, v0
	v_mov_b32_e32 v99, v0
	v_mov_b32_e32 v100, v0
	v_mov_b32_e32 v101, v0
	v_mov_b32_e32 v102, v0
	v_mov_b32_e32 v103, v0
	v_mov_b32_e32 v112, v0
	v_mov_b32_e32 v113, v0
	v_mov_b32_e32 v114, v0
	v_mov_b32_e32 v115, v0
	v_mov_b32_e32 v116, v0
	v_mov_b32_e32 v117, v0
	v_mov_b32_e32 v118, v0
	v_mov_b32_e32 v119, v0
	v_mov_b32_e32 v128, v0
	v_mov_b32_e32 v129, v0
	v_mov_b32_e32 v130, v0
	v_mov_b32_e32 v131, v0
	v_mov_b32_e32 v132, v0
	v_mov_b32_e32 v133, v0
	v_mov_b32_e32 v134, v0
	v_mov_b32_e32 v135, v0
	v_mov_b32_e32 v88, v0
	v_mov_b32_e32 v89, v0
	v_mov_b32_e32 v90, v0
	v_mov_b32_e32 v91, v0
	v_mov_b32_e32 v92, v0
	v_mov_b32_e32 v93, v0
	v_mov_b32_e32 v94, v0
	v_mov_b32_e32 v95, v0
	v_mov_b32_e32 v104, v0
	v_mov_b32_e32 v105, v0
	v_mov_b32_e32 v106, v0
	v_mov_b32_e32 v107, v0
	v_mov_b32_e32 v108, v0
	v_mov_b32_e32 v109, v0
	v_mov_b32_e32 v110, v0
	v_mov_b32_e32 v111, v0
	v_mov_b32_e32 v120, v0
	v_mov_b32_e32 v121, v0
	v_mov_b32_e32 v122, v0
	v_mov_b32_e32 v123, v0
	v_mov_b32_e32 v124, v0
	v_mov_b32_e32 v125, v0
	v_mov_b32_e32 v126, v0
	v_mov_b32_e32 v127, v0
	v_mov_b32_e32 v136, v0
	v_mov_b32_e32 v137, v0
	v_mov_b32_e32 v138, v0
	v_mov_b32_e32 v139, v0
	v_mov_b32_e32 v140, v0
	v_mov_b32_e32 v141, v0
	v_mov_b32_e32 v142, v0
	v_mov_b32_e32 v143, v0
	s_branch .LBB0_604

.LBB0_604:
	ds_read_b128 v[16:19], v176
	ds_read_b128 v[20:23], v176 offset:1024
	ds_read_b128 v[32:35], v176 offset:2048
	ds_read_b128 v[36:39], v176 offset:3072
	s_add_u32 s41, s10, 0xfff00080
	s_addc_u32 s46, s11, -1
	s_cmp_eq_u32 s39, 60
	s_cselect_b32 s49, s4, s46
	s_cselect_b32 s48, s5, s41
	s_cselect_b32 s47, s6, s15
	s_cselect_b32 s46, s7, s13
	v_lshl_add_u64 v[160:161], s[10:11], 0, v[152:153]
	s_add_i32 m0, s52, 0xc000
	ds_read_b128 v[164:167], v177
	ds_read_b128 v[168:171], v177 offset:1024
	ds_read_b128 v[190:193], v177 offset:2048
	ds_read_b128 v[194:197], v177 offset:3072
	ds_read_b128 v[198:201], v177 offset:4096
	ds_read_b128 v[202:205], v177 offset:5120
	ds_read_b128 v[206:209], v177 offset:6144
	ds_read_b128 v[210:213], v177 offset:7168
	global_load_lds_dwordx4 v[160:161], off
	v_lshl_add_u64 v[160:161], s[10:11], 0, v[154:155]
	s_add_i32 m0, s52, 0xe000
	s_nop 0
	global_load_lds_dwordx4 v[160:161], off
	s_waitcnt lgkmcnt(8)
	s_barrier
	s_waitcnt lgkmcnt(0)
	s_waitcnt lgkmcnt(0)
	v_mfma_f32_16x16x32_bf16 v[140:143], v[16:19], v[164:167], v[140:143]
	v_mfma_f32_16x16x32_bf16 v[140:143], v[20:23], v[168:171], v[140:143]
	v_mfma_f32_16x16x32_bf16 v[136:139], v[32:35], v[164:167], v[136:139]
	v_mfma_f32_16x16x32_bf16 v[136:139], v[36:39], v[168:171], v[136:139]
	v_mfma_f32_16x16x32_bf16 v[124:127], v[16:19], v[190:193], v[124:127]
	v_mfma_f32_16x16x32_bf16 v[124:127], v[20:23], v[194:197], v[124:127]
	v_mfma_f32_16x16x32_bf16 v[120:123], v[32:35], v[190:193], v[120:123]
	v_mfma_f32_16x16x32_bf16 v[120:123], v[36:39], v[194:197], v[120:123]
	v_mfma_f32_16x16x32_bf16 v[108:111], v[16:19], v[198:201], v[108:111]
	v_mfma_f32_16x16x32_bf16 v[108:111], v[20:23], v[202:205], v[108:111]
	v_mfma_f32_16x16x32_bf16 v[104:107], v[32:35], v[198:201], v[104:107]
	v_mfma_f32_16x16x32_bf16 v[104:107], v[36:39], v[202:205], v[104:107]
	v_mfma_f32_16x16x32_bf16 v[92:95], v[16:19], v[206:209], v[92:95]
	v_mfma_f32_16x16x32_bf16 v[92:95], v[20:23], v[210:213], v[92:95]
	v_mfma_f32_16x16x32_bf16 v[88:91], v[32:35], v[206:209], v[88:91]
	v_mfma_f32_16x16x32_bf16 v[88:91], v[36:39], v[210:213], v[88:91]
	s_barrier
	s_add_i32 s41, s81, s51
	v_lshl_add_u64 v[160:161], s[46:47], 0, v[146:147]
	s_mov_b32 m0, s41
	ds_read_b128 v[214:217], v178
	ds_read_b128 v[218:221], v178 offset:1024
	ds_read_b128 v[222:225], v178 offset:2048
	ds_read_b128 v[226:229], v178 offset:3072
	global_load_lds_dwordx4 v[160:161], off
	v_lshl_add_u64 v[230:231], s[46:47], 0, v[150:151]
	s_add_i32 m0, s41, 0x2000
	s_nop 0
	global_load_lds_dwordx4 v[230:231], off
	s_barrier
	s_waitcnt lgkmcnt(0)
	s_waitcnt lgkmcnt(0)
	v_mfma_f32_16x16x32_bf16 v[132:135], v[214:217], v[164:167], v[132:135]
	v_mfma_f32_16x16x32_bf16 v[132:135], v[218:221], v[168:171], v[132:135]
	v_mfma_f32_16x16x32_bf16 v[128:131], v[222:225], v[164:167], v[128:131]
	v_mfma_f32_16x16x32_bf16 v[128:131], v[226:229], v[168:171], v[128:131]
	v_mfma_f32_16x16x32_bf16 v[116:119], v[214:217], v[190:193], v[116:119]
	v_mfma_f32_16x16x32_bf16 v[116:119], v[218:221], v[194:197], v[116:119]
	v_mfma_f32_16x16x32_bf16 v[112:115], v[222:225], v[190:193], v[112:115]
	v_mfma_f32_16x16x32_bf16 v[112:115], v[226:229], v[194:197], v[112:115]
	v_mfma_f32_16x16x32_bf16 v[100:103], v[214:217], v[198:201], v[100:103]
	v_mfma_f32_16x16x32_bf16 v[100:103], v[218:221], v[202:205], v[100:103]
	v_mfma_f32_16x16x32_bf16 v[96:99], v[222:225], v[198:201], v[96:99]
	v_mfma_f32_16x16x32_bf16 v[96:99], v[226:229], v[202:205], v[96:99]
	v_mfma_f32_16x16x32_bf16 v[84:87], v[214:217], v[206:209], v[84:87]
	v_mfma_f32_16x16x32_bf16 v[84:87], v[218:221], v[210:213], v[84:87]
	v_mfma_f32_16x16x32_bf16 v[80:83], v[222:225], v[206:209], v[80:83]
	v_mfma_f32_16x16x32_bf16 v[80:83], v[226:229], v[210:213], v[80:83]
	s_mov_b32 m0, s52
	v_lshl_add_u64 v[232:233], s[48:49], 0, v[144:145]
	s_barrier
	ds_read_b128 v[164:167], v177 offset:16384
	ds_read_b128 v[168:171], v177 offset:17408
	ds_read_b128 v[190:193], v177 offset:18432
	ds_read_b128 v[194:197], v177 offset:19456
	ds_read_b128 v[198:201], v177 offset:20480
	ds_read_b128 v[202:205], v177 offset:21504
	ds_read_b128 v[206:209], v177 offset:22528
	ds_read_b128 v[210:213], v177 offset:23552
	global_load_lds_dwordx4 v[232:233], off
	v_lshl_add_u64 v[234:235], s[48:49], 0, v[148:149]
	s_mov_b32 m0, s53
	s_nop 0
	global_load_lds_dwordx4 v[234:235], off
	s_barrier
	s_waitcnt lgkmcnt(0)
	s_waitcnt lgkmcnt(0)
	v_mfma_f32_16x16x32_bf16 v[76:79], v[16:19], v[164:167], v[76:79]
	v_mfma_f32_16x16x32_bf16 v[76:79], v[20:23], v[168:171], v[76:79]
	v_mfma_f32_16x16x32_bf16 v[72:75], v[32:35], v[164:167], v[72:75]
	v_mfma_f32_16x16x32_bf16 v[72:75], v[36:39], v[168:171], v[72:75]
	v_mfma_f32_16x16x32_bf16 v[60:63], v[16:19], v[190:193], v[60:63]
	v_mfma_f32_16x16x32_bf16 v[60:63], v[20:23], v[194:197], v[60:63]
	v_mfma_f32_16x16x32_bf16 v[56:59], v[32:35], v[190:193], v[56:59]
	v_mfma_f32_16x16x32_bf16 v[56:59], v[36:39], v[194:197], v[56:59]
	v_mfma_f32_16x16x32_bf16 v[44:47], v[16:19], v[198:201], v[44:47]
	v_mfma_f32_16x16x32_bf16 v[44:47], v[20:23], v[202:205], v[44:47]
	v_mfma_f32_16x16x32_bf16 v[40:43], v[32:35], v[198:201], v[40:43]
	v_mfma_f32_16x16x32_bf16 v[40:43], v[36:39], v[202:205], v[40:43]
	v_mfma_f32_16x16x32_bf16 v[12:15], v[16:19], v[206:209], v[12:15]
	v_mfma_f32_16x16x32_bf16 v[12:15], v[20:23], v[210:213], v[12:15]
	v_mfma_f32_16x16x32_bf16 v[8:11], v[32:35], v[206:209], v[8:11]
	v_mfma_f32_16x16x32_bf16 v[8:11], v[36:39], v[210:213], v[8:11]
	s_barrier
	s_add_u32 s54, s46, 0x100000
	s_addc_u32 s55, s47, 0
	s_add_i32 s41, s82, s51
	v_lshl_add_u64 v[16:17], s[54:55], 0, v[146:147]
	s_mov_b32 m0, s41
	s_nop 0
	global_load_lds_dwordx4 v[16:17], off
	v_lshl_add_u64 v[16:17], s[54:55], 0, v[150:151]
	s_add_i32 m0, s41, 0x2000
	s_nop 0
	global_load_lds_dwordx4 v[16:17], off
	s_waitcnt vmcnt(6)
	s_barrier
	v_mfma_f32_16x16x32_bf16 v[28:31], v[214:217], v[198:201], v[28:31]
	v_mfma_f32_16x16x32_bf16 v[28:31], v[218:221], v[202:205], v[28:31]
	v_mfma_f32_16x16x32_bf16 v[24:27], v[222:225], v[198:201], v[24:27]
	v_mfma_f32_16x16x32_bf16 v[24:27], v[226:229], v[202:205], v[24:27]
	v_mfma_f32_16x16x32_bf16 v[4:7], v[214:217], v[206:209], v[4:7]
	v_mfma_f32_16x16x32_bf16 v[4:7], v[218:221], v[210:213], v[4:7]
	v_mfma_f32_16x16x32_bf16 v[0:3], v[222:225], v[206:209], v[0:3]
	v_mfma_f32_16x16x32_bf16 v[0:3], v[226:229], v[210:213], v[0:3]
	v_mfma_f32_16x16x32_bf16 v[16:19], v[214:217], v[164:167], v[68:71]
	v_mfma_f32_16x16x32_bf16 v[16:19], v[218:221], v[168:171], v[16:19]
	v_mfma_f32_16x16x32_bf16 v[20:23], v[222:225], v[164:167], v[64:67]
	v_mfma_f32_16x16x32_bf16 v[20:23], v[226:229], v[168:171], v[20:23]
	v_mfma_f32_16x16x32_bf16 v[32:35], v[214:217], v[190:193], v[52:55]
	v_mfma_f32_16x16x32_bf16 v[32:35], v[218:221], v[194:197], v[32:35]
	v_mfma_f32_16x16x32_bf16 v[36:39], v[222:225], v[190:193], v[48:51]
	v_mfma_f32_16x16x32_bf16 v[36:39], v[226:229], v[194:197], v[36:39]
	s_add_i32 s41, 0, 0x18000
	v_add_u32_e32 v68, s41, v174
	s_barrier
	ds_read_b128 v[48:51], v68
	ds_read_b128 v[52:55], v68 offset:1024
	ds_read_b128 v[64:67], v68 offset:2048
	ds_read_b128 v[68:71], v68 offset:3072
	s_add_u32 s48, s48, 0x100000
	s_addc_u32 s49, s49, 0
	s_mov_b32 m0, s61
	v_lshl_add_u64 v[214:215], s[48:49], 0, v[144:145]
	ds_read_b128 v[164:167], v177 offset:32768
	ds_read_b128 v[168:171], v177 offset:33792
	ds_read_b128 v[190:193], v177 offset:34816
	ds_read_b128 v[194:197], v177 offset:35840
	ds_read_b128 v[198:201], v177 offset:36864
	ds_read_b128 v[202:205], v177 offset:37888
	ds_read_b128 v[206:209], v177 offset:38912
	ds_read_b128 v[210:213], v177 offset:39936
	global_load_lds_dwordx4 v[214:215], off
	v_lshl_add_u64 v[214:215], s[48:49], 0, v[148:149]
	s_mov_b32 m0, s74
	s_nop 0
	global_load_lds_dwordx4 v[214:215], off
	s_waitcnt lgkmcnt(8)
	s_barrier
	s_waitcnt lgkmcnt(0)
	s_waitcnt lgkmcnt(0)
	v_mfma_f32_16x16x32_bf16 v[140:143], v[48:51], v[164:167], v[140:143]
	v_mfma_f32_16x16x32_bf16 v[140:143], v[52:55], v[168:171], v[140:143]
	v_mfma_f32_16x16x32_bf16 v[136:139], v[64:67], v[164:167], v[136:139]
	v_mfma_f32_16x16x32_bf16 v[136:139], v[68:71], v[168:171], v[136:139]
	v_mfma_f32_16x16x32_bf16 v[124:127], v[48:51], v[190:193], v[124:127]
	v_mfma_f32_16x16x32_bf16 v[124:127], v[52:55], v[194:197], v[124:127]
	v_mfma_f32_16x16x32_bf16 v[120:123], v[64:67], v[190:193], v[120:123]
	v_mfma_f32_16x16x32_bf16 v[120:123], v[68:71], v[194:197], v[120:123]
	v_mfma_f32_16x16x32_bf16 v[108:111], v[48:51], v[198:201], v[108:111]
	v_mfma_f32_16x16x32_bf16 v[108:111], v[52:55], v[202:205], v[108:111]
	v_mfma_f32_16x16x32_bf16 v[104:107], v[64:67], v[198:201], v[104:107]
	v_mfma_f32_16x16x32_bf16 v[104:107], v[68:71], v[202:205], v[104:107]
	v_mfma_f32_16x16x32_bf16 v[92:95], v[48:51], v[206:209], v[92:95]
	v_mfma_f32_16x16x32_bf16 v[92:95], v[52:55], v[210:213], v[92:95]
	v_mfma_f32_16x16x32_bf16 v[88:91], v[64:67], v[206:209], v[88:91]
	v_mfma_f32_16x16x32_bf16 v[88:91], v[68:71], v[210:213], v[88:91]
	s_barrier
	s_add_i32 s48, 0, 0x1c000
	s_add_i32 s41, s41, s51
	v_add_u32_e32 v163, s48, v174
	v_lshl_add_u64 v[160:161], v[160:161], 0, s[22:23]
	s_mov_b32 m0, s41
	ds_read_b128 v[214:217], v163
	ds_read_b128 v[218:221], v163 offset:1024
	ds_read_b128 v[222:225], v163 offset:2048
	ds_read_b128 v[226:229], v163 offset:3072
	global_load_lds_dwordx4 v[160:161], off
	v_lshl_add_u64 v[160:161], v[230:231], 0, s[22:23]
	s_add_i32 m0, s41, 0x2000
	s_nop 0
	global_load_lds_dwordx4 v[160:161], off
	s_barrier
	s_waitcnt lgkmcnt(0)
	s_waitcnt lgkmcnt(0)
	v_mfma_f32_16x16x32_bf16 v[132:135], v[214:217], v[164:167], v[132:135]
	v_mfma_f32_16x16x32_bf16 v[132:135], v[218:221], v[168:171], v[132:135]
	v_mfma_f32_16x16x32_bf16 v[128:131], v[222:225], v[164:167], v[128:131]
	v_mfma_f32_16x16x32_bf16 v[128:131], v[226:229], v[168:171], v[128:131]
	v_mfma_f32_16x16x32_bf16 v[116:119], v[214:217], v[190:193], v[116:119]
	v_mfma_f32_16x16x32_bf16 v[116:119], v[218:221], v[194:197], v[116:119]
	v_mfma_f32_16x16x32_bf16 v[112:115], v[222:225], v[190:193], v[112:115]
	v_mfma_f32_16x16x32_bf16 v[112:115], v[226:229], v[194:197], v[112:115]
	v_mfma_f32_16x16x32_bf16 v[100:103], v[214:217], v[198:201], v[100:103]
	v_mfma_f32_16x16x32_bf16 v[100:103], v[218:221], v[202:205], v[100:103]
	v_mfma_f32_16x16x32_bf16 v[96:99], v[222:225], v[198:201], v[96:99]
	v_mfma_f32_16x16x32_bf16 v[96:99], v[226:229], v[202:205], v[96:99]
	v_mfma_f32_16x16x32_bf16 v[84:87], v[214:217], v[206:209], v[84:87]
	v_mfma_f32_16x16x32_bf16 v[84:87], v[218:221], v[210:213], v[84:87]
	v_mfma_f32_16x16x32_bf16 v[80:83], v[222:225], v[206:209], v[80:83]
	v_mfma_f32_16x16x32_bf16 v[80:83], v[226:229], v[210:213], v[80:83]
	s_mov_b32 m0, s76
	v_lshl_add_u64 v[160:161], v[232:233], 0, s[22:23]
	s_barrier
	ds_read_b128 v[164:167], v177 offset:49152
	ds_read_b128 v[168:171], v177 offset:50176
	ds_read_b128 v[190:193], v177 offset:51200
	ds_read_b128 v[194:197], v177 offset:52224
	ds_read_b128 v[198:201], v177 offset:53248
	ds_read_b128 v[202:205], v177 offset:54272
	ds_read_b128 v[206:209], v177 offset:55296
	ds_read_b128 v[210:213], v177 offset:56320
	global_load_lds_dwordx4 v[160:161], off
	v_lshl_add_u64 v[160:161], v[234:235], 0, s[22:23]
	s_mov_b32 m0, s77
	s_nop 0
	global_load_lds_dwordx4 v[160:161], off
	s_barrier
	s_waitcnt lgkmcnt(0)
	s_waitcnt lgkmcnt(0)
	v_mfma_f32_16x16x32_bf16 v[76:79], v[48:51], v[164:167], v[76:79]
	v_mfma_f32_16x16x32_bf16 v[76:79], v[52:55], v[168:171], v[76:79]
	v_mfma_f32_16x16x32_bf16 v[72:75], v[64:67], v[164:167], v[72:75]
	v_mfma_f32_16x16x32_bf16 v[72:75], v[68:71], v[168:171], v[72:75]
	v_mfma_f32_16x16x32_bf16 v[60:63], v[48:51], v[190:193], v[60:63]
	v_mfma_f32_16x16x32_bf16 v[60:63], v[52:55], v[194:197], v[60:63]
	v_mfma_f32_16x16x32_bf16 v[56:59], v[64:67], v[190:193], v[56:59]
	v_mfma_f32_16x16x32_bf16 v[56:59], v[68:71], v[194:197], v[56:59]
	v_mfma_f32_16x16x32_bf16 v[44:47], v[48:51], v[198:201], v[44:47]
	v_mfma_f32_16x16x32_bf16 v[44:47], v[52:55], v[202:205], v[44:47]
	v_mfma_f32_16x16x32_bf16 v[40:43], v[64:67], v[198:201], v[40:43]
	v_mfma_f32_16x16x32_bf16 v[40:43], v[68:71], v[202:205], v[40:43]
	v_mfma_f32_16x16x32_bf16 v[12:15], v[48:51], v[206:209], v[12:15]
	v_mfma_f32_16x16x32_bf16 v[12:15], v[52:55], v[210:213], v[12:15]
	v_mfma_f32_16x16x32_bf16 v[8:11], v[64:67], v[206:209], v[8:11]
	v_mfma_f32_16x16x32_bf16 v[8:11], v[68:71], v[210:213], v[8:11]
	s_barrier
	s_add_u32 s46, s46, 0x100080
	s_addc_u32 s47, s47, 0
	s_add_i32 s41, s48, s51
	v_lshl_add_u64 v[48:49], s[46:47], 0, v[146:147]
	s_mov_b32 m0, s41
	s_nop 0
	global_load_lds_dwordx4 v[48:49], off
	v_lshl_add_u64 v[48:49], s[46:47], 0, v[150:151]
	s_add_i32 m0, s41, 0x2000
	s_nop 0
	global_load_lds_dwordx4 v[48:49], off
	s_waitcnt vmcnt(6)
	s_barrier
	v_mfma_f32_16x16x32_bf16 v[16:19], v[214:217], v[164:167], v[16:19]
	v_mfma_f32_16x16x32_bf16 v[68:71], v[218:221], v[168:171], v[16:19]
	v_mfma_f32_16x16x32_bf16 v[16:19], v[222:225], v[164:167], v[20:23]
	v_mfma_f32_16x16x32_bf16 v[64:67], v[226:229], v[168:171], v[16:19]
	v_mfma_f32_16x16x32_bf16 v[16:19], v[214:217], v[190:193], v[32:35]
	v_mfma_f32_16x16x32_bf16 v[52:55], v[218:221], v[194:197], v[16:19]
	v_mfma_f32_16x16x32_bf16 v[16:19], v[222:225], v[190:193], v[36:39]
	v_mfma_f32_16x16x32_bf16 v[48:51], v[226:229], v[194:197], v[16:19]
	v_mfma_f32_16x16x32_bf16 v[16:19], v[214:217], v[198:201], v[28:31]
	v_mfma_f32_16x16x32_bf16 v[28:31], v[218:221], v[202:205], v[16:19]
	v_mfma_f32_16x16x32_bf16 v[16:19], v[222:225], v[198:201], v[24:27]
	v_mfma_f32_16x16x32_bf16 v[24:27], v[226:229], v[202:205], v[16:19]
	v_mfma_f32_16x16x32_bf16 v[4:7], v[214:217], v[206:209], v[4:7]
	v_mfma_f32_16x16x32_bf16 v[4:7], v[218:221], v[210:213], v[4:7]
	v_mfma_f32_16x16x32_bf16 v[0:3], v[222:225], v[206:209], v[0:3]
	v_mfma_f32_16x16x32_bf16 v[0:3], v[226:229], v[210:213], v[0:3]
	s_add_i32 s39, s39, 2
	s_add_u32 s10, s10, 0x100
	s_addc_u32 s11, s11, 0
	s_add_u32 s13, s13, 0x100
	s_addc_u32 s15, s15, 0
	s_cmp_gt_u32 s39, 61
	s_cbranch_scc0 .Lrot_604
	s_barrier
	s_ashr_i32 s4, s12, 4
	s_cmp_eq_u32 s4, 1
	v_lshl_or_b32 v160, s12, 8, v175
	v_mov_b32_e32 v36, 0
	s_cselect_b64 s[46:47], -1, 0
	s_cmp_lg_u32 s4, 1
	v_mov_b32_e32 v37, 0
	v_mov_b32_e32 v38, 0
	v_mov_b32_e32 v39, 0
	v_mov_b32_e32 v32, 0
	v_mov_b32_e32 v33, 0
	v_mov_b32_e32 v34, 0
	v_mov_b32_e32 v35, 0
	v_mov_b32_e32 v20, 0
	v_mov_b32_e32 v21, 0
	v_mov_b32_e32 v22, 0
	v_mov_b32_e32 v23, 0
	v_mov_b32_e32 v16, 0
	v_mov_b32_e32 v17, 0
	v_mov_b32_e32 v18, 0
	v_mov_b32_e32 v19, 0
	s_cbranch_scc1 .LBB0_607
	v_mov_b32_e32 v161, v147
	v_lshl_add_u64 v[16:17], v[160:161], 2, s[18:19]
	v_add_co_u32_e32 v20, vcc, 0xffffc000, v16
	v_lshl_add_u64 v[18:19], v[16:17], 0, s[24:25]
	s_nop 0
	v_addc_co_u32_e32 v21, vcc, -1, v17, vcc
	global_load_dwordx4 v[36:39], v[20:21], off
	global_load_dwordx4 v[32:35], v[18:19], off offset:16
	v_lshl_add_u64 v[18:19], v[16:17], 0, s[26:27]
	v_add_co_u32_e32 v16, vcc, 0xffffd000, v16
	s_nop 1
	v_addc_co_u32_e32 v17, vcc, -1, v17, vcc
	global_load_dwordx4 v[20:23], v[16:17], off offset:-3584
	s_nop 0
	global_load_dwordx4 v[16:19], v[18:19], off offset:16

.LBB0_980:
	s_ashr_i32 s15, s14, 31
	v_cmp_lt_i64_e32 vcc, s[16:17], v[148:149]
	s_lshl_b64 s[16:17], s[14:15], 23
	s_add_u32 s16, s4, s16
	s_addc_u32 s17, s5, s17
	s_and_b64 s[18:19], vcc, exec
	s_cselect_b32 s15, s17, s25
	s_cselect_b32 s21, s16, s24
	s_ashr_i32 s13, s12, 31
	s_lshl_b64 s[18:19], s[12:13], 21
	s_add_u32 s18, s66, s18
	s_addc_u32 s19, s67, s19
	s_and_b64 s[28:29], vcc, exec
	s_cselect_b32 s13, s19, s27
	s_cselect_b32 s44, s18, s26
	s_add_u32 s24, s24, 0x400080
	s_addc_u32 s25, s25, 0
	s_add_u32 s45, s26, 0x100
	v_mov_b32_e32 v0, 0
	s_addc_u32 s46, s27, 0
	s_mov_b32 s47, -2
	s_waitcnt lgkmcnt(0)
	v_mov_b32_e32 v1, v0
	v_mov_b32_e32 v2, v0
	v_mov_b32_e32 v3, v0
	v_mov_b32_e32 v4, v0
	v_mov_b32_e32 v5, v0
	v_mov_b32_e32 v6, v0
	v_mov_b32_e32 v7, v0
	v_mov_b32_e32 v16, v0
	v_mov_b32_e32 v17, v0
	v_mov_b32_e32 v18, v0
	v_mov_b32_e32 v19, v0
	v_mov_b32_e32 v20, v0
	v_mov_b32_e32 v21, v0
	v_mov_b32_e32 v22, v0
	v_mov_b32_e32 v23, v0
	v_mov_b32_e32 v32, v0
	v_mov_b32_e32 v33, v0
	v_mov_b32_e32 v34, v0
	v_mov_b32_e32 v35, v0
	v_mov_b32_e32 v36, v0
	v_mov_b32_e32 v37, v0
	v_mov_b32_e32 v38, v0
	v_mov_b32_e32 v39, v0
	v_mov_b32_e32 v48, v0
	v_mov_b32_e32 v49, v0
	v_mov_b32_e32 v50, v0
	v_mov_b32_e32 v51, v0
	v_mov_b32_e32 v52, v0
	v_mov_b32_e32 v53, v0
	v_mov_b32_e32 v54, v0
	v_mov_b32_e32 v55, v0
	v_mov_b32_e32 v8, v0
	v_mov_b32_e32 v9, v0
	v_mov_b32_e32 v10, v0
	v_mov_b32_e32 v11, v0
	v_mov_b32_e32 v12, v0
	v_mov_b32_e32 v13, v0
	v_mov_b32_e32 v14, v0
	v_mov_b32_e32 v15, v0
	v_mov_b32_e32 v24, v0
	v_mov_b32_e32 v25, v0
	v_mov_b32_e32 v26, v0
	v_mov_b32_e32 v27, v0
	v_mov_b32_e32 v28, v0
	v_mov_b32_e32 v29, v0
	v_mov_b32_e32 v30, v0
	v_mov_b32_e32 v31, v0
	v_mov_b32_e32 v40, v0
	v_mov_b32_e32 v41, v0
	v_mov_b32_e32 v42, v0
	v_mov_b32_e32 v43, v0
	v_mov_b32_e32 v44, v0
	v_mov_b32_e32 v45, v0
	v_mov_b32_e32 v46, v0
	v_mov_b32_e32 v47, v0
	v_mov_b32_e32 v56, v0
	v_mov_b32_e32 v57, v0
	v_mov_b32_e32 v58, v0
	v_mov_b32_e32 v59, v0
	v_mov_b32_e32 v60, v0
	v_mov_b32_e32 v61, v0
	v_mov_b32_e32 v62, v0
	v_mov_b32_e32 v63, v0
	v_mov_b32_e32 v64, v0
	v_mov_b32_e32 v65, v0
	v_mov_b32_e32 v66, v0
	v_mov_b32_e32 v67, v0
	v_mov_b32_e32 v68, v0
	v_mov_b32_e32 v69, v0
	v_mov_b32_e32 v70, v0
	v_mov_b32_e32 v71, v0
	v_mov_b32_e32 v80, v0
	v_mov_b32_e32 v81, v0
	v_mov_b32_e32 v82, v0
	v_mov_b32_e32 v83, v0
	v_mov_b32_e32 v84, v0
	v_mov_b32_e32 v85, v0
	v_mov_b32_e32 v86, v0
	v_mov_b32_e32 v87, v0
	v_mov_b32_e32 v96, v0
	v_mov_b32_e32 v97, v0
	v_mov_b32_e32 v98, v0
	v_mov_b32_e32 v99, v0
	v_mov_b32_e32 v100, v0
	v_mov_b32_e32 v101, v0
	v_mov_b32_e32 v102, v0
	v_mov_b32_e32 v103, v0
	v_mov_b32_e32 v112, v0
	v_mov_b32_e32 v113, v0
	v_mov_b32_e32 v114, v0
	v_mov_b32_e32 v115, v0
	v_mov_b32_e32 v116, v0
	v_mov_b32_e32 v117, v0
	v_mov_b32_e32 v118, v0
	v_mov_b32_e32 v119, v0
	v_mov_b32_e32 v72, v0
	v_mov_b32_e32 v73, v0
	v_mov_b32_e32 v74, v0
	v_mov_b32_e32 v75, v0
	v_mov_b32_e32 v76, v0
	v_mov_b32_e32 v77, v0
	v_mov_b32_e32 v78, v0
	v_mov_b32_e32 v79, v0
	v_mov_b32_e32 v88, v0
	v_mov_b32_e32 v89, v0
	v_mov_b32_e32 v90, v0
	v_mov_b32_e32 v91, v0
	v_mov_b32_e32 v92, v0
	v_mov_b32_e32 v93, v0
	v_mov_b32_e32 v94, v0
	v_mov_b32_e32 v95, v0
	v_mov_b32_e32 v104, v0
	v_mov_b32_e32 v105, v0
	v_mov_b32_e32 v106, v0
	v_mov_b32_e32 v107, v0
	v_mov_b32_e32 v108, v0
	v_mov_b32_e32 v109, v0
	v_mov_b32_e32 v110, v0
	v_mov_b32_e32 v111, v0
	v_mov_b32_e32 v120, v0
	v_mov_b32_e32 v121, v0
	v_mov_b32_e32 v122, v0
	v_mov_b32_e32 v123, v0
	v_mov_b32_e32 v124, v0
	v_mov_b32_e32 v125, v0
	v_mov_b32_e32 v126, v0
	v_mov_b32_e32 v127, v0
	s_branch .LBB0_981

.LBB0_981:
	ds_read_b128 v[128:131], v163
	ds_read_b128 v[132:135], v163 offset:1024
	ds_read_b128 v[152:155], v163 offset:2048
	ds_read_b128 v[156:159], v163 offset:3072
	s_add_u32 s26, s24, 0xffc00080
	s_addc_u32 s27, s25, -1
	s_cmp_eq_u32 s47, 60
	s_cselect_b32 s29, s15, s27
	s_cselect_b32 s28, s21, s26
	s_cselect_b32 s27, s13, s46
	s_cselect_b32 s26, s44, s45
	v_lshl_add_u64 v[182:183], s[24:25], 0, v[144:145]
	s_add_i32 m0, s23, 0xc000
	ds_read_b128 v[168:171], v164
	ds_read_b128 v[174:177], v164 offset:1024
	ds_read_b128 v[178:181], v164 offset:2048
	ds_read_b128 v[186:189], v164 offset:3072
	ds_read_b128 v[190:193], v164 offset:4096
	ds_read_b128 v[194:197], v164 offset:5120
	ds_read_b128 v[198:201], v164 offset:6144
	ds_read_b128 v[202:205], v164 offset:7168
	global_load_lds_dwordx4 v[182:183], off
	v_lshl_add_u64 v[182:183], s[24:25], 0, v[146:147]
	s_add_i32 m0, s23, 0xe000
	s_nop 0
	global_load_lds_dwordx4 v[182:183], off
	s_waitcnt lgkmcnt(8)
	s_barrier
	s_waitcnt lgkmcnt(0)
	s_waitcnt lgkmcnt(0)
	v_mfma_f32_16x16x32_bf16 v[124:127], v[128:131], v[168:171], v[124:127]
	v_mfma_f32_16x16x32_bf16 v[124:127], v[132:135], v[174:177], v[124:127]
	v_mfma_f32_16x16x32_bf16 v[120:123], v[152:155], v[168:171], v[120:123]
	v_mfma_f32_16x16x32_bf16 v[120:123], v[156:159], v[174:177], v[120:123]
	v_mfma_f32_16x16x32_bf16 v[108:111], v[128:131], v[178:181], v[108:111]
	v_mfma_f32_16x16x32_bf16 v[108:111], v[132:135], v[186:189], v[108:111]
	v_mfma_f32_16x16x32_bf16 v[104:107], v[152:155], v[178:181], v[104:107]
	v_mfma_f32_16x16x32_bf16 v[104:107], v[156:159], v[186:189], v[104:107]
	v_mfma_f32_16x16x32_bf16 v[92:95], v[128:131], v[190:193], v[92:95]
	v_mfma_f32_16x16x32_bf16 v[92:95], v[132:135], v[194:197], v[92:95]
	v_mfma_f32_16x16x32_bf16 v[88:91], v[152:155], v[190:193], v[88:91]
	v_mfma_f32_16x16x32_bf16 v[88:91], v[156:159], v[194:197], v[88:91]
	v_mfma_f32_16x16x32_bf16 v[76:79], v[128:131], v[198:201], v[76:79]
	v_mfma_f32_16x16x32_bf16 v[76:79], v[132:135], v[202:205], v[76:79]
	v_mfma_f32_16x16x32_bf16 v[72:75], v[152:155], v[198:201], v[72:75]
	v_mfma_f32_16x16x32_bf16 v[72:75], v[156:159], v[202:205], v[72:75]
	s_barrier
	s_add_i32 s48, s42, s30
	v_lshl_add_u64 v[182:183], s[26:27], 0, v[138:139]
	s_mov_b32 m0, s48
	ds_read_b128 v[206:209], v165
	ds_read_b128 v[210:213], v165 offset:1024
	ds_read_b128 v[214:217], v165 offset:2048
	ds_read_b128 v[218:221], v165 offset:3072
	global_load_lds_dwordx4 v[182:183], off
	v_lshl_add_u64 v[222:223], s[26:27], 0, v[142:143]
	s_add_i32 m0, s48, 0x2000
	s_nop 0
	global_load_lds_dwordx4 v[222:223], off
	s_barrier
	s_waitcnt lgkmcnt(0)
	s_waitcnt lgkmcnt(0)
	v_mfma_f32_16x16x32_bf16 v[116:119], v[206:209], v[168:171], v[116:119]
	v_mfma_f32_16x16x32_bf16 v[116:119], v[210:213], v[174:177], v[116:119]
	v_mfma_f32_16x16x32_bf16 v[112:115], v[214:217], v[168:171], v[112:115]
	v_mfma_f32_16x16x32_bf16 v[112:115], v[218:221], v[174:177], v[112:115]
	v_mfma_f32_16x16x32_bf16 v[100:103], v[206:209], v[178:181], v[100:103]
	v_mfma_f32_16x16x32_bf16 v[100:103], v[210:213], v[186:189], v[100:103]
	v_mfma_f32_16x16x32_bf16 v[96:99], v[214:217], v[178:181], v[96:99]
	v_mfma_f32_16x16x32_bf16 v[96:99], v[218:221], v[186:189], v[96:99]
	v_mfma_f32_16x16x32_bf16 v[84:87], v[206:209], v[190:193], v[84:87]
	v_mfma_f32_16x16x32_bf16 v[84:87], v[210:213], v[194:197], v[84:87]
	v_mfma_f32_16x16x32_bf16 v[80:83], v[214:217], v[190:193], v[80:83]
	v_mfma_f32_16x16x32_bf16 v[80:83], v[218:221], v[194:197], v[80:83]
	v_mfma_f32_16x16x32_bf16 v[68:71], v[206:209], v[198:201], v[68:71]
	v_mfma_f32_16x16x32_bf16 v[68:71], v[210:213], v[202:205], v[68:71]
	v_mfma_f32_16x16x32_bf16 v[64:67], v[214:217], v[198:201], v[64:67]
	v_mfma_f32_16x16x32_bf16 v[64:67], v[218:221], v[202:205], v[64:67]
	s_mov_b32 m0, s23
	v_lshl_add_u64 v[224:225], s[28:29], 0, v[136:137]
	s_barrier
	ds_read_b128 v[168:171], v164 offset:16384
	ds_read_b128 v[174:177], v164 offset:17408
	ds_read_b128 v[178:181], v164 offset:18432
	ds_read_b128 v[186:189], v164 offset:19456
	ds_read_b128 v[190:193], v164 offset:20480
	ds_read_b128 v[194:197], v164 offset:21504
	ds_read_b128 v[198:201], v164 offset:22528
	ds_read_b128 v[202:205], v164 offset:23552
	global_load_lds_dwordx4 v[224:225], off
	v_lshl_add_u64 v[226:227], s[28:29], 0, v[140:141]
	s_mov_b32 m0, s31
	s_nop 0
	global_load_lds_dwordx4 v[226:227], off
	s_barrier
	s_waitcnt lgkmcnt(0)
	s_waitcnt lgkmcnt(0)
	v_mfma_f32_16x16x32_bf16 v[60:63], v[128:131], v[168:171], v[60:63]
	v_mfma_f32_16x16x32_bf16 v[60:63], v[132:135], v[174:177], v[60:63]
	v_mfma_f32_16x16x32_bf16 v[56:59], v[152:155], v[168:171], v[56:59]
	v_mfma_f32_16x16x32_bf16 v[56:59], v[156:159], v[174:177], v[56:59]
	v_mfma_f32_16x16x32_bf16 v[44:47], v[128:131], v[178:181], v[44:47]
	v_mfma_f32_16x16x32_bf16 v[44:47], v[132:135], v[186:189], v[44:47]
	v_mfma_f32_16x16x32_bf16 v[40:43], v[152:155], v[178:181], v[40:43]
	v_mfma_f32_16x16x32_bf16 v[40:43], v[156:159], v[186:189], v[40:43]
	v_mfma_f32_16x16x32_bf16 v[28:31], v[128:131], v[190:193], v[28:31]
	v_mfma_f32_16x16x32_bf16 v[28:31], v[132:135], v[194:197], v[28:31]
	v_mfma_f32_16x16x32_bf16 v[24:27], v[152:155], v[190:193], v[24:27]
	v_mfma_f32_16x16x32_bf16 v[24:27], v[156:159], v[194:197], v[24:27]
	v_mfma_f32_16x16x32_bf16 v[12:15], v[128:131], v[198:201], v[12:15]
	v_mfma_f32_16x16x32_bf16 v[12:15], v[132:135], v[202:205], v[12:15]
	v_mfma_f32_16x16x32_bf16 v[8:11], v[152:155], v[198:201], v[8:11]
	v_mfma_f32_16x16x32_bf16 v[8:11], v[156:159], v[202:205], v[8:11]
	s_barrier
	s_add_u32 s48, s26, 0x100000
	s_addc_u32 s49, s27, 0
	s_add_i32 s50, s43, s30
	v_lshl_add_u64 v[128:129], s[48:49], 0, v[138:139]
	s_mov_b32 m0, s50
	s_nop 0
	global_load_lds_dwordx4 v[128:129], off
	v_lshl_add_u64 v[128:129], s[48:49], 0, v[142:143]
	s_add_i32 m0, s50, 0x2000
	s_nop 0
	global_load_lds_dwordx4 v[128:129], off
	s_waitcnt vmcnt(6)
	s_barrier
	v_mfma_f32_16x16x32_bf16 v[52:55], v[206:209], v[168:171], v[52:55]
	v_mfma_f32_16x16x32_bf16 v[52:55], v[210:213], v[174:177], v[52:55]
	v_mfma_f32_16x16x32_bf16 v[48:51], v[214:217], v[168:171], v[48:51]
	v_mfma_f32_16x16x32_bf16 v[48:51], v[218:221], v[174:177], v[48:51]
	v_mfma_f32_16x16x32_bf16 v[36:39], v[206:209], v[178:181], v[36:39]
	v_mfma_f32_16x16x32_bf16 v[36:39], v[210:213], v[186:189], v[36:39]
	v_mfma_f32_16x16x32_bf16 v[32:35], v[214:217], v[178:181], v[32:35]
	v_mfma_f32_16x16x32_bf16 v[32:35], v[218:221], v[186:189], v[32:35]
	v_mfma_f32_16x16x32_bf16 v[20:23], v[206:209], v[190:193], v[20:23]
	v_mfma_f32_16x16x32_bf16 v[20:23], v[210:213], v[194:197], v[20:23]
	v_mfma_f32_16x16x32_bf16 v[16:19], v[214:217], v[190:193], v[16:19]
	v_mfma_f32_16x16x32_bf16 v[16:19], v[218:221], v[194:197], v[16:19]
	v_mfma_f32_16x16x32_bf16 v[4:7], v[206:209], v[198:201], v[4:7]
	v_mfma_f32_16x16x32_bf16 v[4:7], v[210:213], v[202:205], v[4:7]
	v_mfma_f32_16x16x32_bf16 v[0:3], v[214:217], v[198:201], v[0:3]
	v_mfma_f32_16x16x32_bf16 v[0:3], v[218:221], v[202:205], v[0:3]
	s_add_i32 s48, 0, 0x18000
	v_add_u32_e32 v156, s48, v161
	s_barrier
	ds_read_b128 v[128:131], v156
	ds_read_b128 v[132:135], v156 offset:1024
	ds_read_b128 v[152:155], v156 offset:2048
	ds_read_b128 v[156:159], v156 offset:3072
	s_add_u32 s28, s28, 0x400000
	s_addc_u32 s29, s29, 0
	s_mov_b32 m0, s34
	v_lshl_add_u64 v[206:207], s[28:29], 0, v[136:137]
	ds_read_b128 v[168:171], v164 offset:32768
	ds_read_b128 v[174:177], v164 offset:33792
	ds_read_b128 v[178:181], v164 offset:34816
	ds_read_b128 v[186:189], v164 offset:35840
	ds_read_b128 v[190:193], v164 offset:36864
	ds_read_b128 v[194:197], v164 offset:37888
	ds_read_b128 v[198:201], v164 offset:38912
	ds_read_b128 v[202:205], v164 offset:39936
	global_load_lds_dwordx4 v[206:207], off
	v_lshl_add_u64 v[206:207], s[28:29], 0, v[140:141]
	s_mov_b32 m0, s35
	s_nop 0
	global_load_lds_dwordx4 v[206:207], off
	s_waitcnt lgkmcnt(8)
	s_barrier
	s_waitcnt lgkmcnt(0)
	s_waitcnt lgkmcnt(0)
	v_mfma_f32_16x16x32_bf16 v[124:127], v[128:131], v[168:171], v[124:127]
	v_mfma_f32_16x16x32_bf16 v[124:127], v[132:135], v[174:177], v[124:127]
	v_mfma_f32_16x16x32_bf16 v[120:123], v[152:155], v[168:171], v[120:123]
	v_mfma_f32_16x16x32_bf16 v[120:123], v[156:159], v[174:177], v[120:123]
	v_mfma_f32_16x16x32_bf16 v[108:111], v[128:131], v[178:181], v[108:111]
	v_mfma_f32_16x16x32_bf16 v[108:111], v[132:135], v[186:189], v[108:111]
	v_mfma_f32_16x16x32_bf16 v[104:107], v[152:155], v[178:181], v[104:107]
	v_mfma_f32_16x16x32_bf16 v[104:107], v[156:159], v[186:189], v[104:107]
	v_mfma_f32_16x16x32_bf16 v[92:95], v[128:131], v[190:193], v[92:95]
	v_mfma_f32_16x16x32_bf16 v[92:95], v[132:135], v[194:197], v[92:95]
	v_mfma_f32_16x16x32_bf16 v[88:91], v[152:155], v[190:193], v[88:91]
	v_mfma_f32_16x16x32_bf16 v[88:91], v[156:159], v[194:197], v[88:91]
	v_mfma_f32_16x16x32_bf16 v[76:79], v[128:131], v[198:201], v[76:79]
	v_mfma_f32_16x16x32_bf16 v[76:79], v[132:135], v[202:205], v[76:79]
	v_mfma_f32_16x16x32_bf16 v[72:75], v[152:155], v[198:201], v[72:75]
	v_mfma_f32_16x16x32_bf16 v[72:75], v[156:159], v[202:205], v[72:75]
	s_barrier
	s_add_i32 s28, 0, 0x1c000
	s_add_i32 s29, s48, s30
	v_add_u32_e32 v167, s28, v161
	v_lshl_add_u64 v[182:183], v[182:183], 0, s[10:11]
	s_mov_b32 m0, s29
	ds_read_b128 v[206:209], v167
	ds_read_b128 v[210:213], v167 offset:1024
	ds_read_b128 v[214:217], v167 offset:2048
	ds_read_b128 v[218:221], v167 offset:3072
	global_load_lds_dwordx4 v[182:183], off
	v_lshl_add_u64 v[182:183], v[222:223], 0, s[10:11]
	s_add_i32 m0, s29, 0x2000
	s_nop 0
	global_load_lds_dwordx4 v[182:183], off
	s_barrier
	s_waitcnt lgkmcnt(0)
	s_waitcnt lgkmcnt(0)
	v_mfma_f32_16x16x32_bf16 v[116:119], v[206:209], v[168:171], v[116:119]
	v_mfma_f32_16x16x32_bf16 v[116:119], v[210:213], v[174:177], v[116:119]
	v_mfma_f32_16x16x32_bf16 v[112:115], v[214:217], v[168:171], v[112:115]
	v_mfma_f32_16x16x32_bf16 v[112:115], v[218:221], v[174:177], v[112:115]
	v_mfma_f32_16x16x32_bf16 v[100:103], v[206:209], v[178:181], v[100:103]
	v_mfma_f32_16x16x32_bf16 v[100:103], v[210:213], v[186:189], v[100:103]
	v_mfma_f32_16x16x32_bf16 v[96:99], v[214:217], v[178:181], v[96:99]
	v_mfma_f32_16x16x32_bf16 v[96:99], v[218:221], v[186:189], v[96:99]
	v_mfma_f32_16x16x32_bf16 v[84:87], v[206:209], v[190:193], v[84:87]
	v_mfma_f32_16x16x32_bf16 v[84:87], v[210:213], v[194:197], v[84:87]
	v_mfma_f32_16x16x32_bf16 v[80:83], v[214:217], v[190:193], v[80:83]
	v_mfma_f32_16x16x32_bf16 v[80:83], v[218:221], v[194:197], v[80:83]
	v_mfma_f32_16x16x32_bf16 v[68:71], v[206:209], v[198:201], v[68:71]
	v_mfma_f32_16x16x32_bf16 v[68:71], v[210:213], v[202:205], v[68:71]
	v_mfma_f32_16x16x32_bf16 v[64:67], v[214:217], v[198:201], v[64:67]
	v_mfma_f32_16x16x32_bf16 v[64:67], v[218:221], v[202:205], v[64:67]
	s_mov_b32 m0, s37
	v_lshl_add_u64 v[182:183], v[224:225], 0, s[10:11]
	s_barrier
	ds_read_b128 v[168:171], v164 offset:49152
	ds_read_b128 v[174:177], v164 offset:50176
	ds_read_b128 v[178:181], v164 offset:51200
	ds_read_b128 v[186:189], v164 offset:52224
	ds_read_b128 v[190:193], v164 offset:53248
	ds_read_b128 v[194:197], v164 offset:54272
	ds_read_b128 v[198:201], v164 offset:55296
	ds_read_b128 v[202:205], v164 offset:56320
	global_load_lds_dwordx4 v[182:183], off
	v_lshl_add_u64 v[182:183], v[226:227], 0, s[10:11]
	s_mov_b32 m0, s38
	s_nop 0
	global_load_lds_dwordx4 v[182:183], off
	s_barrier
	s_waitcnt lgkmcnt(0)
	s_waitcnt lgkmcnt(0)
	v_mfma_f32_16x16x32_bf16 v[60:63], v[128:131], v[168:171], v[60:63]
	v_mfma_f32_16x16x32_bf16 v[60:63], v[132:135], v[174:177], v[60:63]
	v_mfma_f32_16x16x32_bf16 v[56:59], v[152:155], v[168:171], v[56:59]
	v_mfma_f32_16x16x32_bf16 v[56:59], v[156:159], v[174:177], v[56:59]
	v_mfma_f32_16x16x32_bf16 v[44:47], v[128:131], v[178:181], v[44:47]
	v_mfma_f32_16x16x32_bf16 v[44:47], v[132:135], v[186:189], v[44:47]
	v_mfma_f32_16x16x32_bf16 v[40:43], v[152:155], v[178:181], v[40:43]
	v_mfma_f32_16x16x32_bf16 v[40:43], v[156:159], v[186:189], v[40:43]
	v_mfma_f32_16x16x32_bf16 v[28:31], v[128:131], v[190:193], v[28:31]
	v_mfma_f32_16x16x32_bf16 v[28:31], v[132:135], v[194:197], v[28:31]
	v_mfma_f32_16x16x32_bf16 v[24:27], v[152:155], v[190:193], v[24:27]
	v_mfma_f32_16x16x32_bf16 v[24:27], v[156:159], v[194:197], v[24:27]
	v_mfma_f32_16x16x32_bf16 v[12:15], v[128:131], v[198:201], v[12:15]
	v_mfma_f32_16x16x32_bf16 v[12:15], v[132:135], v[202:205], v[12:15]
	v_mfma_f32_16x16x32_bf16 v[8:11], v[152:155], v[198:201], v[8:11]
	v_mfma_f32_16x16x32_bf16 v[8:11], v[156:159], v[202:205], v[8:11]
	s_barrier
	s_add_u32 s26, s26, 0x100080
	s_addc_u32 s27, s27, 0
	s_add_i32 s28, s28, s30
	v_lshl_add_u64 v[128:129], s[26:27], 0, v[138:139]
	s_mov_b32 m0, s28
	s_nop 0
	global_load_lds_dwordx4 v[128:129], off
	v_lshl_add_u64 v[128:129], s[26:27], 0, v[142:143]
	s_add_i32 m0, s28, 0x2000
	s_nop 0
	global_load_lds_dwordx4 v[128:129], off
	s_waitcnt vmcnt(6)
	s_barrier
	v_mfma_f32_16x16x32_bf16 v[52:55], v[206:209], v[168:171], v[52:55]
	v_mfma_f32_16x16x32_bf16 v[52:55], v[210:213], v[174:177], v[52:55]
	v_mfma_f32_16x16x32_bf16 v[48:51], v[214:217], v[168:171], v[48:51]
	v_mfma_f32_16x16x32_bf16 v[48:51], v[218:221], v[174:177], v[48:51]
	v_mfma_f32_16x16x32_bf16 v[36:39], v[206:209], v[178:181], v[36:39]
	v_mfma_f32_16x16x32_bf16 v[36:39], v[210:213], v[186:189], v[36:39]
	v_mfma_f32_16x16x32_bf16 v[32:35], v[214:217], v[178:181], v[32:35]
	v_mfma_f32_16x16x32_bf16 v[32:35], v[218:221], v[186:189], v[32:35]
	v_mfma_f32_16x16x32_bf16 v[20:23], v[206:209], v[190:193], v[20:23]
	v_mfma_f32_16x16x32_bf16 v[20:23], v[210:213], v[194:197], v[20:23]
	v_mfma_f32_16x16x32_bf16 v[16:19], v[214:217], v[190:193], v[16:19]
	v_mfma_f32_16x16x32_bf16 v[16:19], v[218:221], v[194:197], v[16:19]
	v_mfma_f32_16x16x32_bf16 v[4:7], v[206:209], v[198:201], v[4:7]
	v_mfma_f32_16x16x32_bf16 v[4:7], v[210:213], v[202:205], v[4:7]
	v_mfma_f32_16x16x32_bf16 v[0:3], v[214:217], v[198:201], v[0:3]
	v_mfma_f32_16x16x32_bf16 v[0:3], v[218:221], v[202:205], v[0:3]
	s_add_i32 s47, s47, 2
	s_add_u32 s24, s24, 0x100
	s_addc_u32 s25, s25, 0
	s_add_u32 s45, s45, 0x100
	s_addc_u32 s46, s46, 0
	s_cmp_gt_u32 s47, 61
	s_cbranch_scc0 .Lrot_981
	s_barrier
	v_lshl_add_u32 v156, s20, 8, v160
	v_lshl_or_b32 v152, s22, 8, v162
	v_ashrrev_i32_e32 v157, 31, v156
	v_ashrrev_i32_e32 v153, 31, v152
	v_lshlrev_b64 v[128:129], 13, v[156:157]
	v_lshl_add_u64 v[128:129], s[56:57], 0, v[128:129]
	v_lshlrev_b64 v[154:155], 1, v[152:153]
	v_lshl_add_u64 v[128:129], v[128:129], 0, v[154:155]
	global_load_dwordx4 v[168:171], v[128:129], off
	global_load_dwordx4 v[174:177], v[128:129], off offset:256
	v_or_b32_e32 v158, 16, v156
	v_ashrrev_i32_e32 v159, 31, v158
	v_lshlrev_b64 v[128:129], 13, v[158:159]
	v_lshl_add_u64 v[128:129], s[56:57], 0, v[128:129]
	v_lshl_add_u64 v[128:129], v[128:129], 0, v[154:155]
	global_load_dwordx4 v[132:135], v[128:129], off
	s_nop 0
	global_load_dwordx4 v[128:131], v[128:129], off offset:256
	v_and_b32_e32 v173, 64, v166
	v_xor_b32_e32 v167, 16, v166
	v_add_u32_e32 v173, 64, v173
	v_xor_b32_e32 v180, 32, v166
	v_cmp_lt_i32_e32 vcc, v167, v173
	v_lshlrev_b64 v[178:179], 15, v[156:157]
	v_lshl_add_u64 v[178:179], s[68:69], 0, v[178:179]
	v_cndmask_b32_e32 v167, v166, v167, vcc
	v_cmp_lt_i32_e32 vcc, v180, v173
	v_lshlrev_b32_e32 v167, 2, v167
	v_lshl_add_u64 v[178:179], v[178:179], 0, v[154:155]
	v_cndmask_b32_e32 v173, v166, v180, vcc
	s_waitcnt vmcnt(0)
	v_lshlrev_b32_e32 v180, 16, v168
	v_and_b32_e32 v181, 0xffff0000, v168
	v_lshlrev_b32_e32 v168, 16, v169
	v_and_b32_e32 v169, 0xffff0000, v169
	v_lshlrev_b32_e32 v186, 16, v174
	v_and_b32_e32 v187, 0xffff0000, v174
	v_lshlrev_b32_e32 v174, 16, v175
	v_and_b32_e32 v175, 0xffff0000, v175
	v_lshlrev_b32_e32 v182, 16, v170
	v_and_b32_e32 v183, 0xffff0000, v170
	v_lshlrev_b32_e32 v170, 16, v171
	v_and_b32_e32 v171, 0xffff0000, v171
	v_lshlrev_b32_e32 v188, 16, v176
	v_and_b32_e32 v189, 0xffff0000, v176
	v_lshlrev_b32_e32 v176, 16, v177
	v_and_b32_e32 v177, 0xffff0000, v177
	v_pk_add_f32 v[126:127], v[126:127], v[168:169]
	v_pk_add_f32 v[124:125], v[124:125], v[180:181]
	v_pk_add_f32 v[118:119], v[118:119], v[174:175]
	v_pk_add_f32 v[116:117], v[116:117], v[186:187]
	v_pk_add_f32 v[122:123], v[122:123], v[170:171]
	v_pk_add_f32 v[120:121], v[120:121], v[182:183]
	v_pk_add_f32 v[168:169], v[114:115], v[176:177]
	v_pk_add_f32 v[170:171], v[112:113], v[188:189]
	v_mul_f32_e32 v114, v125, v125
	v_mul_f32_e32 v115, v127, v127
	v_cvt_pk_bf16_f32 v112, v124, v125
	v_cvt_pk_bf16_f32 v113, v126, v127
	v_mul_f32_e32 v125, v117, v117
	v_mul_f32_e32 v127, v119, v119
	v_mul_f32_e32 v174, v121, v121
	v_mul_f32_e32 v176, v171, v171
	v_fmac_f32_e32 v114, v124, v124
	v_fmac_f32_e32 v115, v126, v126
	v_fmac_f32_e32 v125, v116, v116
	v_fmac_f32_e32 v127, v118, v118
	v_mul_f32_e32 v175, v123, v123
	v_mul_f32_e32 v177, v169, v169
	v_fmac_f32_e32 v174, v120, v120
	v_fmac_f32_e32 v176, v170, v170
	v_add_f32_e32 v114, v114, v115
	v_add_f32_e32 v115, v125, v127
	v_fmac_f32_e32 v175, v122, v122
	v_fmac_f32_e32 v177, v168, v168
	v_add_f32_e32 v114, v174, v114
	v_add_f32_e32 v115, v176, v115
	v_add_f32_e32 v114, v175, v114
	v_add_f32_e32 v115, v177, v115
	v_add_f32_e32 v124, v114, v115
	ds_bpermute_b32 v125, v167, v124
	v_cvt_pk_bf16_f32 v114, v120, v121
	v_cvt_pk_bf16_f32 v115, v122, v123
	global_store_dwordx4 v[178:179], v[112:115], off
	v_lshlrev_b32_e32 v122, 2, v173
	s_waitcnt lgkmcnt(0)
	v_add_f32_e32 v112, v124, v125
	ds_bpermute_b32 v113, v122, v112
	v_cvt_pk_bf16_f32 v114, v116, v117
	v_cvt_pk_bf16_f32 v115, v118, v119
	v_cvt_pk_bf16_f32 v116, v170, v171
	v_cvt_pk_bf16_f32 v117, v168, v169
	global_store_dwordx4 v[178:179], v[114:117], off offset:256
	s_and_saveexec_b64 s[20:21], s[6:7]
	s_cbranch_execz .LBB0_984
	v_lshl_add_u64 v[114:115], v[156:157], 2, s[72:73]
	s_waitcnt lgkmcnt(0)
	v_add_f32_e32 v112, v112, v113
	global_atomic_add_f32 v[114:115], v112, off
